# speedup vs baseline: 1.0333x; 1.0074x over previous
; #define WAIT_V0() asm volatile("s_waitcnt vmcnt(0)" ::: "memory")
; #define SBAR() __builtin_amdgcn_sched_barrier(0)
; template <int EPI>
; DEVI void gemm_tile(const u16* __restrict__ Ab, long lda, const u16* __restrict__ Bb, long ldb, int K, const EpiArgs& e,
;                     bool have0 = false, const u16* __restrict__ nA = nullptr, const u16* __restrict__ nB = nullptr) {
;     ...
;   f32x4 acc[8][4];
; #pragma unroll
;   for (int m = 0; m < 8; ++m)
; #pragma unroll
;     for (int n = 0; n < 4; ++n) acc[m][n] = f32x4{0.f, 0.f, 0.f, 0.f};
;   const int nt = K / BK;
;   if (!have0) GLDS_STAGE(0, 0);
;   WAIT_V0(); __syncthreads();
;   for (int t = 0; t < nt; ++t) {
;     const int cur = t & 1;
;     if (t + 1 < nt) GLDS_STAGE(cur ^ 1, t + 1);
;     else if (nA) {
; #pragma unroll
;       for (int i = 0; i < GL; ++i) {
;         __builtin_amdgcn_global_load_lds((const unsigned*)(nA + (long)i * 64 * lda + toffA), (unsigned*)(g_shm + wid * 1024 + i * 8192), 16, 0, 0);
;         __builtin_amdgcn_global_load_lds((const unsigned*)(nB + (long)i * 64 * ldb + toffB), (unsigned*)(g_shm + TILE_B + wid * 1024 + i * 8192), 16, 0, 0);
;       }
;     }
;     const char* sb = g_shm + cur * STAGE_B;
; #pragma unroll
;     for (int ks = 0; ks < 2; ++ks) {
;       bf16x8 Bf[4];
; #pragma unroll
;       for (int n = 0; n < 4; ++n) Bf[n] = *(const bf16x8*)(sb + b_base + n * 2048 + ks * 1024);
; #pragma unroll
;       for (int mh = 0; mh < 2; ++mh) {
;         bf16x8 At[4];
; #pragma unroll
;         for (int m = 0; m < 4; ++m) At[m] = *(const bf16x8*)(sb + a_base + (mh * 4 + m) * 2048 + ks * 1024);
;         __builtin_amdgcn_s_setprio(1);
; #pragma unroll
;         for (int m = 0; m < 4; ++m)
; #pragma unroll
;           for (int n = 0; n < 4; ++n) acc[mh * 4 + m][n] = __builtin_amdgcn_mfma_f32_16x16x32_bf16(Bf[n], At[m], acc[mh * 4 + m][n], 0, 0, 0);
;         __builtin_amdgcn_s_setprio(0);
;       }
;       SBAR();
;     }
;     if (t + 1 < nt) { WAIT_V0(); __syncthreads(); }
.LBB0_150:
	s_and_b32 s3, s2, 0x10000
	v_or_b32_e32 v149, s3, v147
	v_add_u32_e32 v169, v149, v148
	v_add_u32_e32 v149, v149, v146
	ds_read_b128 v[150:153], v169 offset:32768
	ds_read_b128 v[154:157], v169 offset:34816
	ds_read_b128 v[158:161], v169 offset:36864
	ds_read_b128 v[162:165], v169 offset:38912
	ds_read_b128 v[170:173], v149
	ds_read_b128 v[174:177], v149 offset:2048
	ds_read_b128 v[214:217], v149 offset:4096
	ds_read_b128 v[218:221], v149 offset:6144
	v_writelane_b32 v240, s4, 0
	v_writelane_b32 v240, s5, 1
	v_writelane_b32 v240, s6, 2
	v_writelane_b32 v240, s7, 3
	v_writelane_b32 v240, s8, 4
	v_writelane_b32 v240, s9, 5
	v_writelane_b32 v240, s10, 6
	v_readfirstlane_b32 s4, v132
	v_readfirstlane_b32 s5, v133
	s_nop 1
	v_subrev_u32_e32 v238, s4, v132
	s_add_u32 s4, s4, s14
	s_addc_u32 s5, s5, s15
	v_readfirstlane_b32 s6, v134
	v_readfirstlane_b32 s7, v135
	s_nop 1
	v_subrev_u32_e32 v239, s6, v134
	s_add_u32 s6, s6, s14
	s_addc_u32 s7, s7, s15
	v_readfirstlane_b32 s8, v140
	s_nop 3
	s_lshr_b32 s8, s8, 10
	s_lshr_b32 s9, s8, 1
	s_lshl_b32 s9, s9, 4
	s_lshl_b32 s10, s8, 5
	s_sub_u32 s10, s10, s9
	s_mul_i32 s9, s10, 0x800
	s_add_u32 s4, s4, s9
	s_addc_u32 s5, s5, 0
	s_and_b32 s9, s8, 1
	s_lshl_b32 s9, s9, 6
	s_sub_u32 s4, s4, s9
	s_subb_u32 s5, s5, 0
	v_readfirstlane_b32 s8, v140
	s_nop 3
	s_lshr_b32 s8, s8, 10
	s_lshr_b32 s9, s8, 1
	s_lshl_b32 s9, s9, 4
	s_lshl_b32 s10, s8, 5
	s_sub_u32 s10, s10, s9
	s_mul_i32 s9, s10, 0x800
	s_add_u32 s6, s6, s9
	s_addc_u32 s7, s7, 0
	s_and_b32 s9, s8, 1
	s_lshl_b32 s9, s9, 6
	s_sub_u32 s6, s6, s9
	s_subb_u32 s7, s7, 0
	v_readfirstlane_b32 s10, v140
	s_xor_b32 s8, s3, 0x10000
	s_nop 0
	s_lshl_b32 s10, s10, 2
	s_add_i32 s10, s10, s8
	s_add_i32 m0, s10, 0x0
	s_add_u32 s8, s4, s20
	s_addc_u32 s9, s5, s21
	global_load_lds_dwordx4 v238, s[8:9]
.Lkl_150_s1:
	s_add_u32 s8, s4, s20
	s_addc_u32 s9, s5, s21
	s_add_u32 s8, s8, 0xfffffc40
	s_addc_u32 s9, s9, 0xffffffff
	global_load_lds_dwordx4 v238, s[8:9] offset:1024
.Lkl_150_s2:
	s_add_u32 s8, s4, s20
	s_addc_u32 s9, s5, s21
	s_add_u32 s8, s8, 0x7800
	s_addc_u32 s9, s9, 0x0
	global_load_lds_dwordx4 v238, s[8:9] offset:2048
.Lkl_150_s3:
.Lkl_150:
	s_waitcnt lgkmcnt(3)
	v_mfma_f32_16x16x32_bf16 v[126:129], v[150:153], v[170:173], v[126:129]
	v_mfma_f32_16x16x32_bf16 v[122:125], v[154:157], v[170:173], v[122:125]
	v_mfma_f32_16x16x32_bf16 v[118:121], v[158:161], v[170:173], v[118:121]
	v_mfma_f32_16x16x32_bf16 v[114:117], v[162:165], v[170:173], v[114:117]
	ds_read_b128 v[170:173], v149 offset:8192
	ds_read_b128 v[222:225], v169 offset:33792
	s_add_u32 s8, s4, s20
	s_addc_u32 s9, s5, s21
	s_add_u32 s8, s8, 0x7440
	s_addc_u32 s9, s9, 0x0
	global_load_lds_dwordx4 v238, s[8:9] offset:3072
.Lkl_150_s4:
	s_waitcnt lgkmcnt(4)
	v_mfma_f32_16x16x32_bf16 v[110:113], v[150:153], v[174:177], v[110:113]
	v_mfma_f32_16x16x32_bf16 v[106:109], v[154:157], v[174:177], v[106:109]
	v_mfma_f32_16x16x32_bf16 v[102:105], v[158:161], v[174:177], v[102:105]
	v_mfma_f32_16x16x32_bf16 v[98:101], v[162:165], v[174:177], v[98:101]
	ds_read_b128 v[174:177], v149 offset:10240
	ds_read_b128 v[226:229], v169 offset:35840
	s_add_i32 m0, s10, 0x8000
	s_add_u32 s8, s6, s24
	s_addc_u32 s9, s7, s25
	global_load_lds_dwordx4 v239, s[8:9]
.Lkl_150_s5:
	s_waitcnt lgkmcnt(5)
	v_mfma_f32_16x16x32_bf16 v[94:97], v[150:153], v[214:217], v[94:97]
	v_mfma_f32_16x16x32_bf16 v[90:93], v[154:157], v[214:217], v[90:93]
	v_mfma_f32_16x16x32_bf16 v[86:89], v[158:161], v[214:217], v[86:89]
	v_mfma_f32_16x16x32_bf16 v[82:85], v[162:165], v[214:217], v[82:85]
	ds_read_b128 v[214:217], v149 offset:12288
	ds_read_b128 v[230:233], v169 offset:37888
	s_add_u32 s8, s6, s24
	s_addc_u32 s9, s7, s25
	s_add_u32 s8, s8, 0xfffffc40
	s_addc_u32 s9, s9, 0xffffffff
	global_load_lds_dwordx4 v239, s[8:9] offset:1024
.Lkl_150_s6:
	s_waitcnt lgkmcnt(6)
	v_mfma_f32_16x16x32_bf16 v[78:81], v[150:153], v[218:221], v[78:81]
	v_mfma_f32_16x16x32_bf16 v[74:77], v[154:157], v[218:221], v[74:77]
	v_mfma_f32_16x16x32_bf16 v[70:73], v[158:161], v[218:221], v[70:73]
	v_mfma_f32_16x16x32_bf16 v[66:69], v[162:165], v[218:221], v[66:69]
	ds_read_b128 v[218:221], v149 offset:14336
	ds_read_b128 v[234:237], v169 offset:39936
	s_add_u32 s8, s6, s24
	s_addc_u32 s9, s7, s25
	s_add_u32 s8, s8, 0x7800
	s_addc_u32 s9, s9, 0x0
	global_load_lds_dwordx4 v239, s[8:9] offset:2048
.Lkl_150_s7:
	s_waitcnt lgkmcnt(7)
	v_mfma_f32_16x16x32_bf16 v[62:65], v[150:153], v[170:173], v[62:65]
	v_mfma_f32_16x16x32_bf16 v[58:61], v[154:157], v[170:173], v[58:61]
	v_mfma_f32_16x16x32_bf16 v[54:57], v[158:161], v[170:173], v[54:57]
	v_mfma_f32_16x16x32_bf16 v[50:53], v[162:165], v[170:173], v[50:53]
	ds_read_b128 v[170:173], v149 offset:1024
	s_add_u32 s8, s6, s24
	s_addc_u32 s9, s7, s25
	s_add_u32 s8, s8, 0x7440
	s_addc_u32 s9, s9, 0x0
	global_load_lds_dwordx4 v239, s[8:9] offset:3072
; #define WAIT_V0() asm volatile("s_waitcnt vmcnt(0)" ::: "memory")
; #define SBAR() __builtin_amdgcn_sched_barrier(0)
; template <int EPI>
; DEVI void gemm_tile(const u16* __restrict__ Ab, long lda, const u16* __restrict__ Bb, long ldb, int K, const EpiArgs& e,
;                     bool have0 = false, const u16* __restrict__ nA = nullptr, const u16* __restrict__ nB = nullptr) {
;     ...
;     const char* sb = g_shm + cur * STAGE_B;
; #pragma unroll
;     for (int ks = 0; ks < 2; ++ks) {
;       bf16x8 Bf[4];
; #pragma unroll
;       for (int n = 0; n < 4; ++n) Bf[n] = *(const bf16x8*)(sb + b_base + n * 2048 + ks * 1024);
; #pragma unroll
;       for (int mh = 0; mh < 2; ++mh) {
;         bf16x8 At[4];
; #pragma unroll
;         for (int m = 0; m < 4; ++m) At[m] = *(const bf16x8*)(sb + a_base + (mh * 4 + m) * 2048 + ks * 1024);
;         __builtin_amdgcn_s_setprio(1);
; #pragma unroll
;         for (int m = 0; m < 4; ++m)
; #pragma unroll
;           for (int n = 0; n < 4; ++n) acc[mh * 4 + m][n] = __builtin_amdgcn_mfma_f32_16x16x32_bf16(Bf[n], At[m], acc[mh * 4 + m][n], 0, 0, 0);
;         __builtin_amdgcn_s_setprio(0);
;       }
;       SBAR();
;     }
;     if (t + 1 < nt) { WAIT_V0(); __syncthreads(); }
.Lkl_150_s8:
	s_waitcnt lgkmcnt(6)
	v_mfma_f32_16x16x32_bf16 v[46:49], v[150:153], v[174:177], v[46:49]
	v_mfma_f32_16x16x32_bf16 v[42:45], v[154:157], v[174:177], v[42:45]
	v_mfma_f32_16x16x32_bf16 v[38:41], v[158:161], v[174:177], v[38:41]
	v_mfma_f32_16x16x32_bf16 v[34:37], v[162:165], v[174:177], v[34:37]
	ds_read_b128 v[174:177], v149 offset:3072
	s_waitcnt lgkmcnt(5)
	v_mfma_f32_16x16x32_bf16 v[30:33], v[150:153], v[214:217], v[30:33]
	v_mfma_f32_16x16x32_bf16 v[26:29], v[154:157], v[214:217], v[26:29]
	v_mfma_f32_16x16x32_bf16 v[22:25], v[158:161], v[214:217], v[22:25]
	v_mfma_f32_16x16x32_bf16 v[18:21], v[162:165], v[214:217], v[18:21]
	ds_read_b128 v[214:217], v149 offset:5120
	s_waitcnt lgkmcnt(4)
	v_mfma_f32_16x16x32_bf16 v[14:17], v[150:153], v[218:221], v[14:17]
	v_mfma_f32_16x16x32_bf16 v[10:13], v[154:157], v[218:221], v[10:13]
	v_mfma_f32_16x16x32_bf16 v[6:9], v[158:161], v[218:221], v[6:9]
	v_mfma_f32_16x16x32_bf16 v[2:5], v[162:165], v[218:221], v[2:5]
	ds_read_b128 v[218:221], v149 offset:7168
	s_waitcnt lgkmcnt(3)
	v_mfma_f32_16x16x32_bf16 v[126:129], v[222:225], v[170:173], v[126:129]
	v_mfma_f32_16x16x32_bf16 v[122:125], v[226:229], v[170:173], v[122:125]
	v_mfma_f32_16x16x32_bf16 v[118:121], v[230:233], v[170:173], v[118:121]
	v_mfma_f32_16x16x32_bf16 v[114:117], v[234:237], v[170:173], v[114:117]
	ds_read_b128 v[170:173], v149 offset:9216
	s_waitcnt lgkmcnt(3)
	v_mfma_f32_16x16x32_bf16 v[110:113], v[222:225], v[174:177], v[110:113]
	v_mfma_f32_16x16x32_bf16 v[106:109], v[226:229], v[174:177], v[106:109]
	v_mfma_f32_16x16x32_bf16 v[102:105], v[230:233], v[174:177], v[102:105]
	v_mfma_f32_16x16x32_bf16 v[98:101], v[234:237], v[174:177], v[98:101]
	ds_read_b128 v[174:177], v149 offset:11264
	s_waitcnt lgkmcnt(3)
	v_mfma_f32_16x16x32_bf16 v[94:97], v[222:225], v[214:217], v[94:97]
	v_mfma_f32_16x16x32_bf16 v[90:93], v[226:229], v[214:217], v[90:93]
	v_mfma_f32_16x16x32_bf16 v[86:89], v[230:233], v[214:217], v[86:89]
	v_mfma_f32_16x16x32_bf16 v[82:85], v[234:237], v[214:217], v[82:85]
	ds_read_b128 v[214:217], v149 offset:13312
	s_waitcnt lgkmcnt(3)
	v_mfma_f32_16x16x32_bf16 v[78:81], v[222:225], v[218:221], v[78:81]
	v_mfma_f32_16x16x32_bf16 v[74:77], v[226:229], v[218:221], v[74:77]
	v_mfma_f32_16x16x32_bf16 v[70:73], v[230:233], v[218:221], v[70:73]
	v_mfma_f32_16x16x32_bf16 v[66:69], v[234:237], v[218:221], v[66:69]
	ds_read_b128 v[218:221], v149 offset:15360
	s_waitcnt lgkmcnt(3)
	v_mfma_f32_16x16x32_bf16 v[62:65], v[222:225], v[170:173], v[62:65]
	v_mfma_f32_16x16x32_bf16 v[58:61], v[226:229], v[170:173], v[58:61]
	v_mfma_f32_16x16x32_bf16 v[54:57], v[230:233], v[170:173], v[54:57]
	v_mfma_f32_16x16x32_bf16 v[50:53], v[234:237], v[170:173], v[50:53]
	s_waitcnt lgkmcnt(2)
	v_mfma_f32_16x16x32_bf16 v[46:49], v[222:225], v[174:177], v[46:49]
	v_mfma_f32_16x16x32_bf16 v[42:45], v[226:229], v[174:177], v[42:45]
	v_mfma_f32_16x16x32_bf16 v[38:41], v[230:233], v[174:177], v[38:41]
	v_mfma_f32_16x16x32_bf16 v[34:37], v[234:237], v[174:177], v[34:37]
	s_waitcnt lgkmcnt(0)
	s_add_i32 s2, s2, 0x10000
	s_waitcnt vmcnt(0)
	s_add_u32 s14, s14, 0x80
	s_addc_u32 s15, s15, 0
	s_cmpk_eq_i32 s14, 0x780
	s_waitcnt vmcnt(0)
	s_barrier
	s_cselect_b32 s100, 1, 0
	s_and_b32 s3, s2, 0x10000
	v_or_b32_e32 v149, s3, v147
	v_add_u32_e32 v169, v149, v148
	v_add_u32_e32 v149, v149, v146
	ds_read_b128 v[150:153], v169 offset:32768
	ds_read_b128 v[154:157], v169 offset:34816
	ds_read_b128 v[158:161], v169 offset:36864
	ds_read_b128 v[162:165], v169 offset:38912
	ds_read_b128 v[170:173], v149
	ds_read_b128 v[174:177], v149 offset:2048
	s_add_u32 s4, s4, 0x80
	s_addc_u32 s5, s5, 0
	s_add_u32 s6, s6, 0x80
	s_addc_u32 s7, s7, 0
	s_cmp_eq_u32 s100, 1
	s_cbranch_scc1 .Lkl_150_s9
	v_readfirstlane_b32 s10, v140
	s_xor_b32 s8, s3, 0x10000
	s_nop 0
	s_lshl_b32 s10, s10, 2
	s_add_i32 s10, s10, s8
	s_add_i32 m0, s10, 0x0
	s_add_u32 s8, s4, s20
	s_addc_u32 s9, s5, s21
	global_load_lds_dwordx4 v238, s[8:9]
.Lkl_150_s9:
	v_mfma_f32_16x16x32_bf16 v[30:33], v[222:225], v[214:217], v[30:33]
	v_mfma_f32_16x16x32_bf16 v[26:29], v[226:229], v[214:217], v[26:29]
	v_mfma_f32_16x16x32_bf16 v[22:25], v[230:233], v[214:217], v[22:25]
	v_mfma_f32_16x16x32_bf16 v[18:21], v[234:237], v[214:217], v[18:21]
	ds_read_b128 v[214:217], v149 offset:4096
	s_cmp_eq_u32 s100, 1
	s_cbranch_scc1 .Lkl_150_s10
	s_add_u32 s8, s4, s20
	s_addc_u32 s9, s5, s21
	s_add_u32 s8, s8, 0xfffffc40
	s_addc_u32 s9, s9, 0xffffffff
	global_load_lds_dwordx4 v238, s[8:9] offset:1024
.Lkl_150_s10:
	v_mfma_f32_16x16x32_bf16 v[14:17], v[222:225], v[218:221], v[14:17]
	v_mfma_f32_16x16x32_bf16 v[10:13], v[226:229], v[218:221], v[10:13]
	v_mfma_f32_16x16x32_bf16 v[6:9], v[230:233], v[218:221], v[6:9]
	v_mfma_f32_16x16x32_bf16 v[2:5], v[234:237], v[218:221], v[2:5]
	ds_read_b128 v[218:221], v149 offset:6144
	s_cmp_eq_u32 s100, 1
	s_cbranch_scc1 .Lkl_150_s11
	s_add_u32 s8, s4, s20
	s_addc_u32 s9, s5, s21
	s_add_u32 s8, s8, 0x7800
	s_addc_u32 s9, s9, 0x0
	global_load_lds_dwordx4 v238, s[8:9] offset:2048

; #define WAIT_V0() asm volatile("s_waitcnt vmcnt(0)" ::: "memory")
; #define SBAR() __builtin_amdgcn_sched_barrier(0)
; template <int EPI>
; DEVI void gemm_tile(const u16* __restrict__ Ab, long lda, const u16* __restrict__ Bb, long ldb, int K, const EpiArgs& e,
;                     bool have0 = false, const u16* __restrict__ nA = nullptr, const u16* __restrict__ nB = nullptr) {
;     ...
;   f32x4 acc[8][4];
; #pragma unroll
;   for (int m = 0; m < 8; ++m)
; #pragma unroll
;     for (int n = 0; n < 4; ++n) acc[m][n] = f32x4{0.f, 0.f, 0.f, 0.f};
;   const int nt = K / BK;
;   if (!have0) GLDS_STAGE(0, 0);
;   WAIT_V0(); __syncthreads();
;   for (int t = 0; t < nt; ++t) {
;     const int cur = t & 1;
;     if (t + 1 < nt) GLDS_STAGE(cur ^ 1, t + 1);
;     else if (nA) {
; #pragma unroll
;       for (int i = 0; i < GL; ++i) {
;         __builtin_amdgcn_global_load_lds((const unsigned*)(nA + (long)i * 64 * lda + toffA), (unsigned*)(g_shm + wid * 1024 + i * 8192), 16, 0, 0);
;         __builtin_amdgcn_global_load_lds((const unsigned*)(nB + (long)i * 64 * ldb + toffB), (unsigned*)(g_shm + TILE_B + wid * 1024 + i * 8192), 16, 0, 0);
;       }
;     }
;     const char* sb = g_shm + cur * STAGE_B;
; #pragma unroll
;     for (int ks = 0; ks < 2; ++ks) {
;       bf16x8 Bf[4];
; #pragma unroll
;       for (int n = 0; n < 4; ++n) Bf[n] = *(const bf16x8*)(sb + b_base + n * 2048 + ks * 1024);
; #pragma unroll
;       for (int mh = 0; mh < 2; ++mh) {
;         bf16x8 At[4];
; #pragma unroll
;         for (int m = 0; m < 4; ++m) At[m] = *(const bf16x8*)(sb + a_base + (mh * 4 + m) * 2048 + ks * 1024);
;         __builtin_amdgcn_s_setprio(1);
; #pragma unroll
;         for (int m = 0; m < 4; ++m)
; #pragma unroll
;           for (int n = 0; n < 4; ++n) acc[mh * 4 + m][n] = __builtin_amdgcn_mfma_f32_16x16x32_bf16(Bf[n], At[m], acc[mh * 4 + m][n], 0, 0, 0);
;         __builtin_amdgcn_s_setprio(0);
;       }
;       SBAR();
;     }
;     if (t + 1 < nt) { WAIT_V0(); __syncthreads(); }
.LBB0_184:
	s_and_b32 s22, s3, 0x10000
	v_or_b32_e32 v150, s22, v149
	v_add_u32_e32 v169, v150, v148
	v_or_b32_e32 v150, s22, v146
	v_add_u32_e32 v178, v150, v147
	ds_read_b128 v[150:153], v169 offset:32768
	ds_read_b128 v[154:157], v169 offset:34816
	ds_read_b128 v[158:161], v169 offset:36864
	ds_read_b128 v[162:165], v169 offset:38912
	ds_read_b128 v[170:173], v178
	ds_read_b128 v[174:177], v178 offset:2048
	ds_read_b128 v[214:217], v178 offset:4096
	ds_read_b128 v[218:221], v178 offset:6144
	v_writelane_b32 v240, s4, 0
	v_writelane_b32 v240, s5, 1
	v_writelane_b32 v240, s6, 2
	v_writelane_b32 v240, s7, 3
	v_writelane_b32 v240, s8, 4
	v_writelane_b32 v240, s9, 5
	v_writelane_b32 v240, s10, 6
	v_readfirstlane_b32 s4, v134
	v_readfirstlane_b32 s5, v135
	s_nop 1
	v_subrev_u32_e32 v238, s4, v134
	s_add_u32 s4, s4, s14
	s_addc_u32 s5, s5, s15
	v_readfirstlane_b32 s6, v136
	v_readfirstlane_b32 s7, v137
	s_nop 1
	v_subrev_u32_e32 v239, s6, v136
	s_add_u32 s6, s6, s14
	s_addc_u32 s7, s7, s15
	v_readfirstlane_b32 s8, v143
	s_nop 3
	s_lshr_b32 s8, s8, 10
	s_lshr_b32 s9, s8, 1
	s_lshl_b32 s9, s9, 4
	s_lshl_b32 s10, s8, 5
	s_sub_u32 s10, s10, s9
	s_mul_i32 s9, s10, 0x1600
	s_add_u32 s4, s4, s9
	s_addc_u32 s5, s5, 0
	s_and_b32 s9, s8, 1
	s_lshl_b32 s9, s9, 6
	s_sub_u32 s4, s4, s9
	s_subb_u32 s5, s5, 0
	v_readfirstlane_b32 s8, v143
	s_nop 3
	s_lshr_b32 s8, s8, 10
	s_lshr_b32 s9, s8, 1
	s_lshl_b32 s9, s9, 4
	s_lshl_b32 s10, s8, 5
	s_sub_u32 s10, s10, s9
	s_mul_i32 s9, s10, 0x1600
	s_add_u32 s6, s6, s9
	s_addc_u32 s7, s7, 0
	s_and_b32 s9, s8, 1
	s_lshl_b32 s9, s9, 6
	s_sub_u32 s6, s6, s9
	s_subb_u32 s7, s7, 0
	v_readfirstlane_b32 s10, v143
	s_xor_b32 s8, s22, 0x10000
	s_nop 0
	s_lshl_b32 s10, s10, 2
	s_add_i32 s10, s10, s8
	s_add_i32 m0, s10, 0x0
	s_add_u32 s8, s4, s24
	s_addc_u32 s9, s5, s25
	global_load_lds_dwordx4 v238, s[8:9]
.Lkl_184_s1:
	s_add_u32 s8, s4, s24
	s_addc_u32 s9, s5, s25
	s_add_u32 s8, s8, 0xfffffc40
	s_addc_u32 s9, s9, 0xffffffff
	global_load_lds_dwordx4 v238, s[8:9] offset:1024
.Lkl_184_s2:
	s_add_u32 s8, s4, s24
	s_addc_u32 s9, s5, s25
	s_add_u32 s8, s8, 0x15800
	s_addc_u32 s9, s9, 0x0
	global_load_lds_dwordx4 v238, s[8:9] offset:2048
.Lkl_184_s3:
.Lkl_184:
	s_waitcnt lgkmcnt(3)
	v_mfma_f32_16x16x32_bf16 v[126:129], v[150:153], v[170:173], v[126:129]
	v_mfma_f32_16x16x32_bf16 v[122:125], v[154:157], v[170:173], v[122:125]
	v_mfma_f32_16x16x32_bf16 v[118:121], v[158:161], v[170:173], v[118:121]
	v_mfma_f32_16x16x32_bf16 v[114:117], v[162:165], v[170:173], v[114:117]
	ds_read_b128 v[170:173], v178 offset:8192
	ds_read_b128 v[222:225], v169 offset:33792
	s_add_u32 s8, s4, s24
	s_addc_u32 s9, s5, s25
	s_add_u32 s8, s8, 0x15440
	s_addc_u32 s9, s9, 0x0
	global_load_lds_dwordx4 v238, s[8:9] offset:3072
.Lkl_184_s4:
	s_waitcnt lgkmcnt(4)
	v_mfma_f32_16x16x32_bf16 v[110:113], v[150:153], v[174:177], v[110:113]
	v_mfma_f32_16x16x32_bf16 v[106:109], v[154:157], v[174:177], v[106:109]
	v_mfma_f32_16x16x32_bf16 v[102:105], v[158:161], v[174:177], v[102:105]
	v_mfma_f32_16x16x32_bf16 v[98:101], v[162:165], v[174:177], v[98:101]
	ds_read_b128 v[174:177], v178 offset:10240
	ds_read_b128 v[226:229], v169 offset:35840
	s_add_i32 m0, s10, 0x8000
	s_add_u32 s8, s6, 0x1600080
	s_addc_u32 s9, s7, 0x0
	global_load_lds_dwordx4 v239, s[8:9]
.Lkl_184_s5:
	s_waitcnt lgkmcnt(5)
	v_mfma_f32_16x16x32_bf16 v[94:97], v[150:153], v[214:217], v[94:97]
	v_mfma_f32_16x16x32_bf16 v[90:93], v[154:157], v[214:217], v[90:93]
	v_mfma_f32_16x16x32_bf16 v[86:89], v[158:161], v[214:217], v[86:89]
	v_mfma_f32_16x16x32_bf16 v[82:85], v[162:165], v[214:217], v[82:85]
	ds_read_b128 v[214:217], v178 offset:12288
	ds_read_b128 v[230:233], v169 offset:37888
	s_add_u32 s8, s6, 0x15ffcc0
	s_addc_u32 s9, s7, 0x0
	global_load_lds_dwordx4 v239, s[8:9] offset:1024
.Lkl_184_s6:
	s_waitcnt lgkmcnt(6)
	v_mfma_f32_16x16x32_bf16 v[78:81], v[150:153], v[218:221], v[78:81]
	v_mfma_f32_16x16x32_bf16 v[74:77], v[154:157], v[218:221], v[74:77]
	v_mfma_f32_16x16x32_bf16 v[70:73], v[158:161], v[218:221], v[70:73]
	v_mfma_f32_16x16x32_bf16 v[66:69], v[162:165], v[218:221], v[66:69]
	ds_read_b128 v[218:221], v178 offset:14336
	ds_read_b128 v[234:237], v169 offset:39936
	s_add_u32 s8, s6, 0x1615880
	s_addc_u32 s9, s7, 0x0
	global_load_lds_dwordx4 v239, s[8:9] offset:2048
.Lkl_184_s7:
	s_waitcnt lgkmcnt(7)
	v_mfma_f32_16x16x32_bf16 v[62:65], v[150:153], v[170:173], v[62:65]
	v_mfma_f32_16x16x32_bf16 v[58:61], v[154:157], v[170:173], v[58:61]
	v_mfma_f32_16x16x32_bf16 v[54:57], v[158:161], v[170:173], v[54:57]
	v_mfma_f32_16x16x32_bf16 v[50:53], v[162:165], v[170:173], v[50:53]
	ds_read_b128 v[170:173], v178 offset:1024
	s_add_u32 s8, s6, 0x16154c0
	s_addc_u32 s9, s7, 0x0
	global_load_lds_dwordx4 v239, s[8:9] offset:3072
; #define WAIT_V0() asm volatile("s_waitcnt vmcnt(0)" ::: "memory")
; #define SBAR() __builtin_amdgcn_sched_barrier(0)
; template <int EPI>
; DEVI void gemm_tile(const u16* __restrict__ Ab, long lda, const u16* __restrict__ Bb, long ldb, int K, const EpiArgs& e,
;                     bool have0 = false, const u16* __restrict__ nA = nullptr, const u16* __restrict__ nB = nullptr) {
;     ...
;     const char* sb = g_shm + cur * STAGE_B;
; #pragma unroll
;     for (int ks = 0; ks < 2; ++ks) {
;       bf16x8 Bf[4];
; #pragma unroll
;       for (int n = 0; n < 4; ++n) Bf[n] = *(const bf16x8*)(sb + b_base + n * 2048 + ks * 1024);
; #pragma unroll
;       for (int mh = 0; mh < 2; ++mh) {
;         bf16x8 At[4];
; #pragma unroll
;         for (int m = 0; m < 4; ++m) At[m] = *(const bf16x8*)(sb + a_base + (mh * 4 + m) * 2048 + ks * 1024);
;         __builtin_amdgcn_s_setprio(1);
; #pragma unroll
;         for (int m = 0; m < 4; ++m)
; #pragma unroll
;           for (int n = 0; n < 4; ++n) acc[mh * 4 + m][n] = __builtin_amdgcn_mfma_f32_16x16x32_bf16(Bf[n], At[m], acc[mh * 4 + m][n], 0, 0, 0);
;         __builtin_amdgcn_s_setprio(0);
;       }
;       SBAR();
;     }
;     if (t + 1 < nt) { WAIT_V0(); __syncthreads(); }
.Lkl_184_s8:
	s_waitcnt lgkmcnt(6)
	v_mfma_f32_16x16x32_bf16 v[46:49], v[150:153], v[174:177], v[46:49]
	v_mfma_f32_16x16x32_bf16 v[42:45], v[154:157], v[174:177], v[42:45]
	v_mfma_f32_16x16x32_bf16 v[38:41], v[158:161], v[174:177], v[38:41]
	v_mfma_f32_16x16x32_bf16 v[34:37], v[162:165], v[174:177], v[34:37]
	ds_read_b128 v[174:177], v178 offset:3072
	s_waitcnt lgkmcnt(5)
	v_mfma_f32_16x16x32_bf16 v[30:33], v[150:153], v[214:217], v[30:33]
	v_mfma_f32_16x16x32_bf16 v[26:29], v[154:157], v[214:217], v[26:29]
	v_mfma_f32_16x16x32_bf16 v[22:25], v[158:161], v[214:217], v[22:25]
	v_mfma_f32_16x16x32_bf16 v[18:21], v[162:165], v[214:217], v[18:21]
	ds_read_b128 v[214:217], v178 offset:5120
	s_waitcnt lgkmcnt(4)
	v_mfma_f32_16x16x32_bf16 v[14:17], v[150:153], v[218:221], v[14:17]
	v_mfma_f32_16x16x32_bf16 v[10:13], v[154:157], v[218:221], v[10:13]
	v_mfma_f32_16x16x32_bf16 v[6:9], v[158:161], v[218:221], v[6:9]
	v_mfma_f32_16x16x32_bf16 v[2:5], v[162:165], v[218:221], v[2:5]
	ds_read_b128 v[218:221], v178 offset:7168
	s_waitcnt lgkmcnt(3)
	v_mfma_f32_16x16x32_bf16 v[126:129], v[222:225], v[170:173], v[126:129]
	v_mfma_f32_16x16x32_bf16 v[122:125], v[226:229], v[170:173], v[122:125]
	v_mfma_f32_16x16x32_bf16 v[118:121], v[230:233], v[170:173], v[118:121]
	v_mfma_f32_16x16x32_bf16 v[114:117], v[234:237], v[170:173], v[114:117]
	ds_read_b128 v[170:173], v178 offset:9216
	s_waitcnt lgkmcnt(3)
	v_mfma_f32_16x16x32_bf16 v[110:113], v[222:225], v[174:177], v[110:113]
	v_mfma_f32_16x16x32_bf16 v[106:109], v[226:229], v[174:177], v[106:109]
	v_mfma_f32_16x16x32_bf16 v[102:105], v[230:233], v[174:177], v[102:105]
	v_mfma_f32_16x16x32_bf16 v[98:101], v[234:237], v[174:177], v[98:101]
	ds_read_b128 v[174:177], v178 offset:11264
	s_waitcnt lgkmcnt(3)
	v_mfma_f32_16x16x32_bf16 v[94:97], v[222:225], v[214:217], v[94:97]
	v_mfma_f32_16x16x32_bf16 v[90:93], v[226:229], v[214:217], v[90:93]
	v_mfma_f32_16x16x32_bf16 v[86:89], v[230:233], v[214:217], v[86:89]
	v_mfma_f32_16x16x32_bf16 v[82:85], v[234:237], v[214:217], v[82:85]
	ds_read_b128 v[214:217], v178 offset:13312
	s_waitcnt lgkmcnt(3)
	v_mfma_f32_16x16x32_bf16 v[78:81], v[222:225], v[218:221], v[78:81]
	v_mfma_f32_16x16x32_bf16 v[74:77], v[226:229], v[218:221], v[74:77]
	v_mfma_f32_16x16x32_bf16 v[70:73], v[230:233], v[218:221], v[70:73]
	v_mfma_f32_16x16x32_bf16 v[66:69], v[234:237], v[218:221], v[66:69]
	ds_read_b128 v[218:221], v178 offset:15360
	s_waitcnt lgkmcnt(3)
	v_mfma_f32_16x16x32_bf16 v[62:65], v[222:225], v[170:173], v[62:65]
	v_mfma_f32_16x16x32_bf16 v[58:61], v[226:229], v[170:173], v[58:61]
	v_mfma_f32_16x16x32_bf16 v[54:57], v[230:233], v[170:173], v[54:57]
	v_mfma_f32_16x16x32_bf16 v[50:53], v[234:237], v[170:173], v[50:53]
	s_waitcnt lgkmcnt(2)
	v_mfma_f32_16x16x32_bf16 v[46:49], v[222:225], v[174:177], v[46:49]
	v_mfma_f32_16x16x32_bf16 v[42:45], v[226:229], v[174:177], v[42:45]
	v_mfma_f32_16x16x32_bf16 v[38:41], v[230:233], v[174:177], v[38:41]
	v_mfma_f32_16x16x32_bf16 v[34:37], v[234:237], v[174:177], v[34:37]
	s_waitcnt lgkmcnt(0)
	s_waitcnt vmcnt(0)
	s_add_u32 s14, s14, 0x80
	s_addc_u32 s15, s15, 0
	s_add_i32 s3, s3, 0x10000
	s_cmpk_eq_i32 s14, 0x1580
	s_waitcnt vmcnt(0)
	s_barrier
	s_cselect_b32 s100, 1, 0
	s_and_b32 s22, s3, 0x10000
	v_or_b32_e32 v150, s22, v149
	v_add_u32_e32 v169, v150, v148
	v_or_b32_e32 v150, s22, v146
	v_add_u32_e32 v178, v150, v147
	ds_read_b128 v[150:153], v169 offset:32768
	ds_read_b128 v[154:157], v169 offset:34816
	ds_read_b128 v[158:161], v169 offset:36864
	ds_read_b128 v[162:165], v169 offset:38912
	ds_read_b128 v[170:173], v178
	ds_read_b128 v[174:177], v178 offset:2048
	s_add_u32 s4, s4, 0x80
	s_addc_u32 s5, s5, 0
	s_add_u32 s6, s6, 0x80
	s_addc_u32 s7, s7, 0
	s_cmp_eq_u32 s100, 1
	s_cbranch_scc1 .Lkl_184_s9
	v_readfirstlane_b32 s10, v143
	s_xor_b32 s8, s22, 0x10000
	s_nop 0
	s_lshl_b32 s10, s10, 2
	s_add_i32 s10, s10, s8
	s_add_i32 m0, s10, 0x0
	s_add_u32 s8, s4, s24
	s_addc_u32 s9, s5, s25
	global_load_lds_dwordx4 v238, s[8:9]
.Lkl_184_s9:
	v_mfma_f32_16x16x32_bf16 v[30:33], v[222:225], v[214:217], v[30:33]
	v_mfma_f32_16x16x32_bf16 v[26:29], v[226:229], v[214:217], v[26:29]
	v_mfma_f32_16x16x32_bf16 v[22:25], v[230:233], v[214:217], v[22:25]
	v_mfma_f32_16x16x32_bf16 v[18:21], v[234:237], v[214:217], v[18:21]
	ds_read_b128 v[214:217], v178 offset:4096
	s_cmp_eq_u32 s100, 1
	s_cbranch_scc1 .Lkl_184_s10
	s_add_u32 s8, s4, s24
	s_addc_u32 s9, s5, s25
	s_add_u32 s8, s8, 0xfffffc40
	s_addc_u32 s9, s9, 0xffffffff
	global_load_lds_dwordx4 v238, s[8:9] offset:1024
.Lkl_184_s10:
	v_mfma_f32_16x16x32_bf16 v[14:17], v[222:225], v[218:221], v[14:17]
	v_mfma_f32_16x16x32_bf16 v[10:13], v[226:229], v[218:221], v[10:13]
	v_mfma_f32_16x16x32_bf16 v[6:9], v[230:233], v[218:221], v[6:9]
	v_mfma_f32_16x16x32_bf16 v[2:5], v[234:237], v[218:221], v[2:5]
	ds_read_b128 v[218:221], v178 offset:6144
	s_cmp_eq_u32 s100, 1
	s_cbranch_scc1 .Lkl_184_s11
	s_add_u32 s8, s4, s24
	s_addc_u32 s9, s5, s25
	s_add_u32 s8, s8, 0x15800
	s_addc_u32 s9, s9, 0x0
	global_load_lds_dwordx4 v238, s[8:9] offset:2048

; #define WAIT_V0() asm volatile("s_waitcnt vmcnt(0)" ::: "memory")
; #define SBAR() __builtin_amdgcn_sched_barrier(0)
; template <int EPI>
; DEVI void gemm_tile(const u16* __restrict__ Ab, long lda, const u16* __restrict__ Bb, long ldb, int K, const EpiArgs& e,
;                     bool have0 = false, const u16* __restrict__ nA = nullptr, const u16* __restrict__ nB = nullptr) {
;     ...
;   for (int t = 0; t < nt; ++t) {
;     const int cur = t & 1;
;     if (t + 1 < nt) GLDS_STAGE(cur ^ 1, t + 1);
;     else if (nA) {
; #pragma unroll
;       for (int i = 0; i < GL; ++i) {
;         __builtin_amdgcn_global_load_lds((const unsigned*)(nA + (long)i * 64 * lda + toffA), (unsigned*)(g_shm + wid * 1024 + i * 8192), 16, 0, 0);
;         __builtin_amdgcn_global_load_lds((const unsigned*)(nB + (long)i * 64 * ldb + toffB), (unsigned*)(g_shm + TILE_B + wid * 1024 + i * 8192), 16, 0, 0);
;       }
;     }
;     const char* sb = g_shm + cur * STAGE_B;
; #pragma unroll
;     for (int ks = 0; ks < 2; ++ks) {
;       bf16x8 Bf[4];
; #pragma unroll
;       for (int n = 0; n < 4; ++n) Bf[n] = *(const bf16x8*)(sb + b_base + n * 2048 + ks * 1024);
; #pragma unroll
;       for (int mh = 0; mh < 2; ++mh) {
;         bf16x8 At[4];
; #pragma unroll
;         for (int m = 0; m < 4; ++m) At[m] = *(const bf16x8*)(sb + a_base + (mh * 4 + m) * 2048 + ks * 1024);
;         __builtin_amdgcn_s_setprio(1);
; #pragma unroll
;         for (int m = 0; m < 4; ++m)
; #pragma unroll
;           for (int n = 0; n < 4; ++n) acc[mh * 4 + m][n] = __builtin_amdgcn_mfma_f32_16x16x32_bf16(Bf[n], At[m], acc[mh * 4 + m][n], 0, 0, 0);
;         __builtin_amdgcn_s_setprio(0);
;       }
;       SBAR();
;     }
;     if (t + 1 < nt) { WAIT_V0(); __syncthreads(); }
.Lkl_324_s1:
	s_mov_b32 m0, s23
	v_readfirstlane_b32 s23, v244
	v_add_u32_e32 v247, 0xa000, v246
	global_load_lds_dwordx4 v[240:241], off
.Lkl_324_s2:
	v_lshl_add_u64 v[242:243], v[238:239], 0, s[12:13]
	s_mov_b32 m0, s23
	v_readfirstlane_b32 s23, v247
	v_add_u32_e32 v247, 0x4000, v246
	global_load_lds_dwordx4 v[242:243], off
.Lkl_324_s3:
.Lkl_324:
	s_waitcnt lgkmcnt(3)
	v_mfma_f32_16x16x32_bf16 v[126:129], v[154:157], v[174:177], v[126:129]
	v_mfma_f32_16x16x32_bf16 v[122:125], v[158:161], v[174:177], v[122:125]
	v_mfma_f32_16x16x32_bf16 v[118:121], v[162:165], v[174:177], v[118:121]
	v_mfma_f32_16x16x32_bf16 v[114:117], v[170:173], v[174:177], v[114:117]
	ds_read_b128 v[174:177], v178 offset:8192
	ds_read_b128 v[222:225], v169 offset:33792
	v_lshl_add_u64 v[244:245], v[240:241], 0, s[6:7]
	s_mov_b32 m0, s23
	v_readfirstlane_b32 s23, v247
	global_load_lds_dwordx4 v[244:245], off
.Lkl_324_s4:
	s_waitcnt lgkmcnt(4)
	v_mfma_f32_16x16x32_bf16 v[110:113], v[154:157], v[192:195], v[110:113]
	v_mfma_f32_16x16x32_bf16 v[106:109], v[158:161], v[192:195], v[106:109]
	v_mfma_f32_16x16x32_bf16 v[102:105], v[162:165], v[192:195], v[102:105]
	v_mfma_f32_16x16x32_bf16 v[98:101], v[170:173], v[192:195], v[98:101]
	ds_read_b128 v[192:195], v178 offset:10240
	ds_read_b128 v[226:229], v169 offset:35840
	v_lshl_add_u64 v[242:243], v[242:243], 0, s[12:13]
	s_mov_b32 m0, s23
	v_lshl_add_u64 v[238:239], v[238:239], 0, s[14:15]
	global_load_lds_dwordx4 v[242:243], off
.Lkl_324_s5:
	s_waitcnt lgkmcnt(5)
	v_mfma_f32_16x16x32_bf16 v[94:97], v[154:157], v[198:201], v[94:97]
	v_mfma_f32_16x16x32_bf16 v[90:93], v[158:161], v[198:201], v[90:93]
	v_mfma_f32_16x16x32_bf16 v[86:89], v[162:165], v[198:201], v[86:89]
	v_mfma_f32_16x16x32_bf16 v[82:85], v[170:173], v[198:201], v[82:85]
	ds_read_b128 v[198:201], v178 offset:12288
	ds_read_b128 v[230:233], v169 offset:37888
	v_lshl_add_u64 v[242:243], v[244:245], 0, s[6:7]
	v_add_u32_e32 v244, 0xc000, v246
	s_add_i32 s3, s3, 1
	v_readfirstlane_b32 s23, v244
	s_mov_b32 m0, s23
	s_nop 0
	global_load_lds_dwordx4 v[242:243], off
.Lkl_324_s6:
	s_waitcnt lgkmcnt(6)
	v_mfma_f32_16x16x32_bf16 v[78:81], v[154:157], v[204:207], v[78:81]
	v_mfma_f32_16x16x32_bf16 v[74:77], v[158:161], v[204:207], v[74:77]
	v_mfma_f32_16x16x32_bf16 v[70:73], v[162:165], v[204:207], v[70:73]
	v_mfma_f32_16x16x32_bf16 v[66:69], v[170:173], v[204:207], v[66:69]
	ds_read_b128 v[204:207], v178 offset:14336
	ds_read_b128 v[234:237], v169 offset:39936
	v_add_u32_e32 v242, 0x6000, v246
	s_nop 0
	v_readfirstlane_b32 s23, v242
	s_mov_b32 m0, s23
	s_nop 0
	global_load_lds_dwordx4 v[238:239], off
.Lkl_324_s7:
	s_waitcnt lgkmcnt(7)
	v_mfma_f32_16x16x32_bf16 v[62:65], v[154:157], v[174:177], v[62:65]
	v_mfma_f32_16x16x32_bf16 v[58:61], v[158:161], v[174:177], v[58:61]
	v_mfma_f32_16x16x32_bf16 v[54:57], v[162:165], v[174:177], v[54:57]
	v_mfma_f32_16x16x32_bf16 v[50:53], v[170:173], v[174:177], v[50:53]
	ds_read_b128 v[174:177], v178 offset:1024
	v_lshl_add_u64 v[238:239], v[240:241], 0, s[16:17]
	v_add_u32_e32 v240, 0xe000, v246
	s_nop 0
	v_readfirstlane_b32 s23, v240
	s_mov_b32 m0, s23
	s_nop 0
	global_load_lds_dwordx4 v[238:239], off
; #define WAIT_V0() asm volatile("s_waitcnt vmcnt(0)" ::: "memory")
; #define SBAR() __builtin_amdgcn_sched_barrier(0)
; template <int EPI>
; DEVI void gemm_tile(const u16* __restrict__ Ab, long lda, const u16* __restrict__ Bb, long ldb, int K, const EpiArgs& e,
;                     bool have0 = false, const u16* __restrict__ nA = nullptr, const u16* __restrict__ nB = nullptr) {
;     ...
;     const char* sb = g_shm + cur * STAGE_B;
; #pragma unroll
;     for (int ks = 0; ks < 2; ++ks) {
;       bf16x8 Bf[4];
; #pragma unroll
;       for (int n = 0; n < 4; ++n) Bf[n] = *(const bf16x8*)(sb + b_base + n * 2048 + ks * 1024);
; #pragma unroll
;       for (int mh = 0; mh < 2; ++mh) {
;         bf16x8 At[4];
; #pragma unroll
;         for (int m = 0; m < 4; ++m) At[m] = *(const bf16x8*)(sb + a_base + (mh * 4 + m) * 2048 + ks * 1024);
;         __builtin_amdgcn_s_setprio(1);
; #pragma unroll
;         for (int m = 0; m < 4; ++m)
; #pragma unroll
;           for (int n = 0; n < 4; ++n) acc[mh * 4 + m][n] = __builtin_amdgcn_mfma_f32_16x16x32_bf16(Bf[n], At[m], acc[mh * 4 + m][n], 0, 0, 0);
;         __builtin_amdgcn_s_setprio(0);
;       }
;       SBAR();
;     }
;     if (t + 1 < nt) { WAIT_V0(); __syncthreads(); }
.Lkl_324_s8:
	s_waitcnt lgkmcnt(6)
	v_mfma_f32_16x16x32_bf16 v[46:49], v[154:157], v[192:195], v[46:49]
	v_mfma_f32_16x16x32_bf16 v[42:45], v[158:161], v[192:195], v[42:45]
	v_mfma_f32_16x16x32_bf16 v[38:41], v[162:165], v[192:195], v[38:41]
	v_mfma_f32_16x16x32_bf16 v[34:37], v[170:173], v[192:195], v[34:37]
	ds_read_b128 v[192:195], v178 offset:3072
	s_waitcnt lgkmcnt(5)
	v_mfma_f32_16x16x32_bf16 v[30:33], v[154:157], v[198:201], v[30:33]
	v_mfma_f32_16x16x32_bf16 v[26:29], v[158:161], v[198:201], v[26:29]
	v_mfma_f32_16x16x32_bf16 v[22:25], v[162:165], v[198:201], v[22:25]
	v_mfma_f32_16x16x32_bf16 v[18:21], v[170:173], v[198:201], v[18:21]
	ds_read_b128 v[198:201], v178 offset:5120
	s_waitcnt lgkmcnt(4)
	v_mfma_f32_16x16x32_bf16 v[14:17], v[154:157], v[204:207], v[14:17]
	v_mfma_f32_16x16x32_bf16 v[10:13], v[158:161], v[204:207], v[10:13]
	v_mfma_f32_16x16x32_bf16 v[6:9], v[162:165], v[204:207], v[6:9]
	v_mfma_f32_16x16x32_bf16 v[2:5], v[170:173], v[204:207], v[2:5]
	ds_read_b128 v[204:207], v178 offset:7168
	s_waitcnt lgkmcnt(3)
	v_mfma_f32_16x16x32_bf16 v[126:129], v[222:225], v[174:177], v[126:129]
	v_mfma_f32_16x16x32_bf16 v[122:125], v[226:229], v[174:177], v[122:125]
	v_mfma_f32_16x16x32_bf16 v[118:121], v[230:233], v[174:177], v[118:121]
	v_mfma_f32_16x16x32_bf16 v[114:117], v[234:237], v[174:177], v[114:117]
	ds_read_b128 v[174:177], v178 offset:9216
	s_waitcnt lgkmcnt(3)
	v_mfma_f32_16x16x32_bf16 v[110:113], v[222:225], v[192:195], v[110:113]
	v_mfma_f32_16x16x32_bf16 v[106:109], v[226:229], v[192:195], v[106:109]
	v_mfma_f32_16x16x32_bf16 v[102:105], v[230:233], v[192:195], v[102:105]
	v_mfma_f32_16x16x32_bf16 v[98:101], v[234:237], v[192:195], v[98:101]
	ds_read_b128 v[192:195], v178 offset:11264
	s_waitcnt lgkmcnt(3)
	v_mfma_f32_16x16x32_bf16 v[94:97], v[222:225], v[198:201], v[94:97]
	v_mfma_f32_16x16x32_bf16 v[90:93], v[226:229], v[198:201], v[90:93]
	v_mfma_f32_16x16x32_bf16 v[86:89], v[230:233], v[198:201], v[86:89]
	v_mfma_f32_16x16x32_bf16 v[82:85], v[234:237], v[198:201], v[82:85]
	ds_read_b128 v[198:201], v178 offset:13312
	s_waitcnt lgkmcnt(3)
	v_mfma_f32_16x16x32_bf16 v[78:81], v[222:225], v[204:207], v[78:81]
	v_mfma_f32_16x16x32_bf16 v[74:77], v[226:229], v[204:207], v[74:77]
	v_mfma_f32_16x16x32_bf16 v[70:73], v[230:233], v[204:207], v[70:73]
	v_mfma_f32_16x16x32_bf16 v[66:69], v[234:237], v[204:207], v[66:69]
	ds_read_b128 v[204:207], v178 offset:15360
	s_waitcnt lgkmcnt(3)
	v_mfma_f32_16x16x32_bf16 v[62:65], v[222:225], v[174:177], v[62:65]
	v_mfma_f32_16x16x32_bf16 v[58:61], v[226:229], v[174:177], v[58:61]
	v_mfma_f32_16x16x32_bf16 v[54:57], v[230:233], v[174:177], v[54:57]
	v_mfma_f32_16x16x32_bf16 v[50:53], v[234:237], v[174:177], v[50:53]
	s_waitcnt lgkmcnt(2)
	v_mfma_f32_16x16x32_bf16 v[46:49], v[222:225], v[192:195], v[46:49]
	v_mfma_f32_16x16x32_bf16 v[42:45], v[226:229], v[192:195], v[42:45]
	v_mfma_f32_16x16x32_bf16 v[38:41], v[230:233], v[192:195], v[38:41]
	v_mfma_f32_16x16x32_bf16 v[34:37], v[234:237], v[192:195], v[34:37]
	s_waitcnt lgkmcnt(0)
	s_waitcnt vmcnt(0)
	s_add_i32 s2, s2, 0x10000
	s_add_i32 s28, s28, 64
	s_cmp_eq_u32 s70, s3
	s_waitcnt vmcnt(0)
	s_barrier
	s_cselect_b32 s100, 1, 0
	s_and_b32 s11, s2, 0x10000
	v_or_b32_e32 v154, s11, v153
	v_add_u32_e32 v169, v154, v152
	v_or_b32_e32 v154, s11, v150
	v_add_u32_e32 v178, v154, v151
	ds_read_b128 v[154:157], v169 offset:32768
	ds_read_b128 v[158:161], v169 offset:34816
	ds_read_b128 v[162:165], v169 offset:36864
	ds_read_b128 v[170:173], v169 offset:38912
	ds_read_b128 v[174:177], v178
	ds_read_b128 v[192:195], v178 offset:2048
	s_cmp_eq_u32 s100, 1
	s_cbranch_scc1 .Lkl_324_s9
	s_xor_b32 s23, s11, 0x10000
	v_add_u32_e32 v246, s23, v145
	s_lshl_b64 s[30:31], s[28:29], 1
	v_add_u32_e32 v242, 0x8000, v246
	v_readfirstlane_b32 s23, v246
	v_lshl_add_u64 v[238:239], v[136:137], 0, s[30:31]
	s_mov_b32 m0, s23
	v_readfirstlane_b32 s23, v242
	v_add_u32_e32 v244, 0x2000, v246
	v_lshl_add_u64 v[240:241], v[138:139], 0, s[30:31]
	global_load_lds_dwordx4 v[238:239], off

; #define WAIT_V0() asm volatile("s_waitcnt vmcnt(0)" ::: "memory")
; #define SBAR() __builtin_amdgcn_sched_barrier(0)
; template <int EPI>
; DEVI void gemm_tile(const u16* __restrict__ Ab, long lda, const u16* __restrict__ Bb, long ldb, int K, const EpiArgs& e,
;                     bool have0 = false, const u16* __restrict__ nA = nullptr, const u16* __restrict__ nB = nullptr) {
;     ...
;   f32x4 acc[8][4];
; #pragma unroll
;   for (int m = 0; m < 8; ++m)
; #pragma unroll
;     for (int n = 0; n < 4; ++n) acc[m][n] = f32x4{0.f, 0.f, 0.f, 0.f};
;   const int nt = K / BK;
;   if (!have0) GLDS_STAGE(0, 0);
;   WAIT_V0(); __syncthreads();
;   for (int t = 0; t < nt; ++t) {
;     const int cur = t & 1;
;     if (t + 1 < nt) GLDS_STAGE(cur ^ 1, t + 1);
;     else if (nA) {
; #pragma unroll
;       for (int i = 0; i < GL; ++i) {
;         __builtin_amdgcn_global_load_lds((const unsigned*)(nA + (long)i * 64 * lda + toffA), (unsigned*)(g_shm + wid * 1024 + i * 8192), 16, 0, 0);
;         __builtin_amdgcn_global_load_lds((const unsigned*)(nB + (long)i * 64 * ldb + toffB), (unsigned*)(g_shm + TILE_B + wid * 1024 + i * 8192), 16, 0, 0);
;       }
;     }
;     const char* sb = g_shm + cur * STAGE_B;
; #pragma unroll
;     for (int ks = 0; ks < 2; ++ks) {
;       bf16x8 Bf[4];
; #pragma unroll
;       for (int n = 0; n < 4; ++n) Bf[n] = *(const bf16x8*)(sb + b_base + n * 2048 + ks * 1024);
; #pragma unroll
;       for (int mh = 0; mh < 2; ++mh) {
;         bf16x8 At[4];
; #pragma unroll
;         for (int m = 0; m < 4; ++m) At[m] = *(const bf16x8*)(sb + a_base + (mh * 4 + m) * 2048 + ks * 1024);
;         __builtin_amdgcn_s_setprio(1);
; #pragma unroll
;         for (int m = 0; m < 4; ++m)
; #pragma unroll
;           for (int n = 0; n < 4; ++n) acc[mh * 4 + m][n] = __builtin_amdgcn_mfma_f32_16x16x32_bf16(Bf[n], At[m], acc[mh * 4 + m][n], 0, 0, 0);
;         __builtin_amdgcn_s_setprio(0);
;       }
;       SBAR();
;     }
;     if (t + 1 < nt) { WAIT_V0(); __syncthreads(); }
.LBB0_359:
	s_and_b32 s3, s2, 0x10000
	v_or_b32_e32 v150, s3, v149
	v_add_u32_e32 v169, v150, v148
	v_or_b32_e32 v150, s3, v146
	v_add_u32_e32 v178, v150, v147
	ds_read_b128 v[150:153], v169 offset:32768
	ds_read_b128 v[154:157], v169 offset:34816
	ds_read_b128 v[158:161], v169 offset:36864
	ds_read_b128 v[162:165], v169 offset:38912
	ds_read_b128 v[170:173], v178
	ds_read_b128 v[174:177], v178 offset:2048
	ds_read_b128 v[192:195], v178 offset:4096
	ds_read_b128 v[198:201], v178 offset:6144
	v_writelane_b32 v240, s4, 0
	v_writelane_b32 v240, s5, 1
	v_writelane_b32 v240, s6, 2
	v_writelane_b32 v240, s7, 3
	v_writelane_b32 v240, s8, 4
	v_writelane_b32 v240, s9, 5
	v_writelane_b32 v240, s10, 6
	v_readfirstlane_b32 s4, v132
	v_readfirstlane_b32 s5, v133
	s_nop 1
	v_subrev_u32_e32 v238, s4, v132
	s_add_u32 s4, s4, s16
	s_addc_u32 s5, s5, s17
	v_readfirstlane_b32 s6, v134
	v_readfirstlane_b32 s7, v135
	s_nop 1
	v_subrev_u32_e32 v239, s6, v134
	s_add_u32 s6, s6, s16
	s_addc_u32 s7, s7, s17
	v_readfirstlane_b32 s8, v142
	s_nop 3
	s_lshr_b32 s8, s8, 10
	s_lshr_b32 s9, s8, 1
	s_lshl_b32 s9, s9, 4
	s_lshl_b32 s10, s8, 5
	s_sub_u32 s10, s10, s9
	s_mul_i32 s9, s10, 0x1000
	s_add_u32 s4, s4, s9
	s_addc_u32 s5, s5, 0
	s_and_b32 s9, s8, 1
	s_lshl_b32 s9, s9, 6
	s_sub_u32 s4, s4, s9
	s_subb_u32 s5, s5, 0
	v_readfirstlane_b32 s8, v142
	s_nop 3
	s_lshr_b32 s8, s8, 10
	s_lshr_b32 s9, s8, 1
	s_lshl_b32 s9, s9, 4
	s_lshl_b32 s10, s8, 5
	s_sub_u32 s10, s10, s9
	s_mul_i32 s9, s10, 0x1000
	s_add_u32 s6, s6, s9
	s_addc_u32 s7, s7, 0
	s_and_b32 s9, s8, 1
	s_lshl_b32 s9, s9, 6
	s_sub_u32 s6, s6, s9
	s_subb_u32 s7, s7, 0
	v_readfirstlane_b32 s10, v142
	s_xor_b32 s8, s3, 0x10000
	s_nop 0
	s_lshl_b32 s10, s10, 2
	s_add_i32 s10, s10, s8
	s_add_i32 m0, s10, 0x0
	s_add_u32 s8, s4, 0x32500080
	s_addc_u32 s9, s5, 0x0
	global_load_lds_dwordx4 v238, s[8:9]
.Lkl_359_s1:
	s_add_u32 s8, s4, 0x324ffcc0
	s_addc_u32 s9, s5, 0x0
	global_load_lds_dwordx4 v238, s[8:9] offset:1024
.Lkl_359_s2:
	s_add_u32 s8, s4, 0x3250f880
	s_addc_u32 s9, s5, 0x0
	global_load_lds_dwordx4 v238, s[8:9] offset:2048
.Lkl_359_s3:
.Lkl_359:
	s_waitcnt lgkmcnt(3)
	v_mfma_f32_16x16x32_bf16 v[126:129], v[150:153], v[170:173], v[126:129]
	v_mfma_f32_16x16x32_bf16 v[122:125], v[154:157], v[170:173], v[122:125]
	v_mfma_f32_16x16x32_bf16 v[118:121], v[158:161], v[170:173], v[118:121]
	v_mfma_f32_16x16x32_bf16 v[114:117], v[162:165], v[170:173], v[114:117]
	ds_read_b128 v[170:173], v178 offset:8192
	ds_read_b128 v[222:225], v169 offset:33792
	s_add_u32 s8, s4, 0x3250f4c0
	s_addc_u32 s9, s5, 0x0
	global_load_lds_dwordx4 v238, s[8:9] offset:3072
.Lkl_359_s4:
	s_waitcnt lgkmcnt(4)
	v_mfma_f32_16x16x32_bf16 v[110:113], v[150:153], v[174:177], v[110:113]
	v_mfma_f32_16x16x32_bf16 v[106:109], v[154:157], v[174:177], v[106:109]
	v_mfma_f32_16x16x32_bf16 v[102:105], v[158:161], v[174:177], v[102:105]
	v_mfma_f32_16x16x32_bf16 v[98:101], v[162:165], v[174:177], v[98:101]
	ds_read_b128 v[174:177], v178 offset:10240
	ds_read_b128 v[226:229], v169 offset:35840
	s_add_i32 m0, s10, 0x8000
	s_add_u32 s8, s6, 0x99c0080
	s_addc_u32 s9, s7, 0x0
	global_load_lds_dwordx4 v239, s[8:9]
.Lkl_359_s5:
	s_waitcnt lgkmcnt(5)
	v_mfma_f32_16x16x32_bf16 v[94:97], v[150:153], v[192:195], v[94:97]
	v_mfma_f32_16x16x32_bf16 v[90:93], v[154:157], v[192:195], v[90:93]
	v_mfma_f32_16x16x32_bf16 v[86:89], v[158:161], v[192:195], v[86:89]
	v_mfma_f32_16x16x32_bf16 v[82:85], v[162:165], v[192:195], v[82:85]
	ds_read_b128 v[192:195], v178 offset:12288
	ds_read_b128 v[230:233], v169 offset:37888
	s_add_u32 s8, s6, 0x99bfcc0
	s_addc_u32 s9, s7, 0x0
	global_load_lds_dwordx4 v239, s[8:9] offset:1024
.Lkl_359_s6:
	s_waitcnt lgkmcnt(6)
	v_mfma_f32_16x16x32_bf16 v[78:81], v[150:153], v[198:201], v[78:81]
	v_mfma_f32_16x16x32_bf16 v[74:77], v[154:157], v[198:201], v[74:77]
	v_mfma_f32_16x16x32_bf16 v[70:73], v[158:161], v[198:201], v[70:73]
	v_mfma_f32_16x16x32_bf16 v[66:69], v[162:165], v[198:201], v[66:69]
	ds_read_b128 v[198:201], v178 offset:14336
	ds_read_b128 v[234:237], v169 offset:39936
	s_add_u32 s8, s6, 0x99cf880
	s_addc_u32 s9, s7, 0x0
	global_load_lds_dwordx4 v239, s[8:9] offset:2048
.Lkl_359_s7:
	s_waitcnt lgkmcnt(7)
	v_mfma_f32_16x16x32_bf16 v[62:65], v[150:153], v[170:173], v[62:65]
	v_mfma_f32_16x16x32_bf16 v[58:61], v[154:157], v[170:173], v[58:61]
	v_mfma_f32_16x16x32_bf16 v[54:57], v[158:161], v[170:173], v[54:57]
	v_mfma_f32_16x16x32_bf16 v[50:53], v[162:165], v[170:173], v[50:53]
	ds_read_b128 v[170:173], v178 offset:1024
	s_add_u32 s8, s6, 0x99cf4c0
	s_addc_u32 s9, s7, 0x0
	global_load_lds_dwordx4 v239, s[8:9] offset:3072
; #define WAIT_V0() asm volatile("s_waitcnt vmcnt(0)" ::: "memory")
; #define SBAR() __builtin_amdgcn_sched_barrier(0)
; template <int EPI>
; DEVI void gemm_tile(const u16* __restrict__ Ab, long lda, const u16* __restrict__ Bb, long ldb, int K, const EpiArgs& e,
;                     bool have0 = false, const u16* __restrict__ nA = nullptr, const u16* __restrict__ nB = nullptr) {
;     ...
;     const char* sb = g_shm + cur * STAGE_B;
; #pragma unroll
;     for (int ks = 0; ks < 2; ++ks) {
;       bf16x8 Bf[4];
; #pragma unroll
;       for (int n = 0; n < 4; ++n) Bf[n] = *(const bf16x8*)(sb + b_base + n * 2048 + ks * 1024);
; #pragma unroll
;       for (int mh = 0; mh < 2; ++mh) {
;         bf16x8 At[4];
; #pragma unroll
;         for (int m = 0; m < 4; ++m) At[m] = *(const bf16x8*)(sb + a_base + (mh * 4 + m) * 2048 + ks * 1024);
;         __builtin_amdgcn_s_setprio(1);
; #pragma unroll
;         for (int m = 0; m < 4; ++m)
; #pragma unroll
;           for (int n = 0; n < 4; ++n) acc[mh * 4 + m][n] = __builtin_amdgcn_mfma_f32_16x16x32_bf16(Bf[n], At[m], acc[mh * 4 + m][n], 0, 0, 0);
;         __builtin_amdgcn_s_setprio(0);
;       }
;       SBAR();
;     }
;     if (t + 1 < nt) { WAIT_V0(); __syncthreads(); }
.Lkl_359_s8:
	s_waitcnt lgkmcnt(6)
	v_mfma_f32_16x16x32_bf16 v[46:49], v[150:153], v[174:177], v[46:49]
	v_mfma_f32_16x16x32_bf16 v[42:45], v[154:157], v[174:177], v[42:45]
	v_mfma_f32_16x16x32_bf16 v[38:41], v[158:161], v[174:177], v[38:41]
	v_mfma_f32_16x16x32_bf16 v[34:37], v[162:165], v[174:177], v[34:37]
	ds_read_b128 v[174:177], v178 offset:3072
	s_waitcnt lgkmcnt(5)
	v_mfma_f32_16x16x32_bf16 v[30:33], v[150:153], v[192:195], v[30:33]
	v_mfma_f32_16x16x32_bf16 v[26:29], v[154:157], v[192:195], v[26:29]
	v_mfma_f32_16x16x32_bf16 v[22:25], v[158:161], v[192:195], v[22:25]
	v_mfma_f32_16x16x32_bf16 v[18:21], v[162:165], v[192:195], v[18:21]
	ds_read_b128 v[192:195], v178 offset:5120
	s_waitcnt lgkmcnt(4)
	v_mfma_f32_16x16x32_bf16 v[14:17], v[150:153], v[198:201], v[14:17]
	v_mfma_f32_16x16x32_bf16 v[10:13], v[154:157], v[198:201], v[10:13]
	v_mfma_f32_16x16x32_bf16 v[6:9], v[158:161], v[198:201], v[6:9]
	v_mfma_f32_16x16x32_bf16 v[2:5], v[162:165], v[198:201], v[2:5]
	ds_read_b128 v[198:201], v178 offset:7168
	s_waitcnt lgkmcnt(3)
	v_mfma_f32_16x16x32_bf16 v[126:129], v[222:225], v[170:173], v[126:129]
	v_mfma_f32_16x16x32_bf16 v[122:125], v[226:229], v[170:173], v[122:125]
	v_mfma_f32_16x16x32_bf16 v[118:121], v[230:233], v[170:173], v[118:121]
	v_mfma_f32_16x16x32_bf16 v[114:117], v[234:237], v[170:173], v[114:117]
	ds_read_b128 v[170:173], v178 offset:9216
	s_waitcnt lgkmcnt(3)
	v_mfma_f32_16x16x32_bf16 v[110:113], v[222:225], v[174:177], v[110:113]
	v_mfma_f32_16x16x32_bf16 v[106:109], v[226:229], v[174:177], v[106:109]
	v_mfma_f32_16x16x32_bf16 v[102:105], v[230:233], v[174:177], v[102:105]
	v_mfma_f32_16x16x32_bf16 v[98:101], v[234:237], v[174:177], v[98:101]
	ds_read_b128 v[174:177], v178 offset:11264
	s_waitcnt lgkmcnt(3)
	v_mfma_f32_16x16x32_bf16 v[94:97], v[222:225], v[192:195], v[94:97]
	v_mfma_f32_16x16x32_bf16 v[90:93], v[226:229], v[192:195], v[90:93]
	v_mfma_f32_16x16x32_bf16 v[86:89], v[230:233], v[192:195], v[86:89]
	v_mfma_f32_16x16x32_bf16 v[82:85], v[234:237], v[192:195], v[82:85]
	ds_read_b128 v[192:195], v178 offset:13312
	s_waitcnt lgkmcnt(3)
	v_mfma_f32_16x16x32_bf16 v[78:81], v[222:225], v[198:201], v[78:81]
	v_mfma_f32_16x16x32_bf16 v[74:77], v[226:229], v[198:201], v[74:77]
	v_mfma_f32_16x16x32_bf16 v[70:73], v[230:233], v[198:201], v[70:73]
	v_mfma_f32_16x16x32_bf16 v[66:69], v[234:237], v[198:201], v[66:69]
	ds_read_b128 v[198:201], v178 offset:15360
	s_waitcnt lgkmcnt(3)
	v_mfma_f32_16x16x32_bf16 v[62:65], v[222:225], v[170:173], v[62:65]
	v_mfma_f32_16x16x32_bf16 v[58:61], v[226:229], v[170:173], v[58:61]
	v_mfma_f32_16x16x32_bf16 v[54:57], v[230:233], v[170:173], v[54:57]
	v_mfma_f32_16x16x32_bf16 v[50:53], v[234:237], v[170:173], v[50:53]
	s_waitcnt lgkmcnt(2)
	v_mfma_f32_16x16x32_bf16 v[46:49], v[222:225], v[174:177], v[46:49]
	v_mfma_f32_16x16x32_bf16 v[42:45], v[226:229], v[174:177], v[42:45]
	v_mfma_f32_16x16x32_bf16 v[38:41], v[230:233], v[174:177], v[38:41]
	v_mfma_f32_16x16x32_bf16 v[34:37], v[234:237], v[174:177], v[34:37]
	s_waitcnt lgkmcnt(0)
	s_waitcnt vmcnt(0)
	s_add_u32 s16, s16, 0x80
	s_addc_u32 s17, s17, 0
	s_add_i32 s2, s2, 0x10000
	s_cmpk_eq_i32 s16, 0xf80
	s_waitcnt vmcnt(0)
	s_barrier
	s_cselect_b32 s100, 1, 0
	s_and_b32 s3, s2, 0x10000
	v_or_b32_e32 v150, s3, v149
	v_add_u32_e32 v169, v150, v148
	v_or_b32_e32 v150, s3, v146
	v_add_u32_e32 v178, v150, v147
	ds_read_b128 v[150:153], v169 offset:32768
	ds_read_b128 v[154:157], v169 offset:34816
	ds_read_b128 v[158:161], v169 offset:36864
	ds_read_b128 v[162:165], v169 offset:38912
	ds_read_b128 v[170:173], v178
	ds_read_b128 v[174:177], v178 offset:2048
	s_add_u32 s4, s4, 0x80
	s_addc_u32 s5, s5, 0
	s_add_u32 s6, s6, 0x80
	s_addc_u32 s7, s7, 0
	s_cmp_eq_u32 s100, 1
	s_cbranch_scc1 .Lkl_359_s9
	v_readfirstlane_b32 s10, v142
	s_xor_b32 s8, s3, 0x10000
	s_nop 0
	s_lshl_b32 s10, s10, 2
	s_add_i32 s10, s10, s8
	s_add_i32 m0, s10, 0x0
	s_add_u32 s8, s4, 0x32500080
	s_addc_u32 s9, s5, 0x0
	global_load_lds_dwordx4 v238, s[8:9]
.Lkl_359_s9:
	v_mfma_f32_16x16x32_bf16 v[30:33], v[222:225], v[192:195], v[30:33]
	v_mfma_f32_16x16x32_bf16 v[26:29], v[226:229], v[192:195], v[26:29]
	v_mfma_f32_16x16x32_bf16 v[22:25], v[230:233], v[192:195], v[22:25]
	v_mfma_f32_16x16x32_bf16 v[18:21], v[234:237], v[192:195], v[18:21]
	ds_read_b128 v[192:195], v178 offset:4096
	s_cmp_eq_u32 s100, 1
	s_cbranch_scc1 .Lkl_359_s10
	s_add_u32 s8, s4, 0x324ffcc0
	s_addc_u32 s9, s5, 0x0
	global_load_lds_dwordx4 v238, s[8:9] offset:1024
.Lkl_359_s10:
	v_mfma_f32_16x16x32_bf16 v[14:17], v[222:225], v[198:201], v[14:17]
	v_mfma_f32_16x16x32_bf16 v[10:13], v[226:229], v[198:201], v[10:13]
	v_mfma_f32_16x16x32_bf16 v[6:9], v[230:233], v[198:201], v[6:9]
	v_mfma_f32_16x16x32_bf16 v[2:5], v[234:237], v[198:201], v[2:5]
	ds_read_b128 v[198:201], v178 offset:6144
	s_cmp_eq_u32 s100, 1
	s_cbranch_scc1 .Lkl_359_s11
	s_add_u32 s8, s4, 0x3250f880
	s_addc_u32 s9, s5, 0x0
	global_load_lds_dwordx4 v238, s[8:9] offset:2048

; #define WAIT_V0() asm volatile("s_waitcnt vmcnt(0)" ::: "memory")
; #define SBAR() __builtin_amdgcn_sched_barrier(0)
; template <int EPI>
; DEVI void gemm_tile(const u16* __restrict__ Ab, long lda, const u16* __restrict__ Bb, long ldb, int K, const EpiArgs& e,
;                     bool have0 = false, const u16* __restrict__ nA = nullptr, const u16* __restrict__ nB = nullptr) {
;     ...
;   f32x4 acc[8][4];
; #pragma unroll
;   for (int m = 0; m < 8; ++m)
; #pragma unroll
;     for (int n = 0; n < 4; ++n) acc[m][n] = f32x4{0.f, 0.f, 0.f, 0.f};
;   const int nt = K / BK;
;   if (!have0) GLDS_STAGE(0, 0);
;   WAIT_V0(); __syncthreads();
;   for (int t = 0; t < nt; ++t) {
;     const int cur = t & 1;
;     if (t + 1 < nt) GLDS_STAGE(cur ^ 1, t + 1);
;     else if (nA) {
; #pragma unroll
;       for (int i = 0; i < GL; ++i) {
;         __builtin_amdgcn_global_load_lds((const unsigned*)(nA + (long)i * 64 * lda + toffA), (unsigned*)(g_shm + wid * 1024 + i * 8192), 16, 0, 0);
;         __builtin_amdgcn_global_load_lds((const unsigned*)(nB + (long)i * 64 * ldb + toffB), (unsigned*)(g_shm + TILE_B + wid * 1024 + i * 8192), 16, 0, 0);
;       }
;     }
;     const char* sb = g_shm + cur * STAGE_B;
; #pragma unroll
;     for (int ks = 0; ks < 2; ++ks) {
;       bf16x8 Bf[4];
; #pragma unroll
;       for (int n = 0; n < 4; ++n) Bf[n] = *(const bf16x8*)(sb + b_base + n * 2048 + ks * 1024);
; #pragma unroll
;       for (int mh = 0; mh < 2; ++mh) {
;         bf16x8 At[4];
; #pragma unroll
;         for (int m = 0; m < 4; ++m) At[m] = *(const bf16x8*)(sb + a_base + (mh * 4 + m) * 2048 + ks * 1024);
;         __builtin_amdgcn_s_setprio(1);
; #pragma unroll
;         for (int m = 0; m < 4; ++m)
; #pragma unroll
;           for (int n = 0; n < 4; ++n) acc[mh * 4 + m][n] = __builtin_amdgcn_mfma_f32_16x16x32_bf16(Bf[n], At[m], acc[mh * 4 + m][n], 0, 0, 0);
;         __builtin_amdgcn_s_setprio(0);
;       }
;       SBAR();
;     }
;     if (t + 1 < nt) { WAIT_V0(); __syncthreads(); }
.LBB0_459:
	s_and_b32 s3, s2, 0x10000
	v_or_b32_e32 v150, s3, v149
	v_add_u32_e32 v169, v150, v148
	v_or_b32_e32 v150, s3, v146
	v_add_u32_e32 v178, v150, v147
	ds_read_b128 v[150:153], v169 offset:32768
	ds_read_b128 v[154:157], v169 offset:34816
	ds_read_b128 v[158:161], v169 offset:36864
	ds_read_b128 v[162:165], v169 offset:38912
	ds_read_b128 v[170:173], v178
	ds_read_b128 v[174:177], v178 offset:2048
	ds_read_b128 v[192:195], v178 offset:4096
	ds_read_b128 v[198:201], v178 offset:6144
	v_writelane_b32 v240, s4, 0
	v_writelane_b32 v240, s5, 1
	v_writelane_b32 v240, s6, 2
	v_writelane_b32 v240, s7, 3
	v_writelane_b32 v240, s8, 4
	v_writelane_b32 v240, s9, 5
	v_writelane_b32 v240, s10, 6
	v_readfirstlane_b32 s4, v132
	v_readfirstlane_b32 s5, v133
	s_nop 1
	v_subrev_u32_e32 v238, s4, v132
	s_add_u32 s4, s4, s14
	s_addc_u32 s5, s5, s15
	v_readfirstlane_b32 s6, v134
	v_readfirstlane_b32 s7, v135
	s_nop 1
	v_subrev_u32_e32 v239, s6, v134
	s_add_u32 s6, s6, s14
	s_addc_u32 s7, s7, s15
	v_readfirstlane_b32 s8, v142
	s_nop 3
	s_lshr_b32 s8, s8, 10
	s_lshr_b32 s9, s8, 1
	s_lshl_b32 s9, s9, 4
	s_lshl_b32 s10, s8, 5
	s_sub_u32 s10, s10, s9
	s_mul_i32 s9, s10, 0x800
	s_add_u32 s4, s4, s9
	s_addc_u32 s5, s5, 0
	s_and_b32 s9, s8, 1
	s_lshl_b32 s9, s9, 6
	s_sub_u32 s4, s4, s9
	s_subb_u32 s5, s5, 0
	v_readfirstlane_b32 s8, v142
	s_nop 3
	s_lshr_b32 s8, s8, 10
	s_lshr_b32 s9, s8, 1
	s_lshl_b32 s9, s9, 4
	s_lshl_b32 s10, s8, 5
	s_sub_u32 s10, s10, s9
	s_mul_i32 s9, s10, 0x800
	s_add_u32 s6, s6, s9
	s_addc_u32 s7, s7, 0
	s_and_b32 s9, s8, 1
	s_lshl_b32 s9, s9, 6
	s_sub_u32 s6, s6, s9
	s_subb_u32 s7, s7, 0
	v_readfirstlane_b32 s10, v142
	s_xor_b32 s8, s3, 0x10000
	s_nop 0
	s_lshl_b32 s10, s10, 2
	s_add_i32 s10, s10, s8
	s_add_i32 m0, s10, 0x0
	s_add_u32 s8, s4, s30
	s_addc_u32 s9, s5, s31
	global_load_lds_dwordx4 v238, s[8:9]
.Lkl_459_s1:
	s_add_u32 s8, s4, s30
	s_addc_u32 s9, s5, s31
	s_add_u32 s8, s8, 0xfffffc40
	s_addc_u32 s9, s9, 0xffffffff
	global_load_lds_dwordx4 v238, s[8:9] offset:1024
.Lkl_459_s2:
	s_add_u32 s8, s4, s30
	s_addc_u32 s9, s5, s31
	s_add_u32 s8, s8, 0x7800
	s_addc_u32 s9, s9, 0x0
	global_load_lds_dwordx4 v238, s[8:9] offset:2048
.Lkl_459_s3:
.Lkl_459:
	s_waitcnt lgkmcnt(3)
	v_mfma_f32_16x16x32_bf16 v[126:129], v[150:153], v[170:173], v[126:129]
	v_mfma_f32_16x16x32_bf16 v[122:125], v[154:157], v[170:173], v[122:125]
	v_mfma_f32_16x16x32_bf16 v[118:121], v[158:161], v[170:173], v[118:121]
	v_mfma_f32_16x16x32_bf16 v[114:117], v[162:165], v[170:173], v[114:117]
	ds_read_b128 v[170:173], v178 offset:8192
	ds_read_b128 v[222:225], v169 offset:33792
	s_add_u32 s8, s4, s30
	s_addc_u32 s9, s5, s31
	s_add_u32 s8, s8, 0x7440
	s_addc_u32 s9, s9, 0x0
	global_load_lds_dwordx4 v238, s[8:9] offset:3072
.Lkl_459_s4:
	s_waitcnt lgkmcnt(4)
	v_mfma_f32_16x16x32_bf16 v[110:113], v[150:153], v[174:177], v[110:113]
	v_mfma_f32_16x16x32_bf16 v[106:109], v[154:157], v[174:177], v[106:109]
	v_mfma_f32_16x16x32_bf16 v[102:105], v[158:161], v[174:177], v[102:105]
	v_mfma_f32_16x16x32_bf16 v[98:101], v[162:165], v[174:177], v[98:101]
	ds_read_b128 v[174:177], v178 offset:10240
	ds_read_b128 v[226:229], v169 offset:35840
	s_add_i32 m0, s10, 0x8000
	s_add_u32 s8, s6, s20
	s_addc_u32 s9, s7, s21
	global_load_lds_dwordx4 v239, s[8:9]
.Lkl_459_s5:
	s_waitcnt lgkmcnt(5)
	v_mfma_f32_16x16x32_bf16 v[94:97], v[150:153], v[192:195], v[94:97]
	v_mfma_f32_16x16x32_bf16 v[90:93], v[154:157], v[192:195], v[90:93]
	v_mfma_f32_16x16x32_bf16 v[86:89], v[158:161], v[192:195], v[86:89]
	v_mfma_f32_16x16x32_bf16 v[82:85], v[162:165], v[192:195], v[82:85]
	ds_read_b128 v[192:195], v178 offset:12288
	ds_read_b128 v[230:233], v169 offset:37888
	s_add_u32 s8, s6, s20
	s_addc_u32 s9, s7, s21
	s_add_u32 s8, s8, 0xfffffc40
	s_addc_u32 s9, s9, 0xffffffff
	global_load_lds_dwordx4 v239, s[8:9] offset:1024
.Lkl_459_s6:
	s_waitcnt lgkmcnt(6)
	v_mfma_f32_16x16x32_bf16 v[78:81], v[150:153], v[198:201], v[78:81]
	v_mfma_f32_16x16x32_bf16 v[74:77], v[154:157], v[198:201], v[74:77]
	v_mfma_f32_16x16x32_bf16 v[70:73], v[158:161], v[198:201], v[70:73]
	v_mfma_f32_16x16x32_bf16 v[66:69], v[162:165], v[198:201], v[66:69]
	ds_read_b128 v[198:201], v178 offset:14336
	ds_read_b128 v[234:237], v169 offset:39936
	s_add_u32 s8, s6, s20
	s_addc_u32 s9, s7, s21
	s_add_u32 s8, s8, 0x7800
	s_addc_u32 s9, s9, 0x0
	global_load_lds_dwordx4 v239, s[8:9] offset:2048
.Lkl_459_s7:
	s_waitcnt lgkmcnt(7)
	v_mfma_f32_16x16x32_bf16 v[62:65], v[150:153], v[170:173], v[62:65]
	v_mfma_f32_16x16x32_bf16 v[58:61], v[154:157], v[170:173], v[58:61]
	v_mfma_f32_16x16x32_bf16 v[54:57], v[158:161], v[170:173], v[54:57]
	v_mfma_f32_16x16x32_bf16 v[50:53], v[162:165], v[170:173], v[50:53]
	ds_read_b128 v[170:173], v178 offset:1024
	s_add_u32 s8, s6, s20
	s_addc_u32 s9, s7, s21
	s_add_u32 s8, s8, 0x7440
	s_addc_u32 s9, s9, 0x0
	global_load_lds_dwordx4 v239, s[8:9] offset:3072
; #define WAIT_V0() asm volatile("s_waitcnt vmcnt(0)" ::: "memory")
; #define SBAR() __builtin_amdgcn_sched_barrier(0)
; template <int EPI>
; DEVI void gemm_tile(const u16* __restrict__ Ab, long lda, const u16* __restrict__ Bb, long ldb, int K, const EpiArgs& e,
;                     bool have0 = false, const u16* __restrict__ nA = nullptr, const u16* __restrict__ nB = nullptr) {
;     ...
;     const char* sb = g_shm + cur * STAGE_B;
; #pragma unroll
;     for (int ks = 0; ks < 2; ++ks) {
;       bf16x8 Bf[4];
; #pragma unroll
;       for (int n = 0; n < 4; ++n) Bf[n] = *(const bf16x8*)(sb + b_base + n * 2048 + ks * 1024);
; #pragma unroll
;       for (int mh = 0; mh < 2; ++mh) {
;         bf16x8 At[4];
; #pragma unroll
;         for (int m = 0; m < 4; ++m) At[m] = *(const bf16x8*)(sb + a_base + (mh * 4 + m) * 2048 + ks * 1024);
;         __builtin_amdgcn_s_setprio(1);
; #pragma unroll
;         for (int m = 0; m < 4; ++m)
; #pragma unroll
;           for (int n = 0; n < 4; ++n) acc[mh * 4 + m][n] = __builtin_amdgcn_mfma_f32_16x16x32_bf16(Bf[n], At[m], acc[mh * 4 + m][n], 0, 0, 0);
;         __builtin_amdgcn_s_setprio(0);
;       }
;       SBAR();
;     }
;     if (t + 1 < nt) { WAIT_V0(); __syncthreads(); }
.Lkl_459_s8:
	s_waitcnt lgkmcnt(6)
	v_mfma_f32_16x16x32_bf16 v[46:49], v[150:153], v[174:177], v[46:49]
	v_mfma_f32_16x16x32_bf16 v[42:45], v[154:157], v[174:177], v[42:45]
	v_mfma_f32_16x16x32_bf16 v[38:41], v[158:161], v[174:177], v[38:41]
	v_mfma_f32_16x16x32_bf16 v[34:37], v[162:165], v[174:177], v[34:37]
	ds_read_b128 v[174:177], v178 offset:3072
	s_waitcnt lgkmcnt(5)
	v_mfma_f32_16x16x32_bf16 v[30:33], v[150:153], v[192:195], v[30:33]
	v_mfma_f32_16x16x32_bf16 v[26:29], v[154:157], v[192:195], v[26:29]
	v_mfma_f32_16x16x32_bf16 v[22:25], v[158:161], v[192:195], v[22:25]
	v_mfma_f32_16x16x32_bf16 v[18:21], v[162:165], v[192:195], v[18:21]
	ds_read_b128 v[192:195], v178 offset:5120
	s_waitcnt lgkmcnt(4)
	v_mfma_f32_16x16x32_bf16 v[14:17], v[150:153], v[198:201], v[14:17]
	v_mfma_f32_16x16x32_bf16 v[10:13], v[154:157], v[198:201], v[10:13]
	v_mfma_f32_16x16x32_bf16 v[6:9], v[158:161], v[198:201], v[6:9]
	v_mfma_f32_16x16x32_bf16 v[2:5], v[162:165], v[198:201], v[2:5]
	ds_read_b128 v[198:201], v178 offset:7168
	s_waitcnt lgkmcnt(3)
	v_mfma_f32_16x16x32_bf16 v[126:129], v[222:225], v[170:173], v[126:129]
	v_mfma_f32_16x16x32_bf16 v[122:125], v[226:229], v[170:173], v[122:125]
	v_mfma_f32_16x16x32_bf16 v[118:121], v[230:233], v[170:173], v[118:121]
	v_mfma_f32_16x16x32_bf16 v[114:117], v[234:237], v[170:173], v[114:117]
	ds_read_b128 v[170:173], v178 offset:9216
	s_waitcnt lgkmcnt(3)
	v_mfma_f32_16x16x32_bf16 v[110:113], v[222:225], v[174:177], v[110:113]
	v_mfma_f32_16x16x32_bf16 v[106:109], v[226:229], v[174:177], v[106:109]
	v_mfma_f32_16x16x32_bf16 v[102:105], v[230:233], v[174:177], v[102:105]
	v_mfma_f32_16x16x32_bf16 v[98:101], v[234:237], v[174:177], v[98:101]
	ds_read_b128 v[174:177], v178 offset:11264
	s_waitcnt lgkmcnt(3)
	v_mfma_f32_16x16x32_bf16 v[94:97], v[222:225], v[192:195], v[94:97]
	v_mfma_f32_16x16x32_bf16 v[90:93], v[226:229], v[192:195], v[90:93]
	v_mfma_f32_16x16x32_bf16 v[86:89], v[230:233], v[192:195], v[86:89]
	v_mfma_f32_16x16x32_bf16 v[82:85], v[234:237], v[192:195], v[82:85]
	ds_read_b128 v[192:195], v178 offset:13312
	s_waitcnt lgkmcnt(3)
	v_mfma_f32_16x16x32_bf16 v[78:81], v[222:225], v[198:201], v[78:81]
	v_mfma_f32_16x16x32_bf16 v[74:77], v[226:229], v[198:201], v[74:77]
	v_mfma_f32_16x16x32_bf16 v[70:73], v[230:233], v[198:201], v[70:73]
	v_mfma_f32_16x16x32_bf16 v[66:69], v[234:237], v[198:201], v[66:69]
	ds_read_b128 v[198:201], v178 offset:15360
	s_waitcnt lgkmcnt(3)
	v_mfma_f32_16x16x32_bf16 v[62:65], v[222:225], v[170:173], v[62:65]
	v_mfma_f32_16x16x32_bf16 v[58:61], v[226:229], v[170:173], v[58:61]
	v_mfma_f32_16x16x32_bf16 v[54:57], v[230:233], v[170:173], v[54:57]
	v_mfma_f32_16x16x32_bf16 v[50:53], v[234:237], v[170:173], v[50:53]
	s_waitcnt lgkmcnt(2)
	v_mfma_f32_16x16x32_bf16 v[46:49], v[222:225], v[174:177], v[46:49]
	v_mfma_f32_16x16x32_bf16 v[42:45], v[226:229], v[174:177], v[42:45]
	v_mfma_f32_16x16x32_bf16 v[38:41], v[230:233], v[174:177], v[38:41]
	v_mfma_f32_16x16x32_bf16 v[34:37], v[234:237], v[174:177], v[34:37]
	s_waitcnt lgkmcnt(0)
	s_waitcnt vmcnt(0)
	s_add_u32 s14, s14, 0x80
	s_addc_u32 s15, s15, 0
	s_add_i32 s2, s2, 0x10000
	s_cmpk_eq_i32 s14, 0x780
	s_waitcnt vmcnt(0)
	s_barrier
	s_cselect_b32 s100, 1, 0
	s_and_b32 s3, s2, 0x10000
	v_or_b32_e32 v150, s3, v149
	v_add_u32_e32 v169, v150, v148
	v_or_b32_e32 v150, s3, v146
	v_add_u32_e32 v178, v150, v147
	ds_read_b128 v[150:153], v169 offset:32768
	ds_read_b128 v[154:157], v169 offset:34816
	ds_read_b128 v[158:161], v169 offset:36864
	ds_read_b128 v[162:165], v169 offset:38912
	ds_read_b128 v[170:173], v178
	ds_read_b128 v[174:177], v178 offset:2048
	s_add_u32 s4, s4, 0x80
	s_addc_u32 s5, s5, 0
	s_add_u32 s6, s6, 0x80
	s_addc_u32 s7, s7, 0
	s_cmp_eq_u32 s100, 1
	s_cbranch_scc1 .Lkl_459_s9
	v_readfirstlane_b32 s10, v142
	s_xor_b32 s8, s3, 0x10000
	s_nop 0
	s_lshl_b32 s10, s10, 2
	s_add_i32 s10, s10, s8
	s_add_i32 m0, s10, 0x0
	s_add_u32 s8, s4, s30
	s_addc_u32 s9, s5, s31
	global_load_lds_dwordx4 v238, s[8:9]
.Lkl_459_s9:
	v_mfma_f32_16x16x32_bf16 v[30:33], v[222:225], v[192:195], v[30:33]
	v_mfma_f32_16x16x32_bf16 v[26:29], v[226:229], v[192:195], v[26:29]
	v_mfma_f32_16x16x32_bf16 v[22:25], v[230:233], v[192:195], v[22:25]
	v_mfma_f32_16x16x32_bf16 v[18:21], v[234:237], v[192:195], v[18:21]
	ds_read_b128 v[192:195], v178 offset:4096
	s_cmp_eq_u32 s100, 1
	s_cbranch_scc1 .Lkl_459_s10
	s_add_u32 s8, s4, s30
	s_addc_u32 s9, s5, s31
	s_add_u32 s8, s8, 0xfffffc40
	s_addc_u32 s9, s9, 0xffffffff
	global_load_lds_dwordx4 v238, s[8:9] offset:1024
.Lkl_459_s10:
	v_mfma_f32_16x16x32_bf16 v[14:17], v[222:225], v[198:201], v[14:17]
	v_mfma_f32_16x16x32_bf16 v[10:13], v[226:229], v[198:201], v[10:13]
	v_mfma_f32_16x16x32_bf16 v[6:9], v[230:233], v[198:201], v[6:9]
	v_mfma_f32_16x16x32_bf16 v[2:5], v[234:237], v[198:201], v[2:5]
	ds_read_b128 v[198:201], v178 offset:6144
	s_cmp_eq_u32 s100, 1
	s_cbranch_scc1 .Lkl_459_s11
	s_add_u32 s8, s4, s30
	s_addc_u32 s9, s5, s31
	s_add_u32 s8, s8, 0x7800
	s_addc_u32 s9, s9, 0x0
	global_load_lds_dwordx4 v238, s[8:9] offset:2048

; #define WAIT_V0() asm volatile("s_waitcnt vmcnt(0)" ::: "memory")
; template <int EPI>
; DEVI void gemm_tile(const u16* __restrict__ Ab, long lda, const u16* __restrict__ Bb, long ldb, int K, const EpiArgs& e,
;                     bool have0 = false, const u16* __restrict__ nA = nullptr, const u16* __restrict__ nB = nullptr) {
;     ...
;   f32x4 acc[8][4];
; #pragma unroll
;   for (int m = 0; m < 8; ++m)
; #pragma unroll
;     for (int n = 0; n < 4; ++n) acc[m][n] = f32x4{0.f, 0.f, 0.f, 0.f};
;   const int nt = K / BK;
;   if (!have0) GLDS_STAGE(0, 0);
;   WAIT_V0(); __syncthreads();
;   for (int t = 0; t < nt; ++t) {
;     const int cur = t & 1;
;     if (t + 1 < nt) GLDS_STAGE(cur ^ 1, t + 1);
;     else if (nA) {
; #pragma unroll
;       for (int i = 0; i < GL; ++i) {
;         __builtin_amdgcn_global_load_lds((const unsigned*)(nA + (long)i * 64 * lda + toffA), (unsigned*)(g_shm + wid * 1024 + i * 8192), 16, 0, 0);
;         __builtin_amdgcn_global_load_lds((const unsigned*)(nB + (long)i * 64 * ldb + toffB), (unsigned*)(g_shm + TILE_B + wid * 1024 + i * 8192), 16, 0, 0);
;       }
;     }
;     const char* sb = g_shm + cur * STAGE_B;
; #pragma unroll
;     for (int ks = 0; ks < 2; ++ks) {
;       bf16x8 Bf[4];
; #pragma unroll
;       for (int n = 0; n < 4; ++n) Bf[n] = *(const bf16x8*)(sb + b_base + n * 2048 + ks * 1024);
; #pragma unroll
;       for (int mh = 0; mh < 2; ++mh) {
;         bf16x8 At[4];
; #pragma unroll
;         for (int m = 0; m < 4; ++m) At[m] = *(const bf16x8*)(sb + a_base + (mh * 4 + m) * 2048 + ks * 1024);
.LBB0_710:
	s_and_b32 s3, s2, 0x10000
	v_or_b32_e32 v150, s3, v149
	v_add_u32_e32 v169, v150, v148
	v_or_b32_e32 v150, s3, v146
	v_add_u32_e32 v178, v150, v147
	ds_read_b128 v[150:153], v169 offset:32768
	ds_read_b128 v[154:157], v169 offset:34816
	ds_read_b128 v[158:161], v169 offset:36864
	ds_read_b128 v[162:165], v169 offset:38912
	ds_read_b128 v[170:173], v178
	ds_read_b128 v[174:177], v178 offset:2048
	ds_read_b128 v[192:195], v178 offset:4096
	ds_read_b128 v[198:201], v178 offset:6144
	v_writelane_b32 v240, s4, 0
	v_writelane_b32 v240, s5, 1
	v_writelane_b32 v240, s6, 2
	v_writelane_b32 v240, s7, 3
	v_writelane_b32 v240, s8, 4
	v_writelane_b32 v240, s9, 5
	v_writelane_b32 v240, s10, 6
	v_readfirstlane_b32 s4, v132
	v_readfirstlane_b32 s5, v133
	s_nop 1
	v_subrev_u32_e32 v238, s4, v132
	s_add_u32 s4, s4, s14
	s_addc_u32 s5, s5, s15
	v_readfirstlane_b32 s6, v134
	v_readfirstlane_b32 s7, v135
	s_nop 1
	v_subrev_u32_e32 v239, s6, v134
	s_add_u32 s6, s6, s14
	s_addc_u32 s7, s7, s15
	v_readfirstlane_b32 s8, v142
	s_nop 3
	s_lshr_b32 s8, s8, 10
	s_lshr_b32 s9, s8, 1
	s_lshl_b32 s9, s9, 4
	s_lshl_b32 s10, s8, 5
	s_sub_u32 s10, s10, s9
	s_mul_i32 s9, s10, 0x800
	s_add_u32 s4, s4, s9
	s_addc_u32 s5, s5, 0
	s_and_b32 s9, s8, 1
	s_lshl_b32 s9, s9, 6
	s_sub_u32 s4, s4, s9
	s_subb_u32 s5, s5, 0
	v_readfirstlane_b32 s8, v142
	s_nop 3
	s_lshr_b32 s8, s8, 10
	s_lshr_b32 s9, s8, 1
	s_lshl_b32 s9, s9, 4
	s_lshl_b32 s10, s8, 5
	s_sub_u32 s10, s10, s9
	s_mul_i32 s9, s10, 0x800
	s_add_u32 s6, s6, s9
	s_addc_u32 s7, s7, 0
	s_and_b32 s9, s8, 1
	s_lshl_b32 s9, s9, 6
	s_sub_u32 s6, s6, s9
	s_subb_u32 s7, s7, 0
	v_readfirstlane_b32 s10, v142
	s_xor_b32 s8, s3, 0x10000
	s_nop 0
	s_lshl_b32 s10, s10, 2
	s_add_i32 s10, s10, s8
	s_add_i32 m0, s10, 0x0
	s_add_u32 s8, s4, 0xe500080
	s_addc_u32 s9, s5, 0x0
	global_load_lds_dwordx4 v238, s[8:9]
.Lkl_710_s1:
	s_add_u32 s8, s4, 0xe4ffcc0
	s_addc_u32 s9, s5, 0x0
	global_load_lds_dwordx4 v238, s[8:9] offset:1024
.Lkl_710_s2:
	s_add_u32 s8, s4, 0xe507880
	s_addc_u32 s9, s5, 0x0
	global_load_lds_dwordx4 v238, s[8:9] offset:2048
.Lkl_710_s3:
.Lkl_710:
	s_waitcnt lgkmcnt(3)
	v_mfma_f32_16x16x32_bf16 v[126:129], v[150:153], v[170:173], v[126:129]
	v_mfma_f32_16x16x32_bf16 v[122:125], v[154:157], v[170:173], v[122:125]
	v_mfma_f32_16x16x32_bf16 v[118:121], v[158:161], v[170:173], v[118:121]
	v_mfma_f32_16x16x32_bf16 v[114:117], v[162:165], v[170:173], v[114:117]
	ds_read_b128 v[170:173], v178 offset:8192
	ds_read_b128 v[222:225], v169 offset:33792
	s_add_u32 s8, s4, 0xe5074c0
	s_addc_u32 s9, s5, 0x0
	global_load_lds_dwordx4 v238, s[8:9] offset:3072

; #define WAIT_V0() asm volatile("s_waitcnt vmcnt(0)" ::: "memory")
; #define SBAR() __builtin_amdgcn_sched_barrier(0)
; template <int EPI>
; DEVI void gemm_tile(const u16* __restrict__ Ab, long lda, const u16* __restrict__ Bb, long ldb, int K, const EpiArgs& e,
;                     bool have0 = false, const u16* __restrict__ nA = nullptr, const u16* __restrict__ nB = nullptr) {
;     ...
;     const char* sb = g_shm + cur * STAGE_B;
; #pragma unroll
;     for (int ks = 0; ks < 2; ++ks) {
;       bf16x8 Bf[4];
; #pragma unroll
;       for (int n = 0; n < 4; ++n) Bf[n] = *(const bf16x8*)(sb + b_base + n * 2048 + ks * 1024);
; #pragma unroll
;       for (int mh = 0; mh < 2; ++mh) {
;         bf16x8 At[4];
; #pragma unroll
;         for (int m = 0; m < 4; ++m) At[m] = *(const bf16x8*)(sb + a_base + (mh * 4 + m) * 2048 + ks * 1024);
;         __builtin_amdgcn_s_setprio(1);
; #pragma unroll
;         for (int m = 0; m < 4; ++m)
; #pragma unroll
;           for (int n = 0; n < 4; ++n) acc[mh * 4 + m][n] = __builtin_amdgcn_mfma_f32_16x16x32_bf16(Bf[n], At[m], acc[mh * 4 + m][n], 0, 0, 0);
;         __builtin_amdgcn_s_setprio(0);
;       }
;       SBAR();
;     }
;     if (t + 1 < nt) { WAIT_V0(); __syncthreads(); }
.Lkl_710_s8:
	s_waitcnt lgkmcnt(6)
	v_mfma_f32_16x16x32_bf16 v[46:49], v[150:153], v[174:177], v[46:49]
	v_mfma_f32_16x16x32_bf16 v[42:45], v[154:157], v[174:177], v[42:45]
	v_mfma_f32_16x16x32_bf16 v[38:41], v[158:161], v[174:177], v[38:41]
	v_mfma_f32_16x16x32_bf16 v[34:37], v[162:165], v[174:177], v[34:37]
	ds_read_b128 v[174:177], v178 offset:3072
	s_waitcnt lgkmcnt(5)
	v_mfma_f32_16x16x32_bf16 v[30:33], v[150:153], v[192:195], v[30:33]
	v_mfma_f32_16x16x32_bf16 v[26:29], v[154:157], v[192:195], v[26:29]
	v_mfma_f32_16x16x32_bf16 v[22:25], v[158:161], v[192:195], v[22:25]
	v_mfma_f32_16x16x32_bf16 v[18:21], v[162:165], v[192:195], v[18:21]
	ds_read_b128 v[192:195], v178 offset:5120
	s_waitcnt lgkmcnt(4)
	v_mfma_f32_16x16x32_bf16 v[14:17], v[150:153], v[198:201], v[14:17]
	v_mfma_f32_16x16x32_bf16 v[10:13], v[154:157], v[198:201], v[10:13]
	v_mfma_f32_16x16x32_bf16 v[6:9], v[158:161], v[198:201], v[6:9]
	v_mfma_f32_16x16x32_bf16 v[2:5], v[162:165], v[198:201], v[2:5]
	ds_read_b128 v[198:201], v178 offset:7168
	s_waitcnt lgkmcnt(3)
	v_mfma_f32_16x16x32_bf16 v[126:129], v[222:225], v[170:173], v[126:129]
	v_mfma_f32_16x16x32_bf16 v[122:125], v[226:229], v[170:173], v[122:125]
	v_mfma_f32_16x16x32_bf16 v[118:121], v[230:233], v[170:173], v[118:121]
	v_mfma_f32_16x16x32_bf16 v[114:117], v[234:237], v[170:173], v[114:117]
	ds_read_b128 v[170:173], v178 offset:9216
	s_waitcnt lgkmcnt(3)
	v_mfma_f32_16x16x32_bf16 v[110:113], v[222:225], v[174:177], v[110:113]
	v_mfma_f32_16x16x32_bf16 v[106:109], v[226:229], v[174:177], v[106:109]
	v_mfma_f32_16x16x32_bf16 v[102:105], v[230:233], v[174:177], v[102:105]
	v_mfma_f32_16x16x32_bf16 v[98:101], v[234:237], v[174:177], v[98:101]
	ds_read_b128 v[174:177], v178 offset:11264
	s_waitcnt lgkmcnt(3)
	v_mfma_f32_16x16x32_bf16 v[94:97], v[222:225], v[192:195], v[94:97]
	v_mfma_f32_16x16x32_bf16 v[90:93], v[226:229], v[192:195], v[90:93]
	v_mfma_f32_16x16x32_bf16 v[86:89], v[230:233], v[192:195], v[86:89]
	v_mfma_f32_16x16x32_bf16 v[82:85], v[234:237], v[192:195], v[82:85]
	ds_read_b128 v[192:195], v178 offset:13312
	s_waitcnt lgkmcnt(3)
	v_mfma_f32_16x16x32_bf16 v[78:81], v[222:225], v[198:201], v[78:81]
	v_mfma_f32_16x16x32_bf16 v[74:77], v[226:229], v[198:201], v[74:77]
	v_mfma_f32_16x16x32_bf16 v[70:73], v[230:233], v[198:201], v[70:73]
	v_mfma_f32_16x16x32_bf16 v[66:69], v[234:237], v[198:201], v[66:69]
	ds_read_b128 v[198:201], v178 offset:15360
	s_waitcnt lgkmcnt(3)
	v_mfma_f32_16x16x32_bf16 v[62:65], v[222:225], v[170:173], v[62:65]
	v_mfma_f32_16x16x32_bf16 v[58:61], v[226:229], v[170:173], v[58:61]
	v_mfma_f32_16x16x32_bf16 v[54:57], v[230:233], v[170:173], v[54:57]
	v_mfma_f32_16x16x32_bf16 v[50:53], v[234:237], v[170:173], v[50:53]
	s_waitcnt lgkmcnt(2)
	v_mfma_f32_16x16x32_bf16 v[46:49], v[222:225], v[174:177], v[46:49]
	v_mfma_f32_16x16x32_bf16 v[42:45], v[226:229], v[174:177], v[42:45]
	v_mfma_f32_16x16x32_bf16 v[38:41], v[230:233], v[174:177], v[38:41]
	v_mfma_f32_16x16x32_bf16 v[34:37], v[234:237], v[174:177], v[34:37]
	s_waitcnt lgkmcnt(0)
	s_waitcnt vmcnt(0)
	s_add_u32 s14, s14, 0x80
	s_addc_u32 s15, s15, 0
	s_add_i32 s2, s2, 0x10000
	s_cmpk_eq_i32 s14, 0x780
	s_waitcnt vmcnt(0)
	s_barrier
	s_cselect_b32 s100, 1, 0
	s_and_b32 s3, s2, 0x10000
	v_or_b32_e32 v150, s3, v149
	v_add_u32_e32 v169, v150, v148
	v_or_b32_e32 v150, s3, v146
	v_add_u32_e32 v178, v150, v147
	ds_read_b128 v[150:153], v169 offset:32768
	ds_read_b128 v[154:157], v169 offset:34816
	ds_read_b128 v[158:161], v169 offset:36864
	ds_read_b128 v[162:165], v169 offset:38912
	ds_read_b128 v[170:173], v178
	ds_read_b128 v[174:177], v178 offset:2048
	s_add_u32 s4, s4, 0x80
	s_addc_u32 s5, s5, 0
	s_add_u32 s6, s6, 0x80
	s_addc_u32 s7, s7, 0
	s_cmp_eq_u32 s100, 1
	s_cbranch_scc1 .Lkl_710_s9
	v_readfirstlane_b32 s10, v142
	s_xor_b32 s8, s3, 0x10000
	s_nop 0
	s_lshl_b32 s10, s10, 2
	s_add_i32 s10, s10, s8
	s_add_i32 m0, s10, 0x0
	s_add_u32 s8, s4, 0xe500080
	s_addc_u32 s9, s5, 0x0
	global_load_lds_dwordx4 v238, s[8:9]
.Lkl_710_s9:
	v_mfma_f32_16x16x32_bf16 v[30:33], v[222:225], v[192:195], v[30:33]
	v_mfma_f32_16x16x32_bf16 v[26:29], v[226:229], v[192:195], v[26:29]
	v_mfma_f32_16x16x32_bf16 v[22:25], v[230:233], v[192:195], v[22:25]
	v_mfma_f32_16x16x32_bf16 v[18:21], v[234:237], v[192:195], v[18:21]
	ds_read_b128 v[192:195], v178 offset:4096
	s_cmp_eq_u32 s100, 1
	s_cbranch_scc1 .Lkl_710_s10
	s_add_u32 s8, s4, 0xe4ffcc0
	s_addc_u32 s9, s5, 0x0
	global_load_lds_dwordx4 v238, s[8:9] offset:1024
.Lkl_710_s10:
	v_mfma_f32_16x16x32_bf16 v[14:17], v[222:225], v[198:201], v[14:17]
	v_mfma_f32_16x16x32_bf16 v[10:13], v[226:229], v[198:201], v[10:13]
	v_mfma_f32_16x16x32_bf16 v[6:9], v[230:233], v[198:201], v[6:9]
	v_mfma_f32_16x16x32_bf16 v[2:5], v[234:237], v[198:201], v[2:5]
	ds_read_b128 v[198:201], v178 offset:6144
	s_cmp_eq_u32 s100, 1
	s_cbranch_scc1 .Lkl_710_s11
	s_add_u32 s8, s4, 0xe507880
	s_addc_u32 s9, s5, 0x0
	global_load_lds_dwordx4 v238, s[8:9] offset:2048

; #define WAIT_V0() asm volatile("s_waitcnt vmcnt(0)" ::: "memory")
; template <int EPI>
; DEVI void gemm_tile(const u16* __restrict__ Ab, long lda, const u16* __restrict__ Bb, long ldb, int K, const EpiArgs& e,
;                     bool have0 = false, const u16* __restrict__ nA = nullptr, const u16* __restrict__ nB = nullptr) {
;     ...
;   f32x4 acc[8][4];
; #pragma unroll
;   for (int m = 0; m < 8; ++m)
; #pragma unroll
;     for (int n = 0; n < 4; ++n) acc[m][n] = f32x4{0.f, 0.f, 0.f, 0.f};
;   const int nt = K / BK;
;   if (!have0) GLDS_STAGE(0, 0);
;   WAIT_V0(); __syncthreads();
;   for (int t = 0; t < nt; ++t) {
;     const int cur = t & 1;
;     if (t + 1 < nt) GLDS_STAGE(cur ^ 1, t + 1);
;     else if (nA) {
; #pragma unroll
;       for (int i = 0; i < GL; ++i) {
;         __builtin_amdgcn_global_load_lds((const unsigned*)(nA + (long)i * 64 * lda + toffA), (unsigned*)(g_shm + wid * 1024 + i * 8192), 16, 0, 0);
;         __builtin_amdgcn_global_load_lds((const unsigned*)(nB + (long)i * 64 * ldb + toffB), (unsigned*)(g_shm + TILE_B + wid * 1024 + i * 8192), 16, 0, 0);
;       }
;     }
;     const char* sb = g_shm + cur * STAGE_B;
; #pragma unroll
;     for (int ks = 0; ks < 2; ++ks) {
;       bf16x8 Bf[4];
; #pragma unroll
;       for (int n = 0; n < 4; ++n) Bf[n] = *(const bf16x8*)(sb + b_base + n * 2048 + ks * 1024);
; #pragma unroll
;       for (int mh = 0; mh < 2; ++mh) {
;         bf16x8 At[4];
; #pragma unroll
;         for (int m = 0; m < 4; ++m) At[m] = *(const bf16x8*)(sb + a_base + (mh * 4 + m) * 2048 + ks * 1024);
.LBB0_795:
	s_and_b32 s3, s2, 0x10000
	v_or_b32_e32 v150, s3, v149
	v_add_u32_e32 v169, v150, v148
	v_or_b32_e32 v150, s3, v146
	v_add_u32_e32 v178, v150, v147
	ds_read_b128 v[150:153], v169 offset:32768
	ds_read_b128 v[154:157], v169 offset:34816
	ds_read_b128 v[158:161], v169 offset:36864
	ds_read_b128 v[162:165], v169 offset:38912
	ds_read_b128 v[170:173], v178
	ds_read_b128 v[174:177], v178 offset:2048
	ds_read_b128 v[192:195], v178 offset:4096
	ds_read_b128 v[198:201], v178 offset:6144
	v_writelane_b32 v240, s4, 0
	v_writelane_b32 v240, s5, 1
	v_writelane_b32 v240, s6, 2
	v_writelane_b32 v240, s7, 3
	v_writelane_b32 v240, s8, 4
	v_writelane_b32 v240, s9, 5
	v_writelane_b32 v240, s10, 6
	v_readfirstlane_b32 s4, v132
	v_readfirstlane_b32 s5, v133
	s_nop 1
	v_subrev_u32_e32 v238, s4, v132
	s_add_u32 s4, s4, s14
	s_addc_u32 s5, s5, s15
	v_readfirstlane_b32 s6, v134
	v_readfirstlane_b32 s7, v135
	s_nop 1
	v_subrev_u32_e32 v239, s6, v134
	s_add_u32 s6, s6, s14
	s_addc_u32 s7, s7, s15
	v_readfirstlane_b32 s8, v142
	s_nop 3
	s_lshr_b32 s8, s8, 10
	s_lshr_b32 s9, s8, 1
	s_lshl_b32 s9, s9, 4
	s_lshl_b32 s10, s8, 5
	s_sub_u32 s10, s10, s9
	s_mul_i32 s9, s10, 0x800
	s_add_u32 s4, s4, s9
	s_addc_u32 s5, s5, 0
	s_and_b32 s9, s8, 1
	s_lshl_b32 s9, s9, 6
	s_sub_u32 s4, s4, s9
	s_subb_u32 s5, s5, 0
	v_readfirstlane_b32 s8, v142
	s_nop 3
	s_lshr_b32 s8, s8, 10
	s_lshr_b32 s9, s8, 1
	s_lshl_b32 s9, s9, 4
	s_lshl_b32 s10, s8, 5
	s_sub_u32 s10, s10, s9
	s_mul_i32 s9, s10, 0x800
	s_add_u32 s6, s6, s9
	s_addc_u32 s7, s7, 0
	s_and_b32 s9, s8, 1
	s_lshl_b32 s9, s9, 6
	s_sub_u32 s6, s6, s9
	s_subb_u32 s7, s7, 0
	v_readfirstlane_b32 s10, v142
	s_xor_b32 s8, s3, 0x10000
	s_nop 0
	s_lshl_b32 s10, s10, 2
	s_add_i32 s10, s10, s8
	s_add_i32 m0, s10, 0x0
	s_add_u32 s8, s4, 0x12500080
	s_addc_u32 s9, s5, 0x0
	global_load_lds_dwordx4 v238, s[8:9]
.Lkl_795_s1:
	s_add_u32 s8, s4, 0x124ffcc0
	s_addc_u32 s9, s5, 0x0
	global_load_lds_dwordx4 v238, s[8:9] offset:1024
.Lkl_795_s2:
	s_add_u32 s8, s4, 0x12507880
	s_addc_u32 s9, s5, 0x0
	global_load_lds_dwordx4 v238, s[8:9] offset:2048
.Lkl_795_s3:
.Lkl_795:
	s_waitcnt lgkmcnt(3)
	v_mfma_f32_16x16x32_bf16 v[126:129], v[150:153], v[170:173], v[126:129]
	v_mfma_f32_16x16x32_bf16 v[122:125], v[154:157], v[170:173], v[122:125]
	v_mfma_f32_16x16x32_bf16 v[118:121], v[158:161], v[170:173], v[118:121]
	v_mfma_f32_16x16x32_bf16 v[114:117], v[162:165], v[170:173], v[114:117]
	ds_read_b128 v[170:173], v178 offset:8192
	ds_read_b128 v[222:225], v169 offset:33792
	s_add_u32 s8, s4, 0x125074c0
	s_addc_u32 s9, s5, 0x0
	global_load_lds_dwordx4 v238, s[8:9] offset:3072

; #define WAIT_V0() asm volatile("s_waitcnt vmcnt(0)" ::: "memory")
; #define SBAR() __builtin_amdgcn_sched_barrier(0)
; template <int EPI>
; DEVI void gemm_tile(const u16* __restrict__ Ab, long lda, const u16* __restrict__ Bb, long ldb, int K, const EpiArgs& e,
;                     bool have0 = false, const u16* __restrict__ nA = nullptr, const u16* __restrict__ nB = nullptr) {
;     ...
;     const char* sb = g_shm + cur * STAGE_B;
; #pragma unroll
;     for (int ks = 0; ks < 2; ++ks) {
;       bf16x8 Bf[4];
; #pragma unroll
;       for (int n = 0; n < 4; ++n) Bf[n] = *(const bf16x8*)(sb + b_base + n * 2048 + ks * 1024);
; #pragma unroll
;       for (int mh = 0; mh < 2; ++mh) {
;         bf16x8 At[4];
; #pragma unroll
;         for (int m = 0; m < 4; ++m) At[m] = *(const bf16x8*)(sb + a_base + (mh * 4 + m) * 2048 + ks * 1024);
;         __builtin_amdgcn_s_setprio(1);
; #pragma unroll
;         for (int m = 0; m < 4; ++m)
; #pragma unroll
;           for (int n = 0; n < 4; ++n) acc[mh * 4 + m][n] = __builtin_amdgcn_mfma_f32_16x16x32_bf16(Bf[n], At[m], acc[mh * 4 + m][n], 0, 0, 0);
;         __builtin_amdgcn_s_setprio(0);
;       }
;       SBAR();
;     }
;     if (t + 1 < nt) { WAIT_V0(); __syncthreads(); }
.Lkl_795_s8:
	s_waitcnt lgkmcnt(6)
	v_mfma_f32_16x16x32_bf16 v[46:49], v[150:153], v[174:177], v[46:49]
	v_mfma_f32_16x16x32_bf16 v[42:45], v[154:157], v[174:177], v[42:45]
	v_mfma_f32_16x16x32_bf16 v[38:41], v[158:161], v[174:177], v[38:41]
	v_mfma_f32_16x16x32_bf16 v[34:37], v[162:165], v[174:177], v[34:37]
	ds_read_b128 v[174:177], v178 offset:3072
	s_waitcnt lgkmcnt(5)
	v_mfma_f32_16x16x32_bf16 v[30:33], v[150:153], v[192:195], v[30:33]
	v_mfma_f32_16x16x32_bf16 v[26:29], v[154:157], v[192:195], v[26:29]
	v_mfma_f32_16x16x32_bf16 v[22:25], v[158:161], v[192:195], v[22:25]
	v_mfma_f32_16x16x32_bf16 v[18:21], v[162:165], v[192:195], v[18:21]
	ds_read_b128 v[192:195], v178 offset:5120
	s_waitcnt lgkmcnt(4)
	v_mfma_f32_16x16x32_bf16 v[14:17], v[150:153], v[198:201], v[14:17]
	v_mfma_f32_16x16x32_bf16 v[10:13], v[154:157], v[198:201], v[10:13]
	v_mfma_f32_16x16x32_bf16 v[6:9], v[158:161], v[198:201], v[6:9]
	v_mfma_f32_16x16x32_bf16 v[2:5], v[162:165], v[198:201], v[2:5]
	ds_read_b128 v[198:201], v178 offset:7168
	s_waitcnt lgkmcnt(3)
	v_mfma_f32_16x16x32_bf16 v[126:129], v[222:225], v[170:173], v[126:129]
	v_mfma_f32_16x16x32_bf16 v[122:125], v[226:229], v[170:173], v[122:125]
	v_mfma_f32_16x16x32_bf16 v[118:121], v[230:233], v[170:173], v[118:121]
	v_mfma_f32_16x16x32_bf16 v[114:117], v[234:237], v[170:173], v[114:117]
	ds_read_b128 v[170:173], v178 offset:9216
	s_waitcnt lgkmcnt(3)
	v_mfma_f32_16x16x32_bf16 v[110:113], v[222:225], v[174:177], v[110:113]
	v_mfma_f32_16x16x32_bf16 v[106:109], v[226:229], v[174:177], v[106:109]
	v_mfma_f32_16x16x32_bf16 v[102:105], v[230:233], v[174:177], v[102:105]
	v_mfma_f32_16x16x32_bf16 v[98:101], v[234:237], v[174:177], v[98:101]
	ds_read_b128 v[174:177], v178 offset:11264
	s_waitcnt lgkmcnt(3)
	v_mfma_f32_16x16x32_bf16 v[94:97], v[222:225], v[192:195], v[94:97]
	v_mfma_f32_16x16x32_bf16 v[90:93], v[226:229], v[192:195], v[90:93]
	v_mfma_f32_16x16x32_bf16 v[86:89], v[230:233], v[192:195], v[86:89]
	v_mfma_f32_16x16x32_bf16 v[82:85], v[234:237], v[192:195], v[82:85]
	ds_read_b128 v[192:195], v178 offset:13312
	s_waitcnt lgkmcnt(3)
	v_mfma_f32_16x16x32_bf16 v[78:81], v[222:225], v[198:201], v[78:81]
	v_mfma_f32_16x16x32_bf16 v[74:77], v[226:229], v[198:201], v[74:77]
	v_mfma_f32_16x16x32_bf16 v[70:73], v[230:233], v[198:201], v[70:73]
	v_mfma_f32_16x16x32_bf16 v[66:69], v[234:237], v[198:201], v[66:69]
	ds_read_b128 v[198:201], v178 offset:15360
	s_waitcnt lgkmcnt(3)
	v_mfma_f32_16x16x32_bf16 v[62:65], v[222:225], v[170:173], v[62:65]
	v_mfma_f32_16x16x32_bf16 v[58:61], v[226:229], v[170:173], v[58:61]
	v_mfma_f32_16x16x32_bf16 v[54:57], v[230:233], v[170:173], v[54:57]
	v_mfma_f32_16x16x32_bf16 v[50:53], v[234:237], v[170:173], v[50:53]
	s_waitcnt lgkmcnt(2)
	v_mfma_f32_16x16x32_bf16 v[46:49], v[222:225], v[174:177], v[46:49]
	v_mfma_f32_16x16x32_bf16 v[42:45], v[226:229], v[174:177], v[42:45]
	v_mfma_f32_16x16x32_bf16 v[38:41], v[230:233], v[174:177], v[38:41]
	v_mfma_f32_16x16x32_bf16 v[34:37], v[234:237], v[174:177], v[34:37]
	s_waitcnt lgkmcnt(0)
	s_waitcnt vmcnt(0)
	s_add_u32 s14, s14, 0x80
	s_addc_u32 s15, s15, 0
	s_add_i32 s2, s2, 0x10000
	s_cmpk_eq_i32 s14, 0x780
	s_waitcnt vmcnt(0)
	s_barrier
	s_cselect_b32 s100, 1, 0
	s_and_b32 s3, s2, 0x10000
	v_or_b32_e32 v150, s3, v149
	v_add_u32_e32 v169, v150, v148
	v_or_b32_e32 v150, s3, v146
	v_add_u32_e32 v178, v150, v147
	ds_read_b128 v[150:153], v169 offset:32768
	ds_read_b128 v[154:157], v169 offset:34816
	ds_read_b128 v[158:161], v169 offset:36864
	ds_read_b128 v[162:165], v169 offset:38912
	ds_read_b128 v[170:173], v178
	ds_read_b128 v[174:177], v178 offset:2048
	s_add_u32 s4, s4, 0x80
	s_addc_u32 s5, s5, 0
	s_add_u32 s6, s6, 0x80
	s_addc_u32 s7, s7, 0
	s_cmp_eq_u32 s100, 1
	s_cbranch_scc1 .Lkl_795_s9
	v_readfirstlane_b32 s10, v142
	s_xor_b32 s8, s3, 0x10000
	s_nop 0
	s_lshl_b32 s10, s10, 2
	s_add_i32 s10, s10, s8
	s_add_i32 m0, s10, 0x0
	s_add_u32 s8, s4, 0x12500080
	s_addc_u32 s9, s5, 0x0
	global_load_lds_dwordx4 v238, s[8:9]
.Lkl_795_s9:
	v_mfma_f32_16x16x32_bf16 v[30:33], v[222:225], v[192:195], v[30:33]
	v_mfma_f32_16x16x32_bf16 v[26:29], v[226:229], v[192:195], v[26:29]
	v_mfma_f32_16x16x32_bf16 v[22:25], v[230:233], v[192:195], v[22:25]
	v_mfma_f32_16x16x32_bf16 v[18:21], v[234:237], v[192:195], v[18:21]
	ds_read_b128 v[192:195], v178 offset:4096
	s_cmp_eq_u32 s100, 1
	s_cbranch_scc1 .Lkl_795_s10
	s_add_u32 s8, s4, 0x124ffcc0
	s_addc_u32 s9, s5, 0x0
	global_load_lds_dwordx4 v238, s[8:9] offset:1024
.Lkl_795_s10:
	v_mfma_f32_16x16x32_bf16 v[14:17], v[222:225], v[198:201], v[14:17]
	v_mfma_f32_16x16x32_bf16 v[10:13], v[226:229], v[198:201], v[10:13]
	v_mfma_f32_16x16x32_bf16 v[6:9], v[230:233], v[198:201], v[6:9]
	v_mfma_f32_16x16x32_bf16 v[2:5], v[234:237], v[198:201], v[2:5]
	ds_read_b128 v[198:201], v178 offset:6144
	s_cmp_eq_u32 s100, 1
	s_cbranch_scc1 .Lkl_795_s11
	s_add_u32 s8, s4, 0x12507880
	s_addc_u32 s9, s5, 0x0
	global_load_lds_dwordx4 v238, s[8:9] offset:2048

; #define WAIT_V0() asm volatile("s_waitcnt vmcnt(0)" ::: "memory")
; #define SBAR() __builtin_amdgcn_sched_barrier(0)
; template <int EPI>
; DEVI void gemm_tile(const u16* __restrict__ Ab, long lda, const u16* __restrict__ Bb, long ldb, int K, const EpiArgs& e,
;                     bool have0 = false, const u16* __restrict__ nA = nullptr, const u16* __restrict__ nB = nullptr) {
;     ...
;   f32x4 acc[8][4];
; #pragma unroll
;   for (int m = 0; m < 8; ++m)
; #pragma unroll
;     for (int n = 0; n < 4; ++n) acc[m][n] = f32x4{0.f, 0.f, 0.f, 0.f};
;   const int nt = K / BK;
;   if (!have0) GLDS_STAGE(0, 0);
;   WAIT_V0(); __syncthreads();
;   for (int t = 0; t < nt; ++t) {
;     const int cur = t & 1;
;     if (t + 1 < nt) GLDS_STAGE(cur ^ 1, t + 1);
;     else if (nA) {
; #pragma unroll
;       for (int i = 0; i < GL; ++i) {
;         __builtin_amdgcn_global_load_lds((const unsigned*)(nA + (long)i * 64 * lda + toffA), (unsigned*)(g_shm + wid * 1024 + i * 8192), 16, 0, 0);
;         __builtin_amdgcn_global_load_lds((const unsigned*)(nB + (long)i * 64 * ldb + toffB), (unsigned*)(g_shm + TILE_B + wid * 1024 + i * 8192), 16, 0, 0);
;       }
;     }
;     const char* sb = g_shm + cur * STAGE_B;
; #pragma unroll
;     for (int ks = 0; ks < 2; ++ks) {
;       bf16x8 Bf[4];
; #pragma unroll
;       for (int n = 0; n < 4; ++n) Bf[n] = *(const bf16x8*)(sb + b_base + n * 2048 + ks * 1024);
; #pragma unroll
;       for (int mh = 0; mh < 2; ++mh) {
;         bf16x8 At[4];
; #pragma unroll
;         for (int m = 0; m < 4; ++m) At[m] = *(const bf16x8*)(sb + a_base + (mh * 4 + m) * 2048 + ks * 1024);
;         __builtin_amdgcn_s_setprio(1);
; #pragma unroll
;         for (int m = 0; m < 4; ++m)
; #pragma unroll
;           for (int n = 0; n < 4; ++n) acc[mh * 4 + m][n] = __builtin_amdgcn_mfma_f32_16x16x32_bf16(Bf[n], At[m], acc[mh * 4 + m][n], 0, 0, 0);
;         __builtin_amdgcn_s_setprio(0);
;       }
;       SBAR();
;     }
;     if (t + 1 < nt) { WAIT_V0(); __syncthreads(); }
.LBB0_1085:
	s_and_b32 s3, s2, 0x10000
	v_or_b32_e32 v150, s3, v149
	v_add_u32_e32 v169, v150, v148
	v_or_b32_e32 v150, s3, v146
	v_add_u32_e32 v178, v150, v147
	ds_read_b128 v[150:153], v169 offset:32768
	ds_read_b128 v[154:157], v169 offset:34816
	ds_read_b128 v[158:161], v169 offset:36864
	ds_read_b128 v[162:165], v169 offset:38912
	ds_read_b128 v[170:173], v178
	ds_read_b128 v[174:177], v178 offset:2048
	ds_read_b128 v[192:195], v178 offset:4096
	ds_read_b128 v[198:201], v178 offset:6144
	v_writelane_b32 v240, s4, 0
	v_writelane_b32 v240, s5, 1
	v_writelane_b32 v240, s6, 2
	v_writelane_b32 v240, s7, 3
	v_writelane_b32 v240, s8, 4
	v_writelane_b32 v240, s9, 5
	v_writelane_b32 v240, s10, 6
	v_readfirstlane_b32 s4, v134
	v_readfirstlane_b32 s5, v135
	s_nop 1
	v_subrev_u32_e32 v238, s4, v134
	s_add_u32 s4, s4, s16
	s_addc_u32 s5, s5, s17
	v_readfirstlane_b32 s6, v136
	v_readfirstlane_b32 s7, v137
	s_nop 1
	v_subrev_u32_e32 v239, s6, v136
	s_add_u32 s6, s6, s16
	s_addc_u32 s7, s7, s17
	v_readfirstlane_b32 s8, v142
	s_nop 3
	s_lshr_b32 s8, s8, 10
	s_lshr_b32 s9, s8, 1
	s_lshl_b32 s9, s9, 4
	s_lshl_b32 s10, s8, 5
	s_sub_u32 s10, s10, s9
	s_mul_i32 s9, s10, 0x800
	s_add_u32 s4, s4, s9
	s_addc_u32 s5, s5, 0
	s_and_b32 s9, s8, 1
	s_lshl_b32 s9, s9, 6
	s_sub_u32 s4, s4, s9
	s_subb_u32 s5, s5, 0
	v_readfirstlane_b32 s8, v142
	s_nop 3
	s_lshr_b32 s8, s8, 10
	s_lshr_b32 s9, s8, 1
	s_lshl_b32 s9, s9, 4
	s_lshl_b32 s10, s8, 5
	s_sub_u32 s10, s10, s9
	s_mul_i32 s9, s10, 0x800
	s_add_u32 s6, s6, s9
	s_addc_u32 s7, s7, 0
	s_and_b32 s9, s8, 1
	s_lshl_b32 s9, s9, 6
	s_sub_u32 s6, s6, s9
	s_subb_u32 s7, s7, 0
	v_readfirstlane_b32 s10, v142
	s_xor_b32 s8, s3, 0x10000
	s_nop 0
	s_lshl_b32 s10, s10, 2
	s_add_i32 s10, s10, s8
	s_add_i32 m0, s10, 0x0
	s_add_u32 s8, s4, s22
	s_addc_u32 s9, s5, s23
	global_load_lds_dwordx4 v238, s[8:9]
.Lkl_1085_s1:
	s_add_u32 s8, s4, s22
	s_addc_u32 s9, s5, s23
	s_add_u32 s8, s8, 0xfffffc40
	s_addc_u32 s9, s9, 0xffffffff
	global_load_lds_dwordx4 v238, s[8:9] offset:1024
.Lkl_1085_s2:
	s_add_u32 s8, s4, s22
	s_addc_u32 s9, s5, s23
	s_add_u32 s8, s8, 0x7800
	s_addc_u32 s9, s9, 0x0
	global_load_lds_dwordx4 v238, s[8:9] offset:2048
.Lkl_1085_s3:
.Lkl_1085:
	s_waitcnt lgkmcnt(3)
	v_mfma_f32_16x16x32_bf16 v[126:129], v[150:153], v[170:173], v[126:129]
	v_mfma_f32_16x16x32_bf16 v[122:125], v[154:157], v[170:173], v[122:125]
	v_mfma_f32_16x16x32_bf16 v[118:121], v[158:161], v[170:173], v[118:121]
	v_mfma_f32_16x16x32_bf16 v[114:117], v[162:165], v[170:173], v[114:117]
	ds_read_b128 v[170:173], v178 offset:8192
	ds_read_b128 v[222:225], v169 offset:33792
	s_add_u32 s8, s4, s22
	s_addc_u32 s9, s5, s23
	s_add_u32 s8, s8, 0x7440
	s_addc_u32 s9, s9, 0x0
	global_load_lds_dwordx4 v238, s[8:9] offset:3072
.Lkl_1085_s4:
	s_waitcnt lgkmcnt(4)
	v_mfma_f32_16x16x32_bf16 v[110:113], v[150:153], v[174:177], v[110:113]
	v_mfma_f32_16x16x32_bf16 v[106:109], v[154:157], v[174:177], v[106:109]
	v_mfma_f32_16x16x32_bf16 v[102:105], v[158:161], v[174:177], v[102:105]
	v_mfma_f32_16x16x32_bf16 v[98:101], v[162:165], v[174:177], v[98:101]
	ds_read_b128 v[174:177], v178 offset:10240
	ds_read_b128 v[226:229], v169 offset:35840
	s_add_i32 m0, s10, 0x8000
	s_add_u32 s8, s6, 0x97c0080
	s_addc_u32 s9, s7, 0x0
	global_load_lds_dwordx4 v239, s[8:9]
.Lkl_1085_s5:
	s_waitcnt lgkmcnt(5)
	v_mfma_f32_16x16x32_bf16 v[94:97], v[150:153], v[192:195], v[94:97]
	v_mfma_f32_16x16x32_bf16 v[90:93], v[154:157], v[192:195], v[90:93]
	v_mfma_f32_16x16x32_bf16 v[86:89], v[158:161], v[192:195], v[86:89]
	v_mfma_f32_16x16x32_bf16 v[82:85], v[162:165], v[192:195], v[82:85]
	ds_read_b128 v[192:195], v178 offset:12288
	ds_read_b128 v[230:233], v169 offset:37888
	s_add_u32 s8, s6, 0x97bfcc0
	s_addc_u32 s9, s7, 0x0
	global_load_lds_dwordx4 v239, s[8:9] offset:1024
.Lkl_1085_s6:
	s_waitcnt lgkmcnt(6)
	v_mfma_f32_16x16x32_bf16 v[78:81], v[150:153], v[198:201], v[78:81]
	v_mfma_f32_16x16x32_bf16 v[74:77], v[154:157], v[198:201], v[74:77]
	v_mfma_f32_16x16x32_bf16 v[70:73], v[158:161], v[198:201], v[70:73]
	v_mfma_f32_16x16x32_bf16 v[66:69], v[162:165], v[198:201], v[66:69]
	ds_read_b128 v[198:201], v178 offset:14336
	ds_read_b128 v[234:237], v169 offset:39936
	s_add_u32 s8, s6, 0x97c7880
	s_addc_u32 s9, s7, 0x0
	global_load_lds_dwordx4 v239, s[8:9] offset:2048
.Lkl_1085_s7:
	s_waitcnt lgkmcnt(7)
	v_mfma_f32_16x16x32_bf16 v[62:65], v[150:153], v[170:173], v[62:65]
	v_mfma_f32_16x16x32_bf16 v[58:61], v[154:157], v[170:173], v[58:61]
	v_mfma_f32_16x16x32_bf16 v[54:57], v[158:161], v[170:173], v[54:57]
	v_mfma_f32_16x16x32_bf16 v[50:53], v[162:165], v[170:173], v[50:53]
	ds_read_b128 v[170:173], v178 offset:1024
	s_add_u32 s8, s6, 0x97c74c0
	s_addc_u32 s9, s7, 0x0
	global_load_lds_dwordx4 v239, s[8:9] offset:3072
; #define WAIT_V0() asm volatile("s_waitcnt vmcnt(0)" ::: "memory")
; #define SBAR() __builtin_amdgcn_sched_barrier(0)
; template <int EPI>
; DEVI void gemm_tile(const u16* __restrict__ Ab, long lda, const u16* __restrict__ Bb, long ldb, int K, const EpiArgs& e,
;                     bool have0 = false, const u16* __restrict__ nA = nullptr, const u16* __restrict__ nB = nullptr) {
;     ...
;     const char* sb = g_shm + cur * STAGE_B;
; #pragma unroll
;     for (int ks = 0; ks < 2; ++ks) {
;       bf16x8 Bf[4];
; #pragma unroll
;       for (int n = 0; n < 4; ++n) Bf[n] = *(const bf16x8*)(sb + b_base + n * 2048 + ks * 1024);
; #pragma unroll
;       for (int mh = 0; mh < 2; ++mh) {
;         bf16x8 At[4];
; #pragma unroll
;         for (int m = 0; m < 4; ++m) At[m] = *(const bf16x8*)(sb + a_base + (mh * 4 + m) * 2048 + ks * 1024);
;         __builtin_amdgcn_s_setprio(1);
; #pragma unroll
;         for (int m = 0; m < 4; ++m)
; #pragma unroll
;           for (int n = 0; n < 4; ++n) acc[mh * 4 + m][n] = __builtin_amdgcn_mfma_f32_16x16x32_bf16(Bf[n], At[m], acc[mh * 4 + m][n], 0, 0, 0);
;         __builtin_amdgcn_s_setprio(0);
;       }
;       SBAR();
;     }
;     if (t + 1 < nt) { WAIT_V0(); __syncthreads(); }
.Lkl_1085_s8:
	s_waitcnt lgkmcnt(6)
	v_mfma_f32_16x16x32_bf16 v[46:49], v[150:153], v[174:177], v[46:49]
	v_mfma_f32_16x16x32_bf16 v[42:45], v[154:157], v[174:177], v[42:45]
	v_mfma_f32_16x16x32_bf16 v[38:41], v[158:161], v[174:177], v[38:41]
	v_mfma_f32_16x16x32_bf16 v[34:37], v[162:165], v[174:177], v[34:37]
	ds_read_b128 v[174:177], v178 offset:3072
	s_waitcnt lgkmcnt(5)
	v_mfma_f32_16x16x32_bf16 v[30:33], v[150:153], v[192:195], v[30:33]
	v_mfma_f32_16x16x32_bf16 v[26:29], v[154:157], v[192:195], v[26:29]
	v_mfma_f32_16x16x32_bf16 v[22:25], v[158:161], v[192:195], v[22:25]
	v_mfma_f32_16x16x32_bf16 v[18:21], v[162:165], v[192:195], v[18:21]
	ds_read_b128 v[192:195], v178 offset:5120
	s_waitcnt lgkmcnt(4)
	v_mfma_f32_16x16x32_bf16 v[14:17], v[150:153], v[198:201], v[14:17]
	v_mfma_f32_16x16x32_bf16 v[10:13], v[154:157], v[198:201], v[10:13]
	v_mfma_f32_16x16x32_bf16 v[6:9], v[158:161], v[198:201], v[6:9]
	v_mfma_f32_16x16x32_bf16 v[2:5], v[162:165], v[198:201], v[2:5]
	ds_read_b128 v[198:201], v178 offset:7168
	s_waitcnt lgkmcnt(3)
	v_mfma_f32_16x16x32_bf16 v[126:129], v[222:225], v[170:173], v[126:129]
	v_mfma_f32_16x16x32_bf16 v[122:125], v[226:229], v[170:173], v[122:125]
	v_mfma_f32_16x16x32_bf16 v[118:121], v[230:233], v[170:173], v[118:121]
	v_mfma_f32_16x16x32_bf16 v[114:117], v[234:237], v[170:173], v[114:117]
	ds_read_b128 v[170:173], v178 offset:9216
	s_waitcnt lgkmcnt(3)
	v_mfma_f32_16x16x32_bf16 v[110:113], v[222:225], v[174:177], v[110:113]
	v_mfma_f32_16x16x32_bf16 v[106:109], v[226:229], v[174:177], v[106:109]
	v_mfma_f32_16x16x32_bf16 v[102:105], v[230:233], v[174:177], v[102:105]
	v_mfma_f32_16x16x32_bf16 v[98:101], v[234:237], v[174:177], v[98:101]
	ds_read_b128 v[174:177], v178 offset:11264
	s_waitcnt lgkmcnt(3)
	v_mfma_f32_16x16x32_bf16 v[94:97], v[222:225], v[192:195], v[94:97]
	v_mfma_f32_16x16x32_bf16 v[90:93], v[226:229], v[192:195], v[90:93]
	v_mfma_f32_16x16x32_bf16 v[86:89], v[230:233], v[192:195], v[86:89]
	v_mfma_f32_16x16x32_bf16 v[82:85], v[234:237], v[192:195], v[82:85]
	ds_read_b128 v[192:195], v178 offset:13312
	s_waitcnt lgkmcnt(3)
	v_mfma_f32_16x16x32_bf16 v[78:81], v[222:225], v[198:201], v[78:81]
	v_mfma_f32_16x16x32_bf16 v[74:77], v[226:229], v[198:201], v[74:77]
	v_mfma_f32_16x16x32_bf16 v[70:73], v[230:233], v[198:201], v[70:73]
	v_mfma_f32_16x16x32_bf16 v[66:69], v[234:237], v[198:201], v[66:69]
	ds_read_b128 v[198:201], v178 offset:15360
	s_waitcnt lgkmcnt(3)
	v_mfma_f32_16x16x32_bf16 v[62:65], v[222:225], v[170:173], v[62:65]
	v_mfma_f32_16x16x32_bf16 v[58:61], v[226:229], v[170:173], v[58:61]
	v_mfma_f32_16x16x32_bf16 v[54:57], v[230:233], v[170:173], v[54:57]
	v_mfma_f32_16x16x32_bf16 v[50:53], v[234:237], v[170:173], v[50:53]
	s_waitcnt lgkmcnt(2)
	v_mfma_f32_16x16x32_bf16 v[46:49], v[222:225], v[174:177], v[46:49]
	v_mfma_f32_16x16x32_bf16 v[42:45], v[226:229], v[174:177], v[42:45]
	v_mfma_f32_16x16x32_bf16 v[38:41], v[230:233], v[174:177], v[38:41]
	v_mfma_f32_16x16x32_bf16 v[34:37], v[234:237], v[174:177], v[34:37]
	s_waitcnt lgkmcnt(0)
	s_waitcnt vmcnt(0)
	s_add_u32 s16, s16, 0x80
	s_addc_u32 s17, s17, 0
	s_add_i32 s2, s2, 0x10000
	s_cmpk_eq_i32 s16, 0x780
	s_waitcnt vmcnt(0)
	s_barrier
	s_cselect_b32 s100, 1, 0
	s_and_b32 s3, s2, 0x10000
	v_or_b32_e32 v150, s3, v149
	v_add_u32_e32 v169, v150, v148
	v_or_b32_e32 v150, s3, v146
	v_add_u32_e32 v178, v150, v147
	ds_read_b128 v[150:153], v169 offset:32768
	ds_read_b128 v[154:157], v169 offset:34816
	ds_read_b128 v[158:161], v169 offset:36864
	ds_read_b128 v[162:165], v169 offset:38912
	ds_read_b128 v[170:173], v178
	ds_read_b128 v[174:177], v178 offset:2048
	s_add_u32 s4, s4, 0x80
	s_addc_u32 s5, s5, 0
	s_add_u32 s6, s6, 0x80
	s_addc_u32 s7, s7, 0
	s_cmp_eq_u32 s100, 1
	s_cbranch_scc1 .Lkl_1085_s9
	v_readfirstlane_b32 s10, v142
	s_xor_b32 s8, s3, 0x10000
	s_nop 0
	s_lshl_b32 s10, s10, 2
	s_add_i32 s10, s10, s8
	s_add_i32 m0, s10, 0x0
	s_add_u32 s8, s4, s22
	s_addc_u32 s9, s5, s23
	global_load_lds_dwordx4 v238, s[8:9]
.Lkl_1085_s9:
	v_mfma_f32_16x16x32_bf16 v[30:33], v[222:225], v[192:195], v[30:33]
	v_mfma_f32_16x16x32_bf16 v[26:29], v[226:229], v[192:195], v[26:29]
	v_mfma_f32_16x16x32_bf16 v[22:25], v[230:233], v[192:195], v[22:25]
	v_mfma_f32_16x16x32_bf16 v[18:21], v[234:237], v[192:195], v[18:21]
	ds_read_b128 v[192:195], v178 offset:4096
	s_cmp_eq_u32 s100, 1
	s_cbranch_scc1 .Lkl_1085_s10
	s_add_u32 s8, s4, s22
	s_addc_u32 s9, s5, s23
	s_add_u32 s8, s8, 0xfffffc40
	s_addc_u32 s9, s9, 0xffffffff
	global_load_lds_dwordx4 v238, s[8:9] offset:1024
.Lkl_1085_s10:
	v_mfma_f32_16x16x32_bf16 v[14:17], v[222:225], v[198:201], v[14:17]
	v_mfma_f32_16x16x32_bf16 v[10:13], v[226:229], v[198:201], v[10:13]
	v_mfma_f32_16x16x32_bf16 v[6:9], v[230:233], v[198:201], v[6:9]
	v_mfma_f32_16x16x32_bf16 v[2:5], v[234:237], v[198:201], v[2:5]
	ds_read_b128 v[198:201], v178 offset:6144
	s_cmp_eq_u32 s100, 1
	s_cbranch_scc1 .Lkl_1085_s11
	s_add_u32 s8, s4, s22
	s_addc_u32 s9, s5, s23
	s_add_u32 s8, s8, 0x7800
	s_addc_u32 s9, s9, 0x0
	global_load_lds_dwordx4 v238, s[8:9] offset:2048

; #define WAIT_V0() asm volatile("s_waitcnt vmcnt(0)" ::: "memory")
; template <int EPI>
; DEVI void gemm_tile(const u16* __restrict__ Ab, long lda, const u16* __restrict__ Bb, long ldb, int K, const EpiArgs& e,
;                     bool have0 = false, const u16* __restrict__ nA = nullptr, const u16* __restrict__ nB = nullptr) {
;     ...
;   f32x4 acc[8][4];
; #pragma unroll
;   for (int m = 0; m < 8; ++m)
; #pragma unroll
;     for (int n = 0; n < 4; ++n) acc[m][n] = f32x4{0.f, 0.f, 0.f, 0.f};
;   const int nt = K / BK;
;   if (!have0) GLDS_STAGE(0, 0);
;   WAIT_V0(); __syncthreads();
;   for (int t = 0; t < nt; ++t) {
;     const int cur = t & 1;
;     if (t + 1 < nt) GLDS_STAGE(cur ^ 1, t + 1);
;     else if (nA) {
; #pragma unroll
;       for (int i = 0; i < GL; ++i) {
;         __builtin_amdgcn_global_load_lds((const unsigned*)(nA + (long)i * 64 * lda + toffA), (unsigned*)(g_shm + wid * 1024 + i * 8192), 16, 0, 0);
;         __builtin_amdgcn_global_load_lds((const unsigned*)(nB + (long)i * 64 * ldb + toffB), (unsigned*)(g_shm + TILE_B + wid * 1024 + i * 8192), 16, 0, 0);
;       }
;     }
;     const char* sb = g_shm + cur * STAGE_B;
; #pragma unroll
;     for (int ks = 0; ks < 2; ++ks) {
;       bf16x8 Bf[4];
; #pragma unroll
;       for (int n = 0; n < 4; ++n) Bf[n] = *(const bf16x8*)(sb + b_base + n * 2048 + ks * 1024);
; #pragma unroll
;       for (int mh = 0; mh < 2; ++mh) {
;         bf16x8 At[4];
; #pragma unroll
;         for (int m = 0; m < 4; ++m) At[m] = *(const bf16x8*)(sb + a_base + (mh * 4 + m) * 2048 + ks * 1024);
.LBB0_1121:
	s_and_b32 s3, s2, 0x10000
	v_or_b32_e32 v150, s3, v149
	v_add_u32_e32 v169, v150, v148
	v_or_b32_e32 v150, s3, v146
	v_add_u32_e32 v178, v150, v147
	ds_read_b128 v[150:153], v169 offset:32768
	ds_read_b128 v[154:157], v169 offset:34816
	ds_read_b128 v[158:161], v169 offset:36864
	ds_read_b128 v[162:165], v169 offset:38912
	ds_read_b128 v[170:173], v178
	ds_read_b128 v[174:177], v178 offset:2048
	ds_read_b128 v[214:217], v178 offset:4096
	ds_read_b128 v[218:221], v178 offset:6144
	v_writelane_b32 v240, s4, 0
	v_writelane_b32 v240, s5, 1
	v_writelane_b32 v240, s6, 2
	v_writelane_b32 v240, s7, 3
	v_writelane_b32 v240, s8, 4
	v_writelane_b32 v240, s9, 5
	v_writelane_b32 v240, s10, 6
	v_readfirstlane_b32 s4, v132
	v_readfirstlane_b32 s5, v133
	s_nop 1
	v_subrev_u32_e32 v238, s4, v132
	s_add_u32 s4, s4, s16
	s_addc_u32 s5, s5, s17
	v_readfirstlane_b32 s6, v134
	v_readfirstlane_b32 s7, v135
	s_nop 1
	v_subrev_u32_e32 v239, s6, v134
	s_add_u32 s6, s6, s16
	s_addc_u32 s7, s7, s17
	v_readfirstlane_b32 s8, v142
	s_nop 3
	s_lshr_b32 s8, s8, 10
	s_lshr_b32 s9, s8, 1
	s_lshl_b32 s9, s9, 4
	s_lshl_b32 s10, s8, 5
	s_sub_u32 s10, s10, s9
	s_mul_i32 s9, s10, 0x800
	s_add_u32 s4, s4, s9
	s_addc_u32 s5, s5, 0
	s_and_b32 s9, s8, 1
	s_lshl_b32 s9, s9, 6
	s_sub_u32 s4, s4, s9
	s_subb_u32 s5, s5, 0
	v_readfirstlane_b32 s8, v142
	s_nop 3
	s_lshr_b32 s8, s8, 10
	s_lshr_b32 s9, s8, 1
	s_lshl_b32 s9, s9, 4
	s_lshl_b32 s10, s8, 5
	s_sub_u32 s10, s10, s9
	s_mul_i32 s9, s10, 0x800
	s_add_u32 s6, s6, s9
	s_addc_u32 s7, s7, 0
	s_and_b32 s9, s8, 1
	s_lshl_b32 s9, s9, 6
	s_sub_u32 s6, s6, s9
	s_subb_u32 s7, s7, 0
	v_readfirstlane_b32 s10, v142
	s_xor_b32 s8, s3, 0x10000
	s_nop 0
	s_lshl_b32 s10, s10, 2
	s_add_i32 s10, s10, s8
	s_add_i32 m0, s10, 0x0
	s_add_u32 s8, s4, s30
	s_addc_u32 s9, s5, s31
	global_load_lds_dwordx4 v238, s[8:9]

; #define WAIT_V0() asm volatile("s_waitcnt vmcnt(0)" ::: "memory")
; template <int EPI>
; DEVI void gemm_tile(const u16* __restrict__ Ab, long lda, const u16* __restrict__ Bb, long ldb, int K, const EpiArgs& e,
;                     bool have0 = false, const u16* __restrict__ nA = nullptr, const u16* __restrict__ nB = nullptr) {
;     ...
;   f32x4 acc[8][4];
; #pragma unroll
;   for (int m = 0; m < 8; ++m)
; #pragma unroll
;     for (int n = 0; n < 4; ++n) acc[m][n] = f32x4{0.f, 0.f, 0.f, 0.f};
;   const int nt = K / BK;
;   if (!have0) GLDS_STAGE(0, 0);
;   WAIT_V0(); __syncthreads();
;   for (int t = 0; t < nt; ++t) {
;     const int cur = t & 1;
;     if (t + 1 < nt) GLDS_STAGE(cur ^ 1, t + 1);
;     else if (nA) {
; #pragma unroll
;       for (int i = 0; i < GL; ++i) {
;         __builtin_amdgcn_global_load_lds((const unsigned*)(nA + (long)i * 64 * lda + toffA), (unsigned*)(g_shm + wid * 1024 + i * 8192), 16, 0, 0);
;         __builtin_amdgcn_global_load_lds((const unsigned*)(nB + (long)i * 64 * ldb + toffB), (unsigned*)(g_shm + TILE_B + wid * 1024 + i * 8192), 16, 0, 0);
;       }
;     }
;     const char* sb = g_shm + cur * STAGE_B;
; #pragma unroll
;     for (int ks = 0; ks < 2; ++ks) {
;       bf16x8 Bf[4];
; #pragma unroll
;       for (int n = 0; n < 4; ++n) Bf[n] = *(const bf16x8*)(sb + b_base + n * 2048 + ks * 1024);
; #pragma unroll
;       for (int mh = 0; mh < 2; ++mh) {
;         bf16x8 At[4];
; #pragma unroll
;         for (int m = 0; m < 4; ++m) At[m] = *(const bf16x8*)(sb + a_base + (mh * 4 + m) * 2048 + ks * 1024);
;         __builtin_amdgcn_s_setprio(1);
; #pragma unroll
;         for (int m = 0; m < 4; ++m)
; #pragma unroll
;           for (int n = 0; n < 4; ++n) acc[mh * 4 + m][n] = __builtin_amdgcn_mfma_f32_16x16x32_bf16(Bf[n], At[m], acc[mh * 4 + m][n], 0, 0, 0);
.Lkl_1121_s4:
	s_waitcnt lgkmcnt(4)
	v_mfma_f32_16x16x32_bf16 v[110:113], v[150:153], v[174:177], v[110:113]
	v_mfma_f32_16x16x32_bf16 v[106:109], v[154:157], v[174:177], v[106:109]
	v_mfma_f32_16x16x32_bf16 v[102:105], v[158:161], v[174:177], v[102:105]
	v_mfma_f32_16x16x32_bf16 v[98:101], v[162:165], v[174:177], v[98:101]
	ds_read_b128 v[174:177], v178 offset:10240
	ds_read_b128 v[226:229], v169 offset:35840
	s_add_i32 m0, s10, 0x8000
	s_add_u32 s8, s6, 0x8400080
	s_addc_u32 s9, s7, 0x0
	global_load_lds_dwordx4 v239, s[8:9]
.Lkl_1121_s5:
	s_waitcnt lgkmcnt(5)
	v_mfma_f32_16x16x32_bf16 v[94:97], v[150:153], v[214:217], v[94:97]
	v_mfma_f32_16x16x32_bf16 v[90:93], v[154:157], v[214:217], v[90:93]
	v_mfma_f32_16x16x32_bf16 v[86:89], v[158:161], v[214:217], v[86:89]
	v_mfma_f32_16x16x32_bf16 v[82:85], v[162:165], v[214:217], v[82:85]
	ds_read_b128 v[214:217], v178 offset:12288
	ds_read_b128 v[230:233], v169 offset:37888
	s_add_u32 s8, s6, 0x83ffcc0
	s_addc_u32 s9, s7, 0x0
	global_load_lds_dwordx4 v239, s[8:9] offset:1024
.Lkl_1121_s6:
	s_waitcnt lgkmcnt(6)
	v_mfma_f32_16x16x32_bf16 v[78:81], v[150:153], v[218:221], v[78:81]
	v_mfma_f32_16x16x32_bf16 v[74:77], v[154:157], v[218:221], v[74:77]
	v_mfma_f32_16x16x32_bf16 v[70:73], v[158:161], v[218:221], v[70:73]
	v_mfma_f32_16x16x32_bf16 v[66:69], v[162:165], v[218:221], v[66:69]
	ds_read_b128 v[218:221], v178 offset:14336
	ds_read_b128 v[234:237], v169 offset:39936
	s_add_u32 s8, s6, 0x8407880
	s_addc_u32 s9, s7, 0x0
	global_load_lds_dwordx4 v239, s[8:9] offset:2048
.Lkl_1121_s7:
	s_waitcnt lgkmcnt(7)
	v_mfma_f32_16x16x32_bf16 v[62:65], v[150:153], v[170:173], v[62:65]
	v_mfma_f32_16x16x32_bf16 v[58:61], v[154:157], v[170:173], v[58:61]
	v_mfma_f32_16x16x32_bf16 v[54:57], v[158:161], v[170:173], v[54:57]
	v_mfma_f32_16x16x32_bf16 v[50:53], v[162:165], v[170:173], v[50:53]
	ds_read_b128 v[170:173], v178 offset:1024
	s_add_u32 s8, s6, 0x84074c0
	s_addc_u32 s9, s7, 0x0
	global_load_lds_dwordx4 v239, s[8:9] offset:3072
; #define WAIT_V0() asm volatile("s_waitcnt vmcnt(0)" ::: "memory")
; #define SBAR() __builtin_amdgcn_sched_barrier(0)
; template <int EPI>
; DEVI void gemm_tile(const u16* __restrict__ Ab, long lda, const u16* __restrict__ Bb, long ldb, int K, const EpiArgs& e,
;                     bool have0 = false, const u16* __restrict__ nA = nullptr, const u16* __restrict__ nB = nullptr) {
;     ...
;     const char* sb = g_shm + cur * STAGE_B;
; #pragma unroll
;     for (int ks = 0; ks < 2; ++ks) {
;       bf16x8 Bf[4];
; #pragma unroll
;       for (int n = 0; n < 4; ++n) Bf[n] = *(const bf16x8*)(sb + b_base + n * 2048 + ks * 1024);
; #pragma unroll
;       for (int mh = 0; mh < 2; ++mh) {
;         bf16x8 At[4];
; #pragma unroll
;         for (int m = 0; m < 4; ++m) At[m] = *(const bf16x8*)(sb + a_base + (mh * 4 + m) * 2048 + ks * 1024);
;         __builtin_amdgcn_s_setprio(1);
; #pragma unroll
;         for (int m = 0; m < 4; ++m)
; #pragma unroll
;           for (int n = 0; n < 4; ++n) acc[mh * 4 + m][n] = __builtin_amdgcn_mfma_f32_16x16x32_bf16(Bf[n], At[m], acc[mh * 4 + m][n], 0, 0, 0);
;         __builtin_amdgcn_s_setprio(0);
;       }
;       SBAR();
;     }
;     if (t + 1 < nt) { WAIT_V0(); __syncthreads(); }
.Lkl_1121_s8:
	s_waitcnt lgkmcnt(6)
	v_mfma_f32_16x16x32_bf16 v[46:49], v[150:153], v[174:177], v[46:49]
	v_mfma_f32_16x16x32_bf16 v[42:45], v[154:157], v[174:177], v[42:45]
	v_mfma_f32_16x16x32_bf16 v[38:41], v[158:161], v[174:177], v[38:41]
	v_mfma_f32_16x16x32_bf16 v[34:37], v[162:165], v[174:177], v[34:37]
	ds_read_b128 v[174:177], v178 offset:3072
	s_waitcnt lgkmcnt(5)
	v_mfma_f32_16x16x32_bf16 v[30:33], v[150:153], v[214:217], v[30:33]
	v_mfma_f32_16x16x32_bf16 v[26:29], v[154:157], v[214:217], v[26:29]
	v_mfma_f32_16x16x32_bf16 v[22:25], v[158:161], v[214:217], v[22:25]
	v_mfma_f32_16x16x32_bf16 v[18:21], v[162:165], v[214:217], v[18:21]
	ds_read_b128 v[214:217], v178 offset:5120
	s_waitcnt lgkmcnt(4)
	v_mfma_f32_16x16x32_bf16 v[14:17], v[150:153], v[218:221], v[14:17]
	v_mfma_f32_16x16x32_bf16 v[10:13], v[154:157], v[218:221], v[10:13]
	v_mfma_f32_16x16x32_bf16 v[6:9], v[158:161], v[218:221], v[6:9]
	v_mfma_f32_16x16x32_bf16 v[2:5], v[162:165], v[218:221], v[2:5]
	ds_read_b128 v[218:221], v178 offset:7168
	s_waitcnt lgkmcnt(3)
	v_mfma_f32_16x16x32_bf16 v[126:129], v[222:225], v[170:173], v[126:129]
	v_mfma_f32_16x16x32_bf16 v[122:125], v[226:229], v[170:173], v[122:125]
	v_mfma_f32_16x16x32_bf16 v[118:121], v[230:233], v[170:173], v[118:121]
	v_mfma_f32_16x16x32_bf16 v[114:117], v[234:237], v[170:173], v[114:117]
	ds_read_b128 v[170:173], v178 offset:9216
	s_waitcnt lgkmcnt(3)
	v_mfma_f32_16x16x32_bf16 v[110:113], v[222:225], v[174:177], v[110:113]
	v_mfma_f32_16x16x32_bf16 v[106:109], v[226:229], v[174:177], v[106:109]
	v_mfma_f32_16x16x32_bf16 v[102:105], v[230:233], v[174:177], v[102:105]
	v_mfma_f32_16x16x32_bf16 v[98:101], v[234:237], v[174:177], v[98:101]
	ds_read_b128 v[174:177], v178 offset:11264
	s_waitcnt lgkmcnt(3)
	v_mfma_f32_16x16x32_bf16 v[94:97], v[222:225], v[214:217], v[94:97]
	v_mfma_f32_16x16x32_bf16 v[90:93], v[226:229], v[214:217], v[90:93]
	v_mfma_f32_16x16x32_bf16 v[86:89], v[230:233], v[214:217], v[86:89]
	v_mfma_f32_16x16x32_bf16 v[82:85], v[234:237], v[214:217], v[82:85]
	ds_read_b128 v[214:217], v178 offset:13312
	s_waitcnt lgkmcnt(3)
	v_mfma_f32_16x16x32_bf16 v[78:81], v[222:225], v[218:221], v[78:81]
	v_mfma_f32_16x16x32_bf16 v[74:77], v[226:229], v[218:221], v[74:77]
	v_mfma_f32_16x16x32_bf16 v[70:73], v[230:233], v[218:221], v[70:73]
	v_mfma_f32_16x16x32_bf16 v[66:69], v[234:237], v[218:221], v[66:69]
	ds_read_b128 v[218:221], v178 offset:15360
	s_waitcnt lgkmcnt(3)
	v_mfma_f32_16x16x32_bf16 v[62:65], v[222:225], v[170:173], v[62:65]
	v_mfma_f32_16x16x32_bf16 v[58:61], v[226:229], v[170:173], v[58:61]
	v_mfma_f32_16x16x32_bf16 v[54:57], v[230:233], v[170:173], v[54:57]
	v_mfma_f32_16x16x32_bf16 v[50:53], v[234:237], v[170:173], v[50:53]
	s_waitcnt lgkmcnt(2)
	v_mfma_f32_16x16x32_bf16 v[46:49], v[222:225], v[174:177], v[46:49]
	v_mfma_f32_16x16x32_bf16 v[42:45], v[226:229], v[174:177], v[42:45]
	v_mfma_f32_16x16x32_bf16 v[38:41], v[230:233], v[174:177], v[38:41]
	v_mfma_f32_16x16x32_bf16 v[34:37], v[234:237], v[174:177], v[34:37]
	s_waitcnt lgkmcnt(0)
	s_waitcnt vmcnt(0)
	s_add_u32 s16, s16, 0x80
	s_addc_u32 s17, s17, 0
	s_add_i32 s2, s2, 0x10000
	s_cmpk_eq_i32 s16, 0x780
	s_waitcnt vmcnt(0)
	s_barrier
	s_cselect_b32 s100, 1, 0
	s_and_b32 s3, s2, 0x10000
	v_or_b32_e32 v150, s3, v149
	v_add_u32_e32 v169, v150, v148
	v_or_b32_e32 v150, s3, v146
	v_add_u32_e32 v178, v150, v147
	ds_read_b128 v[150:153], v169 offset:32768
	ds_read_b128 v[154:157], v169 offset:34816
	ds_read_b128 v[158:161], v169 offset:36864
	ds_read_b128 v[162:165], v169 offset:38912
	ds_read_b128 v[170:173], v178
	ds_read_b128 v[174:177], v178 offset:2048
	s_add_u32 s4, s4, 0x80
	s_addc_u32 s5, s5, 0
	s_add_u32 s6, s6, 0x80
	s_addc_u32 s7, s7, 0
	s_cmp_eq_u32 s100, 1
	s_cbranch_scc1 .Lkl_1121_s9
	v_readfirstlane_b32 s10, v142
	s_xor_b32 s8, s3, 0x10000
	s_nop 0
	s_lshl_b32 s10, s10, 2
	s_add_i32 s10, s10, s8
	s_add_i32 m0, s10, 0x0
	s_add_u32 s8, s4, s30
	s_addc_u32 s9, s5, s31
	global_load_lds_dwordx4 v238, s[8:9]
.Lkl_1121_s9:
	v_mfma_f32_16x16x32_bf16 v[30:33], v[222:225], v[214:217], v[30:33]
	v_mfma_f32_16x16x32_bf16 v[26:29], v[226:229], v[214:217], v[26:29]
	v_mfma_f32_16x16x32_bf16 v[22:25], v[230:233], v[214:217], v[22:25]
	v_mfma_f32_16x16x32_bf16 v[18:21], v[234:237], v[214:217], v[18:21]
	ds_read_b128 v[214:217], v178 offset:4096
	s_cmp_eq_u32 s100, 1
	s_cbranch_scc1 .Lkl_1121_s10
	s_add_u32 s8, s4, s30
	s_addc_u32 s9, s5, s31
	s_add_u32 s8, s8, 0xfffffc40
	s_addc_u32 s9, s9, 0xffffffff
	global_load_lds_dwordx4 v238, s[8:9] offset:1024
.Lkl_1121_s10:
	v_mfma_f32_16x16x32_bf16 v[14:17], v[222:225], v[218:221], v[14:17]
	v_mfma_f32_16x16x32_bf16 v[10:13], v[226:229], v[218:221], v[10:13]
	v_mfma_f32_16x16x32_bf16 v[6:9], v[230:233], v[218:221], v[6:9]
	v_mfma_f32_16x16x32_bf16 v[2:5], v[234:237], v[218:221], v[2:5]
	ds_read_b128 v[218:221], v178 offset:6144
	s_cmp_eq_u32 s100, 1
	s_cbranch_scc1 .Lkl_1121_s11
	s_add_u32 s8, s4, s30
	s_addc_u32 s9, s5, s31
	s_add_u32 s8, s8, 0x7800
	s_addc_u32 s9, s9, 0x0
	global_load_lds_dwordx4 v238, s[8:9] offset:2048

; #define WAIT_V0() asm volatile("s_waitcnt vmcnt(0)" ::: "memory")
; #define SBAR() __builtin_amdgcn_sched_barrier(0)
; template <int EPI>
; DEVI void gemm_tile(const u16* __restrict__ Ab, long lda, const u16* __restrict__ Bb, long ldb, int K, const EpiArgs& e,
;                     bool have0 = false, const u16* __restrict__ nA = nullptr, const u16* __restrict__ nB = nullptr) {
;     ...
;   f32x4 acc[8][4];
; #pragma unroll
;   for (int m = 0; m < 8; ++m)
; #pragma unroll
;     for (int n = 0; n < 4; ++n) acc[m][n] = f32x4{0.f, 0.f, 0.f, 0.f};
;   const int nt = K / BK;
;   if (!have0) GLDS_STAGE(0, 0);
;   WAIT_V0(); __syncthreads();
;   for (int t = 0; t < nt; ++t) {
;     const int cur = t & 1;
;     if (t + 1 < nt) GLDS_STAGE(cur ^ 1, t + 1);
;     else if (nA) {
; #pragma unroll
;       for (int i = 0; i < GL; ++i) {
;         __builtin_amdgcn_global_load_lds((const unsigned*)(nA + (long)i * 64 * lda + toffA), (unsigned*)(g_shm + wid * 1024 + i * 8192), 16, 0, 0);
;         __builtin_amdgcn_global_load_lds((const unsigned*)(nB + (long)i * 64 * ldb + toffB), (unsigned*)(g_shm + TILE_B + wid * 1024 + i * 8192), 16, 0, 0);
;       }
;     }
;     const char* sb = g_shm + cur * STAGE_B;
; #pragma unroll
;     for (int ks = 0; ks < 2; ++ks) {
;       bf16x8 Bf[4];
; #pragma unroll
;       for (int n = 0; n < 4; ++n) Bf[n] = *(const bf16x8*)(sb + b_base + n * 2048 + ks * 1024);
; #pragma unroll
;       for (int mh = 0; mh < 2; ++mh) {
;         bf16x8 At[4];
; #pragma unroll
;         for (int m = 0; m < 4; ++m) At[m] = *(const bf16x8*)(sb + a_base + (mh * 4 + m) * 2048 + ks * 1024);
;         __builtin_amdgcn_s_setprio(1);
; #pragma unroll
;         for (int m = 0; m < 4; ++m)
; #pragma unroll
;           for (int n = 0; n < 4; ++n) acc[mh * 4 + m][n] = __builtin_amdgcn_mfma_f32_16x16x32_bf16(Bf[n], At[m], acc[mh * 4 + m][n], 0, 0, 0);
;         __builtin_amdgcn_s_setprio(0);
;       }
;       SBAR();
;     }
;     if (t + 1 < nt) { WAIT_V0(); __syncthreads(); }
.LBB0_1302:
	s_and_b32 s3, s2, 0x10000
	v_or_b32_e32 v150, s3, v149
	v_add_u32_e32 v169, v150, v148
	v_or_b32_e32 v150, s3, v146
	v_add_u32_e32 v178, v150, v147
	ds_read_b128 v[150:153], v169 offset:32768
	ds_read_b128 v[154:157], v169 offset:34816
	ds_read_b128 v[158:161], v169 offset:36864
	ds_read_b128 v[162:165], v169 offset:38912
	ds_read_b128 v[170:173], v178
	ds_read_b128 v[174:177], v178 offset:2048
	ds_read_b128 v[214:217], v178 offset:4096
	ds_read_b128 v[218:221], v178 offset:6144
	v_writelane_b32 v240, s4, 0
	v_writelane_b32 v240, s5, 1
	v_writelane_b32 v240, s6, 2
	v_writelane_b32 v240, s7, 3
	v_writelane_b32 v240, s8, 4
	v_writelane_b32 v240, s9, 5
	v_writelane_b32 v240, s10, 6
	v_readfirstlane_b32 s4, v134
	v_readfirstlane_b32 s5, v135
	s_nop 1
	v_subrev_u32_e32 v238, s4, v134
	s_add_u32 s4, s4, s16
	s_addc_u32 s5, s5, s17
	v_readfirstlane_b32 s6, v136
	v_readfirstlane_b32 s7, v137
	s_nop 1
	v_subrev_u32_e32 v239, s6, v136
	s_add_u32 s6, s6, s16
	s_addc_u32 s7, s7, s17
	v_readfirstlane_b32 s8, v142
	s_nop 3
	s_lshr_b32 s8, s8, 10
	s_lshr_b32 s9, s8, 1
	s_lshl_b32 s9, s9, 4
	s_lshl_b32 s10, s8, 5
	s_sub_u32 s10, s10, s9
	s_mul_i32 s9, s10, 0x800
	s_add_u32 s4, s4, s9
	s_addc_u32 s5, s5, 0
	s_and_b32 s9, s8, 1
	s_lshl_b32 s9, s9, 6
	s_sub_u32 s4, s4, s9
	s_subb_u32 s5, s5, 0
	v_readfirstlane_b32 s8, v142
	s_nop 3
	s_lshr_b32 s8, s8, 10
	s_lshr_b32 s9, s8, 1
	s_lshl_b32 s9, s9, 4
	s_lshl_b32 s10, s8, 5
	s_sub_u32 s10, s10, s9
	s_mul_i32 s9, s10, 0x800
	s_add_u32 s6, s6, s9
	s_addc_u32 s7, s7, 0
	s_and_b32 s9, s8, 1
	s_lshl_b32 s9, s9, 6
	s_sub_u32 s6, s6, s9
	s_subb_u32 s7, s7, 0
	v_readfirstlane_b32 s10, v142
	s_xor_b32 s8, s3, 0x10000
	s_nop 0
	s_lshl_b32 s10, s10, 2
	s_add_i32 s10, s10, s8
	s_add_i32 m0, s10, 0x0
	s_add_u32 s8, s4, 0x1f500080
	s_addc_u32 s9, s5, 0x0
	global_load_lds_dwordx4 v238, s[8:9]
.Lkl_1302_s1:
	s_add_u32 s8, s4, 0x1f4ffcc0
	s_addc_u32 s9, s5, 0x0
	global_load_lds_dwordx4 v238, s[8:9] offset:1024
.Lkl_1302_s2:
	s_add_u32 s8, s4, 0x1f507880
	s_addc_u32 s9, s5, 0x0
	global_load_lds_dwordx4 v238, s[8:9] offset:2048
.Lkl_1302_s3:
.Lkl_1302:
	s_waitcnt lgkmcnt(3)
	v_mfma_f32_16x16x32_bf16 v[126:129], v[150:153], v[170:173], v[126:129]
	v_mfma_f32_16x16x32_bf16 v[122:125], v[154:157], v[170:173], v[122:125]
	v_mfma_f32_16x16x32_bf16 v[118:121], v[158:161], v[170:173], v[118:121]
	v_mfma_f32_16x16x32_bf16 v[114:117], v[162:165], v[170:173], v[114:117]
	ds_read_b128 v[170:173], v178 offset:8192
	ds_read_b128 v[222:225], v169 offset:33792
	s_add_u32 s8, s4, 0x1f5074c0
	s_addc_u32 s9, s5, 0x0
	global_load_lds_dwordx4 v238, s[8:9] offset:3072
.Lkl_1302_s4:
	s_waitcnt lgkmcnt(4)
	v_mfma_f32_16x16x32_bf16 v[110:113], v[150:153], v[174:177], v[110:113]
	v_mfma_f32_16x16x32_bf16 v[106:109], v[154:157], v[174:177], v[106:109]
	v_mfma_f32_16x16x32_bf16 v[102:105], v[158:161], v[174:177], v[102:105]
	v_mfma_f32_16x16x32_bf16 v[98:101], v[162:165], v[174:177], v[98:101]
	ds_read_b128 v[174:177], v178 offset:10240
	ds_read_b128 v[226:229], v169 offset:35840
	s_add_i32 m0, s10, 0x8000
	s_add_u32 s8, s6, 0x87a0080
	s_addc_u32 s9, s7, 0x0
	global_load_lds_dwordx4 v239, s[8:9]
.Lkl_1302_s5:
	s_waitcnt lgkmcnt(5)
	v_mfma_f32_16x16x32_bf16 v[94:97], v[150:153], v[214:217], v[94:97]
	v_mfma_f32_16x16x32_bf16 v[90:93], v[154:157], v[214:217], v[90:93]
	v_mfma_f32_16x16x32_bf16 v[86:89], v[158:161], v[214:217], v[86:89]
	v_mfma_f32_16x16x32_bf16 v[82:85], v[162:165], v[214:217], v[82:85]
	ds_read_b128 v[214:217], v178 offset:12288
	ds_read_b128 v[230:233], v169 offset:37888
	s_add_u32 s8, s6, 0x879fcc0
	s_addc_u32 s9, s7, 0x0
	global_load_lds_dwordx4 v239, s[8:9] offset:1024
.Lkl_1302_s6:
	s_waitcnt lgkmcnt(6)
	v_mfma_f32_16x16x32_bf16 v[78:81], v[150:153], v[218:221], v[78:81]
	v_mfma_f32_16x16x32_bf16 v[74:77], v[154:157], v[218:221], v[74:77]
	v_mfma_f32_16x16x32_bf16 v[70:73], v[158:161], v[218:221], v[70:73]
	v_mfma_f32_16x16x32_bf16 v[66:69], v[162:165], v[218:221], v[66:69]
	ds_read_b128 v[218:221], v178 offset:14336
	ds_read_b128 v[234:237], v169 offset:39936
	s_add_u32 s8, s6, 0x87a7880
	s_addc_u32 s9, s7, 0x0
	global_load_lds_dwordx4 v239, s[8:9] offset:2048
.Lkl_1302_s7:
	s_waitcnt lgkmcnt(7)
	v_mfma_f32_16x16x32_bf16 v[62:65], v[150:153], v[170:173], v[62:65]
	v_mfma_f32_16x16x32_bf16 v[58:61], v[154:157], v[170:173], v[58:61]
	v_mfma_f32_16x16x32_bf16 v[54:57], v[158:161], v[170:173], v[54:57]
	v_mfma_f32_16x16x32_bf16 v[50:53], v[162:165], v[170:173], v[50:53]
	ds_read_b128 v[170:173], v178 offset:1024
	s_add_u32 s8, s6, 0x87a74c0
	s_addc_u32 s9, s7, 0x0
	global_load_lds_dwordx4 v239, s[8:9] offset:3072
; #define WAIT_V0() asm volatile("s_waitcnt vmcnt(0)" ::: "memory")
; #define SBAR() __builtin_amdgcn_sched_barrier(0)
; template <int EPI>
; DEVI void gemm_tile(const u16* __restrict__ Ab, long lda, const u16* __restrict__ Bb, long ldb, int K, const EpiArgs& e,
;                     bool have0 = false, const u16* __restrict__ nA = nullptr, const u16* __restrict__ nB = nullptr) {
;     ...
;     const char* sb = g_shm + cur * STAGE_B;
; #pragma unroll
;     for (int ks = 0; ks < 2; ++ks) {
;       bf16x8 Bf[4];
; #pragma unroll
;       for (int n = 0; n < 4; ++n) Bf[n] = *(const bf16x8*)(sb + b_base + n * 2048 + ks * 1024);
; #pragma unroll
;       for (int mh = 0; mh < 2; ++mh) {
;         bf16x8 At[4];
; #pragma unroll
;         for (int m = 0; m < 4; ++m) At[m] = *(const bf16x8*)(sb + a_base + (mh * 4 + m) * 2048 + ks * 1024);
;         __builtin_amdgcn_s_setprio(1);
; #pragma unroll
;         for (int m = 0; m < 4; ++m)
; #pragma unroll
;           for (int n = 0; n < 4; ++n) acc[mh * 4 + m][n] = __builtin_amdgcn_mfma_f32_16x16x32_bf16(Bf[n], At[m], acc[mh * 4 + m][n], 0, 0, 0);
;         __builtin_amdgcn_s_setprio(0);
;       }
;       SBAR();
;     }
;     if (t + 1 < nt) { WAIT_V0(); __syncthreads(); }
.Lkl_1302_s8:
	s_waitcnt lgkmcnt(6)
	v_mfma_f32_16x16x32_bf16 v[46:49], v[150:153], v[174:177], v[46:49]
	v_mfma_f32_16x16x32_bf16 v[42:45], v[154:157], v[174:177], v[42:45]
	v_mfma_f32_16x16x32_bf16 v[38:41], v[158:161], v[174:177], v[38:41]
	v_mfma_f32_16x16x32_bf16 v[34:37], v[162:165], v[174:177], v[34:37]
	ds_read_b128 v[174:177], v178 offset:3072
	s_waitcnt lgkmcnt(5)
	v_mfma_f32_16x16x32_bf16 v[30:33], v[150:153], v[214:217], v[30:33]
	v_mfma_f32_16x16x32_bf16 v[26:29], v[154:157], v[214:217], v[26:29]
	v_mfma_f32_16x16x32_bf16 v[22:25], v[158:161], v[214:217], v[22:25]
	v_mfma_f32_16x16x32_bf16 v[18:21], v[162:165], v[214:217], v[18:21]
	ds_read_b128 v[214:217], v178 offset:5120
	s_waitcnt lgkmcnt(4)
	v_mfma_f32_16x16x32_bf16 v[14:17], v[150:153], v[218:221], v[14:17]
	v_mfma_f32_16x16x32_bf16 v[10:13], v[154:157], v[218:221], v[10:13]
	v_mfma_f32_16x16x32_bf16 v[6:9], v[158:161], v[218:221], v[6:9]
	v_mfma_f32_16x16x32_bf16 v[2:5], v[162:165], v[218:221], v[2:5]
	ds_read_b128 v[218:221], v178 offset:7168
	s_waitcnt lgkmcnt(3)
	v_mfma_f32_16x16x32_bf16 v[126:129], v[222:225], v[170:173], v[126:129]
	v_mfma_f32_16x16x32_bf16 v[122:125], v[226:229], v[170:173], v[122:125]
	v_mfma_f32_16x16x32_bf16 v[118:121], v[230:233], v[170:173], v[118:121]
	v_mfma_f32_16x16x32_bf16 v[114:117], v[234:237], v[170:173], v[114:117]
	ds_read_b128 v[170:173], v178 offset:9216
	s_waitcnt lgkmcnt(3)
	v_mfma_f32_16x16x32_bf16 v[110:113], v[222:225], v[174:177], v[110:113]
	v_mfma_f32_16x16x32_bf16 v[106:109], v[226:229], v[174:177], v[106:109]
	v_mfma_f32_16x16x32_bf16 v[102:105], v[230:233], v[174:177], v[102:105]
	v_mfma_f32_16x16x32_bf16 v[98:101], v[234:237], v[174:177], v[98:101]
	ds_read_b128 v[174:177], v178 offset:11264
	s_waitcnt lgkmcnt(3)
	v_mfma_f32_16x16x32_bf16 v[94:97], v[222:225], v[214:217], v[94:97]
	v_mfma_f32_16x16x32_bf16 v[90:93], v[226:229], v[214:217], v[90:93]
	v_mfma_f32_16x16x32_bf16 v[86:89], v[230:233], v[214:217], v[86:89]
	v_mfma_f32_16x16x32_bf16 v[82:85], v[234:237], v[214:217], v[82:85]
	ds_read_b128 v[214:217], v178 offset:13312
	s_waitcnt lgkmcnt(3)
	v_mfma_f32_16x16x32_bf16 v[78:81], v[222:225], v[218:221], v[78:81]
	v_mfma_f32_16x16x32_bf16 v[74:77], v[226:229], v[218:221], v[74:77]
	v_mfma_f32_16x16x32_bf16 v[70:73], v[230:233], v[218:221], v[70:73]
	v_mfma_f32_16x16x32_bf16 v[66:69], v[234:237], v[218:221], v[66:69]
	ds_read_b128 v[218:221], v178 offset:15360
	s_waitcnt lgkmcnt(3)
	v_mfma_f32_16x16x32_bf16 v[62:65], v[222:225], v[170:173], v[62:65]
	v_mfma_f32_16x16x32_bf16 v[58:61], v[226:229], v[170:173], v[58:61]
	v_mfma_f32_16x16x32_bf16 v[54:57], v[230:233], v[170:173], v[54:57]
	v_mfma_f32_16x16x32_bf16 v[50:53], v[234:237], v[170:173], v[50:53]
	s_waitcnt lgkmcnt(2)
	v_mfma_f32_16x16x32_bf16 v[46:49], v[222:225], v[174:177], v[46:49]
	v_mfma_f32_16x16x32_bf16 v[42:45], v[226:229], v[174:177], v[42:45]
	v_mfma_f32_16x16x32_bf16 v[38:41], v[230:233], v[174:177], v[38:41]
	v_mfma_f32_16x16x32_bf16 v[34:37], v[234:237], v[174:177], v[34:37]
	s_waitcnt lgkmcnt(0)
	s_waitcnt vmcnt(0)
	s_add_u32 s16, s16, 0x80
	s_addc_u32 s17, s17, 0
	s_add_i32 s2, s2, 0x10000
	s_cmpk_eq_i32 s16, 0x780
	s_waitcnt vmcnt(0)
	s_barrier
	s_cselect_b32 s100, 1, 0
	s_and_b32 s3, s2, 0x10000
	v_or_b32_e32 v150, s3, v149
	v_add_u32_e32 v169, v150, v148
	v_or_b32_e32 v150, s3, v146
	v_add_u32_e32 v178, v150, v147
	ds_read_b128 v[150:153], v169 offset:32768
	ds_read_b128 v[154:157], v169 offset:34816
	ds_read_b128 v[158:161], v169 offset:36864
	ds_read_b128 v[162:165], v169 offset:38912
	ds_read_b128 v[170:173], v178
	ds_read_b128 v[174:177], v178 offset:2048
	s_add_u32 s4, s4, 0x80
	s_addc_u32 s5, s5, 0
	s_add_u32 s6, s6, 0x80
	s_addc_u32 s7, s7, 0
	s_cmp_eq_u32 s100, 1
	s_cbranch_scc1 .Lkl_1302_s9
	v_readfirstlane_b32 s10, v142
	s_xor_b32 s8, s3, 0x10000
	s_nop 0
	s_lshl_b32 s10, s10, 2
	s_add_i32 s10, s10, s8
	s_add_i32 m0, s10, 0x0
	s_add_u32 s8, s4, 0x1f500080
	s_addc_u32 s9, s5, 0x0
	global_load_lds_dwordx4 v238, s[8:9]
.Lkl_1302_s9:
	v_mfma_f32_16x16x32_bf16 v[30:33], v[222:225], v[214:217], v[30:33]
	v_mfma_f32_16x16x32_bf16 v[26:29], v[226:229], v[214:217], v[26:29]
	v_mfma_f32_16x16x32_bf16 v[22:25], v[230:233], v[214:217], v[22:25]
	v_mfma_f32_16x16x32_bf16 v[18:21], v[234:237], v[214:217], v[18:21]
	ds_read_b128 v[214:217], v178 offset:4096
	s_cmp_eq_u32 s100, 1
	s_cbranch_scc1 .Lkl_1302_s10
	s_add_u32 s8, s4, 0x1f4ffcc0
	s_addc_u32 s9, s5, 0x0
	global_load_lds_dwordx4 v238, s[8:9] offset:1024
.Lkl_1302_s10:
	v_mfma_f32_16x16x32_bf16 v[14:17], v[222:225], v[218:221], v[14:17]
	v_mfma_f32_16x16x32_bf16 v[10:13], v[226:229], v[218:221], v[10:13]
	v_mfma_f32_16x16x32_bf16 v[6:9], v[230:233], v[218:221], v[6:9]
	v_mfma_f32_16x16x32_bf16 v[2:5], v[234:237], v[218:221], v[2:5]
	ds_read_b128 v[218:221], v178 offset:6144
	s_cmp_eq_u32 s100, 1
	s_cbranch_scc1 .Lkl_1302_s11
	s_add_u32 s8, s4, 0x1f507880
	s_addc_u32 s9, s5, 0x0
	global_load_lds_dwordx4 v238, s[8:9] offset:2048

; #define WAIT_V0() asm volatile("s_waitcnt vmcnt(0)" ::: "memory")
; #define SBAR() __builtin_amdgcn_sched_barrier(0)
; template <int EPI>
; DEVI void gemm_tile(const u16* __restrict__ Ab, long lda, const u16* __restrict__ Bb, long ldb, int K, const EpiArgs& e,
;                     bool have0 = false, const u16* __restrict__ nA = nullptr, const u16* __restrict__ nB = nullptr) {
;     ...
;   f32x4 acc[8][4];
; #pragma unroll
;   for (int m = 0; m < 8; ++m)
; #pragma unroll
;     for (int n = 0; n < 4; ++n) acc[m][n] = f32x4{0.f, 0.f, 0.f, 0.f};
;   const int nt = K / BK;
;   if (!have0) GLDS_STAGE(0, 0);
;   WAIT_V0(); __syncthreads();
;   for (int t = 0; t < nt; ++t) {
;     const int cur = t & 1;
;     if (t + 1 < nt) GLDS_STAGE(cur ^ 1, t + 1);
;     else if (nA) {
; #pragma unroll
;       for (int i = 0; i < GL; ++i) {
;         __builtin_amdgcn_global_load_lds((const unsigned*)(nA + (long)i * 64 * lda + toffA), (unsigned*)(g_shm + wid * 1024 + i * 8192), 16, 0, 0);
;         __builtin_amdgcn_global_load_lds((const unsigned*)(nB + (long)i * 64 * ldb + toffB), (unsigned*)(g_shm + TILE_B + wid * 1024 + i * 8192), 16, 0, 0);
;       }
;     }
;     const char* sb = g_shm + cur * STAGE_B;
; #pragma unroll
;     for (int ks = 0; ks < 2; ++ks) {
;       bf16x8 Bf[4];
; #pragma unroll
;       for (int n = 0; n < 4; ++n) Bf[n] = *(const bf16x8*)(sb + b_base + n * 2048 + ks * 1024);
; #pragma unroll
;       for (int mh = 0; mh < 2; ++mh) {
;         bf16x8 At[4];
; #pragma unroll
;         for (int m = 0; m < 4; ++m) At[m] = *(const bf16x8*)(sb + a_base + (mh * 4 + m) * 2048 + ks * 1024);
;         __builtin_amdgcn_s_setprio(1);
; #pragma unroll
;         for (int m = 0; m < 4; ++m)
; #pragma unroll
;           for (int n = 0; n < 4; ++n) acc[mh * 4 + m][n] = __builtin_amdgcn_mfma_f32_16x16x32_bf16(Bf[n], At[m], acc[mh * 4 + m][n], 0, 0, 0);
;         __builtin_amdgcn_s_setprio(0);
;       }
;       SBAR();
;     }
;     if (t + 1 < nt) { WAIT_V0(); __syncthreads(); }
.LBB0_1370:
	s_and_b32 s3, s2, 0x10000
	v_or_b32_e32 v149, s3, v147
	v_add_u32_e32 v169, v149, v148
	v_add_u32_e32 v149, v149, v146
	ds_read_b128 v[150:153], v169 offset:32768
	ds_read_b128 v[154:157], v169 offset:34816
	ds_read_b128 v[158:161], v169 offset:36864
	ds_read_b128 v[162:165], v169 offset:38912
	ds_read_b128 v[170:173], v149
	ds_read_b128 v[174:177], v149 offset:2048
	ds_read_b128 v[192:195], v149 offset:4096
	ds_read_b128 v[198:201], v149 offset:6144
	v_writelane_b32 v240, s4, 0
	v_writelane_b32 v240, s5, 1
	v_writelane_b32 v240, s6, 2
	v_writelane_b32 v240, s7, 3
	v_writelane_b32 v240, s8, 4
	v_writelane_b32 v240, s9, 5
	v_writelane_b32 v240, s10, 6
	v_readfirstlane_b32 s4, v132
	v_readfirstlane_b32 s5, v133
	s_nop 1
	v_subrev_u32_e32 v238, s4, v132
	s_add_u32 s4, s4, s18
	s_addc_u32 s5, s5, s19
	v_readfirstlane_b32 s6, v134
	v_readfirstlane_b32 s7, v135
	s_nop 1
	v_subrev_u32_e32 v239, s6, v134
	s_add_u32 s6, s6, s18
	s_addc_u32 s7, s7, s19
	v_readfirstlane_b32 s8, v140
	s_nop 3
	s_lshr_b32 s8, s8, 10
	s_lshr_b32 s9, s8, 1
	s_lshl_b32 s9, s9, 4
	s_lshl_b32 s10, s8, 5
	s_sub_u32 s10, s10, s9
	s_mul_i32 s9, s10, 0x800
	s_add_u32 s4, s4, s9
	s_addc_u32 s5, s5, 0
	s_and_b32 s9, s8, 1
	s_lshl_b32 s9, s9, 6
	s_sub_u32 s4, s4, s9
	s_subb_u32 s5, s5, 0
	v_readfirstlane_b32 s8, v140
	s_nop 3
	s_lshr_b32 s8, s8, 10
	s_lshr_b32 s9, s8, 1
	s_lshl_b32 s9, s9, 4
	s_lshl_b32 s10, s8, 5
	s_sub_u32 s10, s10, s9
	s_mul_i32 s9, s10, 0x800
	s_add_u32 s6, s6, s9
	s_addc_u32 s7, s7, 0
	s_and_b32 s9, s8, 1
	s_lshl_b32 s9, s9, 6
	s_sub_u32 s6, s6, s9
	s_subb_u32 s7, s7, 0
	v_readfirstlane_b32 s10, v140
	s_xor_b32 s8, s3, 0x10000
	s_nop 0
	s_lshl_b32 s10, s10, 2
	s_add_i32 s10, s10, s8
	s_add_i32 m0, s10, 0x0
	s_add_u32 s8, s4, s12
	s_addc_u32 s9, s5, s13
	global_load_lds_dwordx4 v238, s[8:9]
.Lkl_1370_s1:
	s_add_u32 s8, s4, s12
	s_addc_u32 s9, s5, s13
	s_add_u32 s8, s8, 0xfffffc40
	s_addc_u32 s9, s9, 0xffffffff
	global_load_lds_dwordx4 v238, s[8:9] offset:1024
.Lkl_1370_s2:
	s_add_u32 s8, s4, s12
	s_addc_u32 s9, s5, s13
	s_add_u32 s8, s8, 0x7800
	s_addc_u32 s9, s9, 0x0
	global_load_lds_dwordx4 v238, s[8:9] offset:2048
.Lkl_1370_s3:
.Lkl_1370:
	s_waitcnt lgkmcnt(3)
	v_mfma_f32_16x16x32_bf16 v[126:129], v[150:153], v[170:173], v[126:129]
	v_mfma_f32_16x16x32_bf16 v[122:125], v[154:157], v[170:173], v[122:125]
	v_mfma_f32_16x16x32_bf16 v[118:121], v[158:161], v[170:173], v[118:121]
	v_mfma_f32_16x16x32_bf16 v[114:117], v[162:165], v[170:173], v[114:117]
	ds_read_b128 v[170:173], v149 offset:8192
	ds_read_b128 v[222:225], v169 offset:33792
	s_add_u32 s8, s4, s12
	s_addc_u32 s9, s5, s13
	s_add_u32 s8, s8, 0x7440
	s_addc_u32 s9, s9, 0x0
	global_load_lds_dwordx4 v238, s[8:9] offset:3072
.Lkl_1370_s4:
	s_waitcnt lgkmcnt(4)
	v_mfma_f32_16x16x32_bf16 v[110:113], v[150:153], v[174:177], v[110:113]
	v_mfma_f32_16x16x32_bf16 v[106:109], v[154:157], v[174:177], v[106:109]
	v_mfma_f32_16x16x32_bf16 v[102:105], v[158:161], v[174:177], v[102:105]
	v_mfma_f32_16x16x32_bf16 v[98:101], v[162:165], v[174:177], v[98:101]
	ds_read_b128 v[174:177], v149 offset:10240
	ds_read_b128 v[226:229], v169 offset:35840
	s_add_i32 m0, s10, 0x8000
	s_add_u32 s8, s6, 0xb00080
	s_addc_u32 s9, s7, 0x0
	global_load_lds_dwordx4 v239, s[8:9]
.Lkl_1370_s5:
	s_waitcnt lgkmcnt(5)
	v_mfma_f32_16x16x32_bf16 v[94:97], v[150:153], v[192:195], v[94:97]
	v_mfma_f32_16x16x32_bf16 v[90:93], v[154:157], v[192:195], v[90:93]
	v_mfma_f32_16x16x32_bf16 v[86:89], v[158:161], v[192:195], v[86:89]
	v_mfma_f32_16x16x32_bf16 v[82:85], v[162:165], v[192:195], v[82:85]
	ds_read_b128 v[192:195], v149 offset:12288
	ds_read_b128 v[230:233], v169 offset:37888
	s_add_u32 s8, s6, 0xaffcc0
	s_addc_u32 s9, s7, 0x0
	global_load_lds_dwordx4 v239, s[8:9] offset:1024
.Lkl_1370_s6:
	s_waitcnt lgkmcnt(6)
	v_mfma_f32_16x16x32_bf16 v[78:81], v[150:153], v[198:201], v[78:81]
	v_mfma_f32_16x16x32_bf16 v[74:77], v[154:157], v[198:201], v[74:77]
	v_mfma_f32_16x16x32_bf16 v[70:73], v[158:161], v[198:201], v[70:73]
	v_mfma_f32_16x16x32_bf16 v[66:69], v[162:165], v[198:201], v[66:69]
	ds_read_b128 v[198:201], v149 offset:14336
	ds_read_b128 v[234:237], v169 offset:39936
	s_add_u32 s8, s6, 0xb07880
	s_addc_u32 s9, s7, 0x0
	global_load_lds_dwordx4 v239, s[8:9] offset:2048
.Lkl_1370_s7:
	s_waitcnt lgkmcnt(7)
	v_mfma_f32_16x16x32_bf16 v[62:65], v[150:153], v[170:173], v[62:65]
	v_mfma_f32_16x16x32_bf16 v[58:61], v[154:157], v[170:173], v[58:61]
	v_mfma_f32_16x16x32_bf16 v[54:57], v[158:161], v[170:173], v[54:57]
	v_mfma_f32_16x16x32_bf16 v[50:53], v[162:165], v[170:173], v[50:53]
	ds_read_b128 v[170:173], v149 offset:1024
	s_add_u32 s8, s6, 0xb074c0
	s_addc_u32 s9, s7, 0x0
	global_load_lds_dwordx4 v239, s[8:9] offset:3072
; #define WAIT_V0() asm volatile("s_waitcnt vmcnt(0)" ::: "memory")
; #define SBAR() __builtin_amdgcn_sched_barrier(0)
; template <int EPI>
; DEVI void gemm_tile(const u16* __restrict__ Ab, long lda, const u16* __restrict__ Bb, long ldb, int K, const EpiArgs& e,
;                     bool have0 = false, const u16* __restrict__ nA = nullptr, const u16* __restrict__ nB = nullptr) {
;     ...
;     const char* sb = g_shm + cur * STAGE_B;
; #pragma unroll
;     for (int ks = 0; ks < 2; ++ks) {
;       bf16x8 Bf[4];
; #pragma unroll
;       for (int n = 0; n < 4; ++n) Bf[n] = *(const bf16x8*)(sb + b_base + n * 2048 + ks * 1024);
; #pragma unroll
;       for (int mh = 0; mh < 2; ++mh) {
;         bf16x8 At[4];
; #pragma unroll
;         for (int m = 0; m < 4; ++m) At[m] = *(const bf16x8*)(sb + a_base + (mh * 4 + m) * 2048 + ks * 1024);
;         __builtin_amdgcn_s_setprio(1);
; #pragma unroll
;         for (int m = 0; m < 4; ++m)
; #pragma unroll
;           for (int n = 0; n < 4; ++n) acc[mh * 4 + m][n] = __builtin_amdgcn_mfma_f32_16x16x32_bf16(Bf[n], At[m], acc[mh * 4 + m][n], 0, 0, 0);
;         __builtin_amdgcn_s_setprio(0);
;       }
;       SBAR();
;     }
;     if (t + 1 < nt) { WAIT_V0(); __syncthreads(); }
.Lkl_1370_s8:
	s_waitcnt lgkmcnt(6)
	v_mfma_f32_16x16x32_bf16 v[46:49], v[150:153], v[174:177], v[46:49]
	v_mfma_f32_16x16x32_bf16 v[42:45], v[154:157], v[174:177], v[42:45]
	v_mfma_f32_16x16x32_bf16 v[38:41], v[158:161], v[174:177], v[38:41]
	v_mfma_f32_16x16x32_bf16 v[34:37], v[162:165], v[174:177], v[34:37]
	ds_read_b128 v[174:177], v149 offset:3072
	s_waitcnt lgkmcnt(5)
	v_mfma_f32_16x16x32_bf16 v[30:33], v[150:153], v[192:195], v[30:33]
	v_mfma_f32_16x16x32_bf16 v[26:29], v[154:157], v[192:195], v[26:29]
	v_mfma_f32_16x16x32_bf16 v[22:25], v[158:161], v[192:195], v[22:25]
	v_mfma_f32_16x16x32_bf16 v[18:21], v[162:165], v[192:195], v[18:21]
	ds_read_b128 v[192:195], v149 offset:5120
	s_waitcnt lgkmcnt(4)
	v_mfma_f32_16x16x32_bf16 v[14:17], v[150:153], v[198:201], v[14:17]
	v_mfma_f32_16x16x32_bf16 v[10:13], v[154:157], v[198:201], v[10:13]
	v_mfma_f32_16x16x32_bf16 v[6:9], v[158:161], v[198:201], v[6:9]
	v_mfma_f32_16x16x32_bf16 v[2:5], v[162:165], v[198:201], v[2:5]
	ds_read_b128 v[198:201], v149 offset:7168
	s_waitcnt lgkmcnt(3)
	v_mfma_f32_16x16x32_bf16 v[126:129], v[222:225], v[170:173], v[126:129]
	v_mfma_f32_16x16x32_bf16 v[122:125], v[226:229], v[170:173], v[122:125]
	v_mfma_f32_16x16x32_bf16 v[118:121], v[230:233], v[170:173], v[118:121]
	v_mfma_f32_16x16x32_bf16 v[114:117], v[234:237], v[170:173], v[114:117]
	ds_read_b128 v[170:173], v149 offset:9216
	s_waitcnt lgkmcnt(3)
	v_mfma_f32_16x16x32_bf16 v[110:113], v[222:225], v[174:177], v[110:113]
	v_mfma_f32_16x16x32_bf16 v[106:109], v[226:229], v[174:177], v[106:109]
	v_mfma_f32_16x16x32_bf16 v[102:105], v[230:233], v[174:177], v[102:105]
	v_mfma_f32_16x16x32_bf16 v[98:101], v[234:237], v[174:177], v[98:101]
	ds_read_b128 v[174:177], v149 offset:11264
	s_waitcnt lgkmcnt(3)
	v_mfma_f32_16x16x32_bf16 v[94:97], v[222:225], v[192:195], v[94:97]
	v_mfma_f32_16x16x32_bf16 v[90:93], v[226:229], v[192:195], v[90:93]
	v_mfma_f32_16x16x32_bf16 v[86:89], v[230:233], v[192:195], v[86:89]
	v_mfma_f32_16x16x32_bf16 v[82:85], v[234:237], v[192:195], v[82:85]
	ds_read_b128 v[192:195], v149 offset:13312
	s_waitcnt lgkmcnt(3)
	v_mfma_f32_16x16x32_bf16 v[78:81], v[222:225], v[198:201], v[78:81]
	v_mfma_f32_16x16x32_bf16 v[74:77], v[226:229], v[198:201], v[74:77]
	v_mfma_f32_16x16x32_bf16 v[70:73], v[230:233], v[198:201], v[70:73]
	v_mfma_f32_16x16x32_bf16 v[66:69], v[234:237], v[198:201], v[66:69]
	ds_read_b128 v[198:201], v149 offset:15360
	s_waitcnt lgkmcnt(3)
	v_mfma_f32_16x16x32_bf16 v[62:65], v[222:225], v[170:173], v[62:65]
	v_mfma_f32_16x16x32_bf16 v[58:61], v[226:229], v[170:173], v[58:61]
	v_mfma_f32_16x16x32_bf16 v[54:57], v[230:233], v[170:173], v[54:57]
	v_mfma_f32_16x16x32_bf16 v[50:53], v[234:237], v[170:173], v[50:53]
	s_waitcnt lgkmcnt(2)
	v_mfma_f32_16x16x32_bf16 v[46:49], v[222:225], v[174:177], v[46:49]
	v_mfma_f32_16x16x32_bf16 v[42:45], v[226:229], v[174:177], v[42:45]
	v_mfma_f32_16x16x32_bf16 v[38:41], v[230:233], v[174:177], v[38:41]
	v_mfma_f32_16x16x32_bf16 v[34:37], v[234:237], v[174:177], v[34:37]
	s_waitcnt lgkmcnt(0)
	s_add_i32 s2, s2, 0x10000
	s_waitcnt vmcnt(0)
	s_add_u32 s18, s18, 0x80
	s_addc_u32 s19, s19, 0
	s_cmpk_eq_i32 s18, 0x780
	s_waitcnt vmcnt(0)
	s_barrier
	s_cselect_b32 s100, 1, 0
	s_and_b32 s3, s2, 0x10000
	v_or_b32_e32 v149, s3, v147
	v_add_u32_e32 v169, v149, v148
	v_add_u32_e32 v149, v149, v146
	ds_read_b128 v[150:153], v169 offset:32768
	ds_read_b128 v[154:157], v169 offset:34816
	ds_read_b128 v[158:161], v169 offset:36864
	ds_read_b128 v[162:165], v169 offset:38912
	ds_read_b128 v[170:173], v149
	ds_read_b128 v[174:177], v149 offset:2048
	s_add_u32 s4, s4, 0x80
	s_addc_u32 s5, s5, 0
	s_add_u32 s6, s6, 0x80
	s_addc_u32 s7, s7, 0
	s_cmp_eq_u32 s100, 1
	s_cbranch_scc1 .Lkl_1370_s9
	v_readfirstlane_b32 s10, v140
	s_xor_b32 s8, s3, 0x10000
	s_nop 0
	s_lshl_b32 s10, s10, 2
	s_add_i32 s10, s10, s8
	s_add_i32 m0, s10, 0x0
	s_add_u32 s8, s4, s12
	s_addc_u32 s9, s5, s13
	global_load_lds_dwordx4 v238, s[8:9]
.Lkl_1370_s9:
	v_mfma_f32_16x16x32_bf16 v[30:33], v[222:225], v[192:195], v[30:33]
	v_mfma_f32_16x16x32_bf16 v[26:29], v[226:229], v[192:195], v[26:29]
	v_mfma_f32_16x16x32_bf16 v[22:25], v[230:233], v[192:195], v[22:25]
	v_mfma_f32_16x16x32_bf16 v[18:21], v[234:237], v[192:195], v[18:21]
	ds_read_b128 v[192:195], v149 offset:4096
	s_cmp_eq_u32 s100, 1
	s_cbranch_scc1 .Lkl_1370_s10
	s_add_u32 s8, s4, s12
	s_addc_u32 s9, s5, s13
	s_add_u32 s8, s8, 0xfffffc40
	s_addc_u32 s9, s9, 0xffffffff
	global_load_lds_dwordx4 v238, s[8:9] offset:1024
.Lkl_1370_s10:
	v_mfma_f32_16x16x32_bf16 v[14:17], v[222:225], v[198:201], v[14:17]
	v_mfma_f32_16x16x32_bf16 v[10:13], v[226:229], v[198:201], v[10:13]
	v_mfma_f32_16x16x32_bf16 v[6:9], v[230:233], v[198:201], v[6:9]
	v_mfma_f32_16x16x32_bf16 v[2:5], v[234:237], v[198:201], v[2:5]
	ds_read_b128 v[198:201], v149 offset:6144
	s_cmp_eq_u32 s100, 1
	s_cbranch_scc1 .Lkl_1370_s11
	s_add_u32 s8, s4, s12
	s_addc_u32 s9, s5, s13
	s_add_u32 s8, s8, 0x7800
	s_addc_u32 s9, s9, 0x0
	global_load_lds_dwordx4 v238, s[8:9] offset:2048

; #define WAIT_V0() asm volatile("s_waitcnt vmcnt(0)" ::: "memory")
; template <int EPI>
; DEVI void gemm_tile(const u16* __restrict__ Ab, long lda, const u16* __restrict__ Bb, long ldb, int K, const EpiArgs& e,
;                     bool have0 = false, const u16* __restrict__ nA = nullptr, const u16* __restrict__ nB = nullptr) {
;     ...
;   f32x4 acc[8][4];
; #pragma unroll
;   for (int m = 0; m < 8; ++m)
; #pragma unroll
;     for (int n = 0; n < 4; ++n) acc[m][n] = f32x4{0.f, 0.f, 0.f, 0.f};
;   const int nt = K / BK;
;   if (!have0) GLDS_STAGE(0, 0);
;   WAIT_V0(); __syncthreads();
;   for (int t = 0; t < nt; ++t) {
;     const int cur = t & 1;
;     if (t + 1 < nt) GLDS_STAGE(cur ^ 1, t + 1);
;     else if (nA) {
; #pragma unroll
;       for (int i = 0; i < GL; ++i) {
;         __builtin_amdgcn_global_load_lds((const unsigned*)(nA + (long)i * 64 * lda + toffA), (unsigned*)(g_shm + wid * 1024 + i * 8192), 16, 0, 0);
;         __builtin_amdgcn_global_load_lds((const unsigned*)(nB + (long)i * 64 * ldb + toffB), (unsigned*)(g_shm + TILE_B + wid * 1024 + i * 8192), 16, 0, 0);
;       }
;     }
;     const char* sb = g_shm + cur * STAGE_B;
; #pragma unroll
;     for (int ks = 0; ks < 2; ++ks) {
;       bf16x8 Bf[4];
; #pragma unroll
;       for (int n = 0; n < 4; ++n) Bf[n] = *(const bf16x8*)(sb + b_base + n * 2048 + ks * 1024);
; #pragma unroll
;       for (int mh = 0; mh < 2; ++mh) {
;         bf16x8 At[4];
; #pragma unroll
;         for (int m = 0; m < 4; ++m) At[m] = *(const bf16x8*)(sb + a_base + (mh * 4 + m) * 2048 + ks * 1024);
.LBB0_1404:
	s_and_b32 s26, s3, 0x10000
	v_or_b32_e32 v150, s26, v149
	v_add_u32_e32 v169, v150, v148
	v_or_b32_e32 v150, s26, v146
	v_add_u32_e32 v178, v150, v147
	ds_read_b128 v[150:153], v169 offset:32768
	ds_read_b128 v[154:157], v169 offset:34816
	ds_read_b128 v[158:161], v169 offset:36864
	ds_read_b128 v[162:165], v169 offset:38912
	ds_read_b128 v[170:173], v178
	ds_read_b128 v[174:177], v178 offset:2048
	ds_read_b128 v[192:195], v178 offset:4096
	ds_read_b128 v[198:201], v178 offset:6144
	v_writelane_b32 v240, s4, 0
	v_writelane_b32 v240, s5, 1
	v_writelane_b32 v240, s6, 2
	v_writelane_b32 v240, s7, 3
	v_writelane_b32 v240, s8, 4
	v_writelane_b32 v240, s9, 5
	v_writelane_b32 v240, s10, 6
	v_readfirstlane_b32 s4, v134
	v_readfirstlane_b32 s5, v135
	s_nop 1
	v_subrev_u32_e32 v238, s4, v134
	s_add_u32 s4, s4, s18
	s_addc_u32 s5, s5, s19
	v_readfirstlane_b32 s6, v136
	v_readfirstlane_b32 s7, v137
	s_nop 1
	v_subrev_u32_e32 v239, s6, v136
	s_add_u32 s6, s6, s18
	s_addc_u32 s7, s7, s19
	v_readfirstlane_b32 s8, v143
	s_nop 3
	s_lshr_b32 s8, s8, 10
	s_lshr_b32 s9, s8, 1
	s_lshl_b32 s9, s9, 4
	s_lshl_b32 s10, s8, 5
	s_sub_u32 s10, s10, s9
	s_mul_i32 s9, s10, 0x1600
	s_add_u32 s4, s4, s9
	s_addc_u32 s5, s5, 0
	s_and_b32 s9, s8, 1
	s_lshl_b32 s9, s9, 6
	s_sub_u32 s4, s4, s9
	s_subb_u32 s5, s5, 0
	v_readfirstlane_b32 s8, v143
	s_nop 3
	s_lshr_b32 s8, s8, 10
	s_lshr_b32 s9, s8, 1
	s_lshl_b32 s9, s9, 4
	s_lshl_b32 s10, s8, 5
	s_sub_u32 s10, s10, s9
	s_mul_i32 s9, s10, 0x1600
	s_add_u32 s6, s6, s9
	s_addc_u32 s7, s7, 0
	s_and_b32 s9, s8, 1
	s_lshl_b32 s9, s9, 6
	s_sub_u32 s6, s6, s9
	s_subb_u32 s7, s7, 0
	v_readfirstlane_b32 s10, v143
	s_xor_b32 s8, s26, 0x10000
	s_nop 0
	s_lshl_b32 s10, s10, 2
	s_add_i32 s10, s10, s8
	s_add_i32 m0, s10, 0x0
	s_add_u32 s8, s4, s30
	s_addc_u32 s9, s5, s31
	global_load_lds_dwordx4 v238, s[8:9]

; #define WAIT_V0() asm volatile("s_waitcnt vmcnt(0)" ::: "memory")
; #define SBAR() __builtin_amdgcn_sched_barrier(0)
; template <int EPI>
; DEVI void gemm_tile(const u16* __restrict__ Ab, long lda, const u16* __restrict__ Bb, long ldb, int K, const EpiArgs& e,
;                     bool have0 = false, const u16* __restrict__ nA = nullptr, const u16* __restrict__ nB = nullptr) {
;     ...
;   f32x4 acc[8][4];
; #pragma unroll
;   for (int m = 0; m < 8; ++m)
; #pragma unroll
;     for (int n = 0; n < 4; ++n) acc[m][n] = f32x4{0.f, 0.f, 0.f, 0.f};
;   const int nt = K / BK;
;   if (!have0) GLDS_STAGE(0, 0);
;   WAIT_V0(); __syncthreads();
;   for (int t = 0; t < nt; ++t) {
;     const int cur = t & 1;
;     if (t + 1 < nt) GLDS_STAGE(cur ^ 1, t + 1);
;     else if (nA) {
; #pragma unroll
;       for (int i = 0; i < GL; ++i) {
;         __builtin_amdgcn_global_load_lds((const unsigned*)(nA + (long)i * 64 * lda + toffA), (unsigned*)(g_shm + wid * 1024 + i * 8192), 16, 0, 0);
;         __builtin_amdgcn_global_load_lds((const unsigned*)(nB + (long)i * 64 * ldb + toffB), (unsigned*)(g_shm + TILE_B + wid * 1024 + i * 8192), 16, 0, 0);
;       }
;     }
;     const char* sb = g_shm + cur * STAGE_B;
; #pragma unroll
;     for (int ks = 0; ks < 2; ++ks) {
;       bf16x8 Bf[4];
; #pragma unroll
;       for (int n = 0; n < 4; ++n) Bf[n] = *(const bf16x8*)(sb + b_base + n * 2048 + ks * 1024);
; #pragma unroll
;       for (int mh = 0; mh < 2; ++mh) {
;         bf16x8 At[4];
; #pragma unroll
;         for (int m = 0; m < 4; ++m) At[m] = *(const bf16x8*)(sb + a_base + (mh * 4 + m) * 2048 + ks * 1024);
;         __builtin_amdgcn_s_setprio(1);
; #pragma unroll
;         for (int m = 0; m < 4; ++m)
; #pragma unroll
;           for (int n = 0; n < 4; ++n) acc[mh * 4 + m][n] = __builtin_amdgcn_mfma_f32_16x16x32_bf16(Bf[n], At[m], acc[mh * 4 + m][n], 0, 0, 0);
;         __builtin_amdgcn_s_setprio(0);
;       }
;       SBAR();
;     }
;     if (t + 1 < nt) { WAIT_V0(); __syncthreads(); }
;   }
.Lkl_1404_s2:
	s_add_u32 s8, s4, s30
	s_addc_u32 s9, s5, s31
	s_add_u32 s8, s8, 0x15800
	s_addc_u32 s9, s9, 0x0
	global_load_lds_dwordx4 v238, s[8:9] offset:2048
.Lkl_1404_s3:
.Lkl_1404:
	s_waitcnt lgkmcnt(3)
	v_mfma_f32_16x16x32_bf16 v[126:129], v[150:153], v[170:173], v[126:129]
	v_mfma_f32_16x16x32_bf16 v[122:125], v[154:157], v[170:173], v[122:125]
	v_mfma_f32_16x16x32_bf16 v[118:121], v[158:161], v[170:173], v[118:121]
	v_mfma_f32_16x16x32_bf16 v[114:117], v[162:165], v[170:173], v[114:117]
	ds_read_b128 v[170:173], v178 offset:8192
	ds_read_b128 v[222:225], v169 offset:33792
	s_add_u32 s8, s4, s30
	s_addc_u32 s9, s5, s31
	s_add_u32 s8, s8, 0x15440
	s_addc_u32 s9, s9, 0x0
	global_load_lds_dwordx4 v238, s[8:9] offset:3072
.Lkl_1404_s4:
	s_waitcnt lgkmcnt(4)
	v_mfma_f32_16x16x32_bf16 v[110:113], v[150:153], v[174:177], v[110:113]
	v_mfma_f32_16x16x32_bf16 v[106:109], v[154:157], v[174:177], v[106:109]
	v_mfma_f32_16x16x32_bf16 v[102:105], v[158:161], v[174:177], v[102:105]
	v_mfma_f32_16x16x32_bf16 v[98:101], v[162:165], v[174:177], v[98:101]
	ds_read_b128 v[174:177], v178 offset:10240
	ds_read_b128 v[226:229], v169 offset:35840
	s_add_i32 m0, s10, 0x8000
	s_add_u32 s8, s6, 0x1b80080
	s_addc_u32 s9, s7, 0x0
	global_load_lds_dwordx4 v239, s[8:9]
.Lkl_1404_s5:
	s_waitcnt lgkmcnt(5)
	v_mfma_f32_16x16x32_bf16 v[94:97], v[150:153], v[192:195], v[94:97]
	v_mfma_f32_16x16x32_bf16 v[90:93], v[154:157], v[192:195], v[90:93]
	v_mfma_f32_16x16x32_bf16 v[86:89], v[158:161], v[192:195], v[86:89]
	v_mfma_f32_16x16x32_bf16 v[82:85], v[162:165], v[192:195], v[82:85]
	ds_read_b128 v[192:195], v178 offset:12288
	ds_read_b128 v[230:233], v169 offset:37888
	s_add_u32 s8, s6, 0x1b7fcc0
	s_addc_u32 s9, s7, 0x0
	global_load_lds_dwordx4 v239, s[8:9] offset:1024
.Lkl_1404_s6:
	s_waitcnt lgkmcnt(6)
	v_mfma_f32_16x16x32_bf16 v[78:81], v[150:153], v[198:201], v[78:81]
	v_mfma_f32_16x16x32_bf16 v[74:77], v[154:157], v[198:201], v[74:77]
	v_mfma_f32_16x16x32_bf16 v[70:73], v[158:161], v[198:201], v[70:73]
	v_mfma_f32_16x16x32_bf16 v[66:69], v[162:165], v[198:201], v[66:69]
	ds_read_b128 v[198:201], v178 offset:14336
	ds_read_b128 v[234:237], v169 offset:39936
	s_add_u32 s8, s6, 0x1b95880
	s_addc_u32 s9, s7, 0x0
	global_load_lds_dwordx4 v239, s[8:9] offset:2048
.Lkl_1404_s7:
	s_waitcnt lgkmcnt(7)
	v_mfma_f32_16x16x32_bf16 v[62:65], v[150:153], v[170:173], v[62:65]
	v_mfma_f32_16x16x32_bf16 v[58:61], v[154:157], v[170:173], v[58:61]
	v_mfma_f32_16x16x32_bf16 v[54:57], v[158:161], v[170:173], v[54:57]
	v_mfma_f32_16x16x32_bf16 v[50:53], v[162:165], v[170:173], v[50:53]
	ds_read_b128 v[170:173], v178 offset:1024
	s_add_u32 s8, s6, 0x1b954c0
	s_addc_u32 s9, s7, 0x0
	global_load_lds_dwordx4 v239, s[8:9] offset:3072
.Lkl_1404_s8:
	s_waitcnt lgkmcnt(6)
	v_mfma_f32_16x16x32_bf16 v[46:49], v[150:153], v[174:177], v[46:49]
	v_mfma_f32_16x16x32_bf16 v[42:45], v[154:157], v[174:177], v[42:45]
	v_mfma_f32_16x16x32_bf16 v[38:41], v[158:161], v[174:177], v[38:41]
	v_mfma_f32_16x16x32_bf16 v[34:37], v[162:165], v[174:177], v[34:37]
	ds_read_b128 v[174:177], v178 offset:3072
	s_waitcnt lgkmcnt(5)
	v_mfma_f32_16x16x32_bf16 v[30:33], v[150:153], v[192:195], v[30:33]
	v_mfma_f32_16x16x32_bf16 v[26:29], v[154:157], v[192:195], v[26:29]
	v_mfma_f32_16x16x32_bf16 v[22:25], v[158:161], v[192:195], v[22:25]
	v_mfma_f32_16x16x32_bf16 v[18:21], v[162:165], v[192:195], v[18:21]
	ds_read_b128 v[192:195], v178 offset:5120
	s_waitcnt lgkmcnt(4)
	v_mfma_f32_16x16x32_bf16 v[14:17], v[150:153], v[198:201], v[14:17]
	v_mfma_f32_16x16x32_bf16 v[10:13], v[154:157], v[198:201], v[10:13]
	v_mfma_f32_16x16x32_bf16 v[6:9], v[158:161], v[198:201], v[6:9]
	v_mfma_f32_16x16x32_bf16 v[2:5], v[162:165], v[198:201], v[2:5]
	ds_read_b128 v[198:201], v178 offset:7168
	s_waitcnt lgkmcnt(3)
	v_mfma_f32_16x16x32_bf16 v[126:129], v[222:225], v[170:173], v[126:129]
	v_mfma_f32_16x16x32_bf16 v[122:125], v[226:229], v[170:173], v[122:125]
	v_mfma_f32_16x16x32_bf16 v[118:121], v[230:233], v[170:173], v[118:121]
	v_mfma_f32_16x16x32_bf16 v[114:117], v[234:237], v[170:173], v[114:117]
	ds_read_b128 v[170:173], v178 offset:9216
	s_waitcnt lgkmcnt(3)
	v_mfma_f32_16x16x32_bf16 v[110:113], v[222:225], v[174:177], v[110:113]
	v_mfma_f32_16x16x32_bf16 v[106:109], v[226:229], v[174:177], v[106:109]
	v_mfma_f32_16x16x32_bf16 v[102:105], v[230:233], v[174:177], v[102:105]
	v_mfma_f32_16x16x32_bf16 v[98:101], v[234:237], v[174:177], v[98:101]
	ds_read_b128 v[174:177], v178 offset:11264
	s_waitcnt lgkmcnt(3)
	v_mfma_f32_16x16x32_bf16 v[94:97], v[222:225], v[192:195], v[94:97]
	v_mfma_f32_16x16x32_bf16 v[90:93], v[226:229], v[192:195], v[90:93]
	v_mfma_f32_16x16x32_bf16 v[86:89], v[230:233], v[192:195], v[86:89]
	v_mfma_f32_16x16x32_bf16 v[82:85], v[234:237], v[192:195], v[82:85]
	ds_read_b128 v[192:195], v178 offset:13312
	s_waitcnt lgkmcnt(3)
	v_mfma_f32_16x16x32_bf16 v[78:81], v[222:225], v[198:201], v[78:81]
	v_mfma_f32_16x16x32_bf16 v[74:77], v[226:229], v[198:201], v[74:77]
	v_mfma_f32_16x16x32_bf16 v[70:73], v[230:233], v[198:201], v[70:73]
	v_mfma_f32_16x16x32_bf16 v[66:69], v[234:237], v[198:201], v[66:69]
	ds_read_b128 v[198:201], v178 offset:15360
	s_waitcnt lgkmcnt(3)
	v_mfma_f32_16x16x32_bf16 v[62:65], v[222:225], v[170:173], v[62:65]
	v_mfma_f32_16x16x32_bf16 v[58:61], v[226:229], v[170:173], v[58:61]
	v_mfma_f32_16x16x32_bf16 v[54:57], v[230:233], v[170:173], v[54:57]
	v_mfma_f32_16x16x32_bf16 v[50:53], v[234:237], v[170:173], v[50:53]
	s_waitcnt lgkmcnt(2)
	v_mfma_f32_16x16x32_bf16 v[46:49], v[222:225], v[174:177], v[46:49]
	v_mfma_f32_16x16x32_bf16 v[42:45], v[226:229], v[174:177], v[42:45]
	v_mfma_f32_16x16x32_bf16 v[38:41], v[230:233], v[174:177], v[38:41]
	v_mfma_f32_16x16x32_bf16 v[34:37], v[234:237], v[174:177], v[34:37]
	s_waitcnt lgkmcnt(0)
	s_waitcnt vmcnt(0)
	s_add_u32 s18, s18, 0x80
	s_addc_u32 s19, s19, 0
	s_add_i32 s3, s3, 0x10000
	s_cmpk_eq_i32 s18, 0x1580
	s_waitcnt vmcnt(0)
	s_barrier
	s_cselect_b32 s100, 1, 0
	s_and_b32 s26, s3, 0x10000
	v_or_b32_e32 v150, s26, v149
	v_add_u32_e32 v169, v150, v148
	v_or_b32_e32 v150, s26, v146
	v_add_u32_e32 v178, v150, v147
	ds_read_b128 v[150:153], v169 offset:32768
	ds_read_b128 v[154:157], v169 offset:34816
	ds_read_b128 v[158:161], v169 offset:36864
	ds_read_b128 v[162:165], v169 offset:38912
	ds_read_b128 v[170:173], v178
	ds_read_b128 v[174:177], v178 offset:2048
	s_add_u32 s4, s4, 0x80
	s_addc_u32 s5, s5, 0
	s_add_u32 s6, s6, 0x80
	s_addc_u32 s7, s7, 0
	s_cmp_eq_u32 s100, 1
	s_cbranch_scc1 .Lkl_1404_s9
	v_readfirstlane_b32 s10, v143
	s_xor_b32 s8, s26, 0x10000
	s_nop 0
	s_lshl_b32 s10, s10, 2
	s_add_i32 s10, s10, s8
	s_add_i32 m0, s10, 0x0
	s_add_u32 s8, s4, s30
	s_addc_u32 s9, s5, s31
	global_load_lds_dwordx4 v238, s[8:9]

; #define WAIT_V0() asm volatile("s_waitcnt vmcnt(0)" ::: "memory")
; #define SBAR() __builtin_amdgcn_sched_barrier(0)
; template <int EPI>
; DEVI void gemm_tile(const u16* __restrict__ Ab, long lda, const u16* __restrict__ Bb, long ldb, int K, const EpiArgs& e,
;                     bool have0 = false, const u16* __restrict__ nA = nullptr, const u16* __restrict__ nB = nullptr) {
;     ...
;   f32x4 acc[8][4];
; #pragma unroll
;   for (int m = 0; m < 8; ++m)
; #pragma unroll
;     for (int n = 0; n < 4; ++n) acc[m][n] = f32x4{0.f, 0.f, 0.f, 0.f};
;   const int nt = K / BK;
;   if (!have0) GLDS_STAGE(0, 0);
;   WAIT_V0(); __syncthreads();
;   for (int t = 0; t < nt; ++t) {
;     const int cur = t & 1;
;     if (t + 1 < nt) GLDS_STAGE(cur ^ 1, t + 1);
;     else if (nA) {
; #pragma unroll
;       for (int i = 0; i < GL; ++i) {
;         __builtin_amdgcn_global_load_lds((const unsigned*)(nA + (long)i * 64 * lda + toffA), (unsigned*)(g_shm + wid * 1024 + i * 8192), 16, 0, 0);
;         __builtin_amdgcn_global_load_lds((const unsigned*)(nB + (long)i * 64 * ldb + toffB), (unsigned*)(g_shm + TILE_B + wid * 1024 + i * 8192), 16, 0, 0);
;       }
;     }
;     const char* sb = g_shm + cur * STAGE_B;
; #pragma unroll
;     for (int ks = 0; ks < 2; ++ks) {
;       bf16x8 Bf[4];
; #pragma unroll
;       for (int n = 0; n < 4; ++n) Bf[n] = *(const bf16x8*)(sb + b_base + n * 2048 + ks * 1024);
; #pragma unroll
;       for (int mh = 0; mh < 2; ++mh) {
;         bf16x8 At[4];
; #pragma unroll
;         for (int m = 0; m < 4; ++m) At[m] = *(const bf16x8*)(sb + a_base + (mh * 4 + m) * 2048 + ks * 1024);
;         __builtin_amdgcn_s_setprio(1);
; #pragma unroll
;         for (int m = 0; m < 4; ++m)
; #pragma unroll
;           for (int n = 0; n < 4; ++n) acc[mh * 4 + m][n] = __builtin_amdgcn_mfma_f32_16x16x32_bf16(Bf[n], At[m], acc[mh * 4 + m][n], 0, 0, 0);
;         __builtin_amdgcn_s_setprio(0);
;       }
;       SBAR();
;     }
;     if (t + 1 < nt) { WAIT_V0(); __syncthreads(); }
;   }
.Lkl_1404_s10:
	v_mfma_f32_16x16x32_bf16 v[14:17], v[222:225], v[198:201], v[14:17]
	v_mfma_f32_16x16x32_bf16 v[10:13], v[226:229], v[198:201], v[10:13]
	v_mfma_f32_16x16x32_bf16 v[6:9], v[230:233], v[198:201], v[6:9]
	v_mfma_f32_16x16x32_bf16 v[2:5], v[234:237], v[198:201], v[2:5]
	ds_read_b128 v[198:201], v178 offset:6144
	s_cmp_eq_u32 s100, 1
	s_cbranch_scc1 .Lkl_1404_s11
	s_add_u32 s8, s4, s30
	s_addc_u32 s9, s5, s31
	s_add_u32 s8, s8, 0x15800
	s_addc_u32 s9, s9, 0x0
	global_load_lds_dwordx4 v238, s[8:9] offset:2048
